# PEER expert inner loop hand-written for both layers: next group rows prefetched into a second register buffer, saddr loads, half-wave dot reduction via DPP row ops instead of a bpermute chain
# speedup vs baseline: 1.0468x; 1.0196x over previous
.LBB0_389:
	v_mov_b32_e32 v90, v62
	v_ashrrev_i32_e32 v91, 31, v90
	v_lshlrev_b64 v[0:1], 12, v[90:91]
	s_waitcnt vmcnt(1)
	v_mov_b32_e32 v33, v95
	v_lshl_add_u64 v[92:93], s[40:41], 0, v[0:1]
	v_ashrrev_i32_e32 v95, 31, v94
	v_readlane_b32 s24, v245, 53
	v_lshl_add_u64 v[28:29], v[92:93], 0, v[88:89]
	v_lshlrev_b64 v[34:35], 2, v[94:95]
	v_readlane_b32 s25, v245, 54
	v_readlane_b32 s26, v245, 55
	v_readlane_b32 s27, v245, 56
	v_ashrrev_i32_e32 v97, 31, v96
	v_add_u32_e32 v62, s14, v90
	global_load_dwordx4 v[12:15], v[28:29], off offset:16
	global_load_dwordx4 v[24:27], v[28:29], off
	global_load_dwordx4 v[4:7], v[28:29], off offset:32
	global_load_dwordx4 v[0:3], v[28:29], off offset:48
	global_load_dwordx4 v[20:23], v[28:29], off offset:112
	global_load_dwordx4 v[8:11], v[28:29], off offset:96
	global_load_dwordx4 v[16:19], v[28:29], off offset:80
	s_nop 0
	global_load_dwordx4 v[28:31], v[28:29], off offset:64
	v_lshl_add_u64 v[36:37], s[24:25], 0, v[34:35]
	v_lshlrev_b64 v[38:39], 2, v[96:97]
	v_lshl_add_u64 v[34:35], s[26:27], 0, v[34:35]
	v_cmp_gt_i32_e64 s[0:1], s3, v62
	v_lshl_add_u64 v[40:41], s[24:25], 0, v[38:39]
	global_load_dword v149, v[36:37], off
	global_load_dword v150, v[40:41], off
	v_lshl_add_u64 v[36:37], s[26:27], 0, v[38:39]
	global_load_dword v38, v[34:35], off
	global_load_dword v39, v[36:37], off
	v_cndmask_b32_e64 v34, v90, v62, s[0:1]
	v_ashrrev_i32_e32 v35, 31, v34
	v_lshlrev_b64 v[34:35], 9, v[34:35]
	v_lshl_or_b32 v34, v60, 2, v34
	v_lshl_add_u64 v[36:37], s[46:47], 0, v[34:35]
	v_lshl_add_u64 v[34:35], s[44:45], 0, v[34:35]
	global_load_dword v147, v[36:37], off
	global_load_dword v148, v[36:37], off offset:256
	global_load_dword v95, v[34:35], off
	global_load_dword v97, v[34:35], off offset:256
	v_cmp_lt_i32_e64 s[0:1], s15, v62
	s_mov_b32 s21, 0
	v_mov_b32_e32 v48, 0
	v_mov_b32_e32 v49, v65
	v_mov_b32_e32 v108, 0
	v_mov_b32_e32 v109, v65
	v_mov_b32_e32 v106, 0
	v_mov_b32_e32 v107, v65
	v_mov_b32_e32 v98, 0
	v_mov_b32_e32 v99, v65
	v_mov_b32_e32 v56, 0
	v_mov_b32_e32 v57, v65
	v_mov_b32_e32 v50, 0
	v_mov_b32_e32 v51, v65
	v_mov_b32_e32 v53, 0
	v_mov_b32_e32 v52, v65
	v_mov_b32_e32 v59, 0
	v_mov_b32_e32 v58, v65
	v_mov_b32_e32 v55, 0
	v_mov_b32_e32 v54, v65
	v_mov_b32_e32 v101, 0
	v_mov_b32_e32 v100, v65
	v_mov_b32_e32 v103, 0
	v_mov_b32_e32 v102, v65
	v_mov_b32_e32 v111, 0
	v_mov_b32_e32 v110, v65
	v_mov_b32_e32 v115, 0
	v_mov_b32_e32 v114, v65
	s_mov_b32 s22, 0
	v_mov_b32_e32 v104, 0
	v_mov_b32_e32 v105, v65
	s_or_b64 s[16:17], s[0:1], s[16:17]
	v_mov_b32_e32 v112, 0
	v_mov_b32_e32 v113, v65
	v_mov_b32_e32 v116, 0
	v_mov_b32_e32 v117, v65
	s_waitcnt vmcnt(5)
	v_mul_f32_e32 v151, v33, v38
	s_waitcnt vmcnt(4)
	v_mul_f32_e32 v152, v32, v39
	v_readfirstlane_b32 s98, v66
	v_readfirstlane_b32 s99, v67
	v_readfirstlane_b32 s100, v68
	v_readfirstlane_b32 s101, v69
	v_and_b32_e32 v241, 31, v60
	v_lshlrev_b32_e32 v241, 4, v241
	s_mov_b32 s22, 0
	v_lshlrev_b32_e32 v129, 2, v139
	ds_bpermute_b32 v240, v129, v94
	ds_bpermute_b32 v242, v129, v94 offset:8
	ds_bpermute_b32 v246, v129, v94 offset:16
	ds_bpermute_b32 v248, v129, v94 offset:24
	s_waitcnt lgkmcnt(0)
	v_lshl_add_u32 v250, v240, 9, v241
	v_lshl_add_u32 v251, v242, 9, v241
	v_lshl_add_u32 v252, v246, 9, v241
	v_lshl_add_u32 v253, v248, 9, v241
	global_load_dwordx4 v[160:163], v250, s[98:99]
	global_load_dwordx4 v[164:167], v251, s[98:99]
	global_load_dwordx4 v[168:171], v252, s[98:99]
	global_load_dwordx4 v[172:175], v253, s[98:99]
	global_load_dwordx4 v[176:179], v250, s[100:101]
	global_load_dwordx4 v[180:183], v251, s[100:101]
	global_load_dwordx4 v[184:187], v252, s[100:101]
	global_load_dwordx4 v[188:191], v253, s[100:101]
	v_add_u32_e32 v129, 32, v129
	ds_bpermute_b32 v240, v129, v94
	ds_bpermute_b32 v242, v129, v94 offset:8
	ds_bpermute_b32 v246, v129, v94 offset:16
	ds_bpermute_b32 v248, v129, v94 offset:24
.Lxg_loop_p6:
	s_waitcnt lgkmcnt(0)
	v_lshl_add_u32 v250, v240, 9, v241
	v_lshl_add_u32 v251, v242, 9, v241
	v_lshl_add_u32 v252, v246, 9, v241
	v_lshl_add_u32 v253, v248, 9, v241
	global_load_dwordx4 v[192:195], v250, s[98:99]
	global_load_dwordx4 v[196:199], v251, s[98:99]
	global_load_dwordx4 v[200:203], v252, s[98:99]
	global_load_dwordx4 v[204:207], v253, s[98:99]
	global_load_dwordx4 v[208:211], v250, s[100:101]
	global_load_dwordx4 v[212:215], v251, s[100:101]
	global_load_dwordx4 v[216:219], v252, s[100:101]
	global_load_dwordx4 v[220:223], v253, s[100:101]
	s_add_u32 s23, s22, 2
	s_cmp_lt_u32 s23, 8
	s_cselect_b64 s[8:9], -1, 0
	s_and_b32 s23, s23, 7
	s_lshl_b32 s23, s23, 5
	v_cndmask_b32_e64 v126, v96, v94, s[8:9]
	v_lshl_add_u32 v129, v139, 2, s23
	ds_bpermute_b32 v240, v129, v126
	ds_bpermute_b32 v242, v129, v126 offset:8
	ds_bpermute_b32 v246, v129, v126 offset:16
	ds_bpermute_b32 v248, v129, v126 offset:24
	s_add_u32 s23, s22, 0
	s_cmp_lt_u32 s23, 8
	s_cselect_b64 s[8:9], -1, 0
	s_and_b32 s23, s23, 7
	s_lshl_b32 s23, s23, 5
	v_cndmask_b32_e64 v127, v150, v149, s[8:9]
	v_cndmask_b32_e64 v128, v152, v151, s[8:9]
	v_lshl_add_u32 v130, v140, 2, s23
	ds_bpermute_b32 v156, v130, v127
	ds_bpermute_b32 v157, v130, v128
	s_waitcnt vmcnt(14)
	v_cvt_scalef32_pk_f32_fp4 v[224:225], v160, 1.0
	v_cvt_scalef32_pk_f32_fp4 v[226:227], v164, 1.0
	v_cvt_scalef32_pk_f32_fp4 v[228:229], v160, 1.0 op_sel:[1,0,0]
	v_cvt_scalef32_pk_f32_fp4 v[230:231], v164, 1.0 op_sel:[1,0,0]
	v_pk_fma_f32 v[232:233], v[24:25], v[224:225], 0 op_sel_hi:[1,1,0]
	v_pk_fma_f32 v[234:235], v[24:25], v[226:227], 0 op_sel_hi:[1,1,0]
	v_cvt_scalef32_pk_f32_fp4 v[224:225], v160, 1.0 op_sel:[0,1,0]
	v_cvt_scalef32_pk_f32_fp4 v[226:227], v164, 1.0 op_sel:[0,1,0]
	v_pk_fma_f32 v[232:233], v[26:27], v[228:229], v[232:233]
	v_pk_fma_f32 v[234:235], v[26:27], v[230:231], v[234:235]
	v_cvt_scalef32_pk_f32_fp4 v[228:229], v160, 1.0 op_sel:[1,1,0]
	v_cvt_scalef32_pk_f32_fp4 v[230:231], v164, 1.0 op_sel:[1,1,0]
	v_pk_fma_f32 v[232:233], v[12:13], v[224:225], v[232:233]
	v_pk_fma_f32 v[234:235], v[12:13], v[226:227], v[234:235]
	v_cvt_scalef32_pk_f32_fp4 v[224:225], v161, 1.0
	v_cvt_scalef32_pk_f32_fp4 v[226:227], v165, 1.0
	v_pk_fma_f32 v[232:233], v[14:15], v[228:229], v[232:233]
	v_pk_fma_f32 v[234:235], v[14:15], v[230:231], v[234:235]
	v_cvt_scalef32_pk_f32_fp4 v[228:229], v161, 1.0 op_sel:[1,0,0]
	v_cvt_scalef32_pk_f32_fp4 v[230:231], v165, 1.0 op_sel:[1,0,0]
	v_pk_fma_f32 v[232:233], v[4:5], v[224:225], v[232:233]
	v_pk_fma_f32 v[234:235], v[4:5], v[226:227], v[234:235]
	v_cvt_scalef32_pk_f32_fp4 v[224:225], v161, 1.0 op_sel:[0,1,0]
	v_cvt_scalef32_pk_f32_fp4 v[226:227], v165, 1.0 op_sel:[0,1,0]
	v_pk_fma_f32 v[232:233], v[6:7], v[228:229], v[232:233]
	v_pk_fma_f32 v[234:235], v[6:7], v[230:231], v[234:235]
	v_cvt_scalef32_pk_f32_fp4 v[228:229], v161, 1.0 op_sel:[1,1,0]
	v_cvt_scalef32_pk_f32_fp4 v[230:231], v165, 1.0 op_sel:[1,1,0]
	v_pk_fma_f32 v[232:233], v[0:1], v[224:225], v[232:233]
	v_pk_fma_f32 v[234:235], v[0:1], v[226:227], v[234:235]
	v_cvt_scalef32_pk_f32_fp4 v[224:225], v162, 1.0
	v_cvt_scalef32_pk_f32_fp4 v[226:227], v166, 1.0
	v_pk_fma_f32 v[232:233], v[2:3], v[228:229], v[232:233]
	v_pk_fma_f32 v[234:235], v[2:3], v[230:231], v[234:235]
	v_cvt_scalef32_pk_f32_fp4 v[228:229], v162, 1.0 op_sel:[1,0,0]
	v_cvt_scalef32_pk_f32_fp4 v[230:231], v166, 1.0 op_sel:[1,0,0]
	v_pk_fma_f32 v[232:233], v[28:29], v[224:225], v[232:233]
	v_pk_fma_f32 v[234:235], v[28:29], v[226:227], v[234:235]
	v_cvt_scalef32_pk_f32_fp4 v[224:225], v162, 1.0 op_sel:[0,1,0]
	v_cvt_scalef32_pk_f32_fp4 v[226:227], v166, 1.0 op_sel:[0,1,0]
	v_pk_fma_f32 v[232:233], v[30:31], v[228:229], v[232:233]
	v_pk_fma_f32 v[234:235], v[30:31], v[230:231], v[234:235]
	v_cvt_scalef32_pk_f32_fp4 v[228:229], v162, 1.0 op_sel:[1,1,0]
	v_cvt_scalef32_pk_f32_fp4 v[230:231], v166, 1.0 op_sel:[1,1,0]
	v_pk_fma_f32 v[232:233], v[16:17], v[224:225], v[232:233]
	v_pk_fma_f32 v[234:235], v[16:17], v[226:227], v[234:235]
	v_cvt_scalef32_pk_f32_fp4 v[224:225], v163, 1.0
	v_cvt_scalef32_pk_f32_fp4 v[226:227], v167, 1.0
	v_pk_fma_f32 v[232:233], v[18:19], v[228:229], v[232:233]
	v_pk_fma_f32 v[234:235], v[18:19], v[230:231], v[234:235]
	v_cvt_scalef32_pk_f32_fp4 v[228:229], v163, 1.0 op_sel:[1,0,0]
	v_cvt_scalef32_pk_f32_fp4 v[230:231], v167, 1.0 op_sel:[1,0,0]
	v_pk_fma_f32 v[232:233], v[8:9], v[224:225], v[232:233]
	v_pk_fma_f32 v[234:235], v[8:9], v[226:227], v[234:235]
	v_cvt_scalef32_pk_f32_fp4 v[224:225], v163, 1.0 op_sel:[0,1,0]
	v_cvt_scalef32_pk_f32_fp4 v[226:227], v167, 1.0 op_sel:[0,1,0]
	v_pk_fma_f32 v[232:233], v[10:11], v[228:229], v[232:233]
	v_pk_fma_f32 v[234:235], v[10:11], v[230:231], v[234:235]
	v_cvt_scalef32_pk_f32_fp4 v[228:229], v163, 1.0 op_sel:[1,1,0]
	v_cvt_scalef32_pk_f32_fp4 v[230:231], v167, 1.0 op_sel:[1,1,0]
	v_pk_fma_f32 v[232:233], v[20:21], v[224:225], v[232:233]
	v_pk_fma_f32 v[234:235], v[20:21], v[226:227], v[234:235]
	v_pk_fma_f32 v[232:233], v[22:23], v[228:229], v[232:233]
	v_pk_fma_f32 v[234:235], v[22:23], v[230:231], v[234:235]
	v_add_f32_e32 v32, v232, v233
	v_add_f32_e32 v33, v234, v235
	s_waitcnt vmcnt(12)
	v_cvt_scalef32_pk_f32_fp4 v[224:225], v168, 1.0
	v_cvt_scalef32_pk_f32_fp4 v[226:227], v172, 1.0
	v_cvt_scalef32_pk_f32_fp4 v[228:229], v168, 1.0 op_sel:[1,0,0]
	v_cvt_scalef32_pk_f32_fp4 v[230:231], v172, 1.0 op_sel:[1,0,0]
	v_pk_fma_f32 v[236:237], v[24:25], v[224:225], 0 op_sel_hi:[1,1,0]
	v_pk_fma_f32 v[238:239], v[24:25], v[226:227], 0 op_sel_hi:[1,1,0]
	v_cvt_scalef32_pk_f32_fp4 v[224:225], v168, 1.0 op_sel:[0,1,0]
	v_cvt_scalef32_pk_f32_fp4 v[226:227], v172, 1.0 op_sel:[0,1,0]
	v_pk_fma_f32 v[236:237], v[26:27], v[228:229], v[236:237]
	v_pk_fma_f32 v[238:239], v[26:27], v[230:231], v[238:239]
	v_cvt_scalef32_pk_f32_fp4 v[228:229], v168, 1.0 op_sel:[1,1,0]
	v_cvt_scalef32_pk_f32_fp4 v[230:231], v172, 1.0 op_sel:[1,1,0]
	v_pk_fma_f32 v[236:237], v[12:13], v[224:225], v[236:237]
	v_pk_fma_f32 v[238:239], v[12:13], v[226:227], v[238:239]
	v_cvt_scalef32_pk_f32_fp4 v[224:225], v169, 1.0
	v_cvt_scalef32_pk_f32_fp4 v[226:227], v173, 1.0
	v_pk_fma_f32 v[236:237], v[14:15], v[228:229], v[236:237]
	v_pk_fma_f32 v[238:239], v[14:15], v[230:231], v[238:239]
	v_cvt_scalef32_pk_f32_fp4 v[228:229], v169, 1.0 op_sel:[1,0,0]
	v_cvt_scalef32_pk_f32_fp4 v[230:231], v173, 1.0 op_sel:[1,0,0]
	v_pk_fma_f32 v[236:237], v[4:5], v[224:225], v[236:237]
	v_pk_fma_f32 v[238:239], v[4:5], v[226:227], v[238:239]
	v_cvt_scalef32_pk_f32_fp4 v[224:225], v169, 1.0 op_sel:[0,1,0]
	v_cvt_scalef32_pk_f32_fp4 v[226:227], v173, 1.0 op_sel:[0,1,0]
	v_pk_fma_f32 v[236:237], v[6:7], v[228:229], v[236:237]
	v_pk_fma_f32 v[238:239], v[6:7], v[230:231], v[238:239]
	v_cvt_scalef32_pk_f32_fp4 v[228:229], v169, 1.0 op_sel:[1,1,0]
	v_cvt_scalef32_pk_f32_fp4 v[230:231], v173, 1.0 op_sel:[1,1,0]
	v_pk_fma_f32 v[236:237], v[0:1], v[224:225], v[236:237]
	v_pk_fma_f32 v[238:239], v[0:1], v[226:227], v[238:239]
	v_cvt_scalef32_pk_f32_fp4 v[224:225], v170, 1.0
	v_cvt_scalef32_pk_f32_fp4 v[226:227], v174, 1.0
	v_pk_fma_f32 v[236:237], v[2:3], v[228:229], v[236:237]
	v_pk_fma_f32 v[238:239], v[2:3], v[230:231], v[238:239]
	v_cvt_scalef32_pk_f32_fp4 v[228:229], v170, 1.0 op_sel:[1,0,0]
	v_cvt_scalef32_pk_f32_fp4 v[230:231], v174, 1.0 op_sel:[1,0,0]
	v_pk_fma_f32 v[236:237], v[28:29], v[224:225], v[236:237]
	v_pk_fma_f32 v[238:239], v[28:29], v[226:227], v[238:239]
	v_cvt_scalef32_pk_f32_fp4 v[224:225], v170, 1.0 op_sel:[0,1,0]
	v_cvt_scalef32_pk_f32_fp4 v[226:227], v174, 1.0 op_sel:[0,1,0]
	v_pk_fma_f32 v[236:237], v[30:31], v[228:229], v[236:237]
	v_pk_fma_f32 v[238:239], v[30:31], v[230:231], v[238:239]
	v_cvt_scalef32_pk_f32_fp4 v[228:229], v170, 1.0 op_sel:[1,1,0]
	v_cvt_scalef32_pk_f32_fp4 v[230:231], v174, 1.0 op_sel:[1,1,0]
	v_pk_fma_f32 v[236:237], v[16:17], v[224:225], v[236:237]
	v_pk_fma_f32 v[238:239], v[16:17], v[226:227], v[238:239]
	v_cvt_scalef32_pk_f32_fp4 v[224:225], v171, 1.0
	v_cvt_scalef32_pk_f32_fp4 v[226:227], v175, 1.0
	v_pk_fma_f32 v[236:237], v[18:19], v[228:229], v[236:237]
	v_pk_fma_f32 v[238:239], v[18:19], v[230:231], v[238:239]
	v_cvt_scalef32_pk_f32_fp4 v[228:229], v171, 1.0 op_sel:[1,0,0]
	v_cvt_scalef32_pk_f32_fp4 v[230:231], v175, 1.0 op_sel:[1,0,0]
	v_pk_fma_f32 v[236:237], v[8:9], v[224:225], v[236:237]
	v_pk_fma_f32 v[238:239], v[8:9], v[226:227], v[238:239]
	v_cvt_scalef32_pk_f32_fp4 v[224:225], v171, 1.0 op_sel:[0,1,0]
	v_cvt_scalef32_pk_f32_fp4 v[226:227], v175, 1.0 op_sel:[0,1,0]
	v_pk_fma_f32 v[236:237], v[10:11], v[228:229], v[236:237]
	v_pk_fma_f32 v[238:239], v[10:11], v[230:231], v[238:239]
	v_cvt_scalef32_pk_f32_fp4 v[228:229], v171, 1.0 op_sel:[1,1,0]
	v_cvt_scalef32_pk_f32_fp4 v[230:231], v175, 1.0 op_sel:[1,1,0]
	v_pk_fma_f32 v[236:237], v[20:21], v[224:225], v[236:237]
	v_pk_fma_f32 v[238:239], v[20:21], v[226:227], v[238:239]
	v_pk_fma_f32 v[236:237], v[22:23], v[228:229], v[236:237]
	v_pk_fma_f32 v[238:239], v[22:23], v[230:231], v[238:239]
	v_add_f32_e32 v34, v236, v237
	v_add_f32_e32 v35, v238, v239
	v_cndmask_b32_e32 v36, v34, v32, vcc
	v_cndmask_b32_e32 v37, v32, v34, vcc
	v_cndmask_b32_e32 v38, v35, v33, vcc
	v_cndmask_b32_e32 v39, v33, v35, vcc
	ds_bpermute_b32 v37, v61, v37
	ds_bpermute_b32 v39, v61, v39
	s_waitcnt lgkmcnt(0)
	v_add_f32_e32 v36, v36, v37
	v_add_f32_e32 v38, v38, v39
	v_cndmask_b32_e64 v40, v38, v36, s[4:5]
	v_cndmask_b32_e64 v41, v36, v38, s[4:5]
	s_nop 1
	v_add_f32_dpp v40, v41, v40 row_ror:8 row_mask:0xf bank_mask:0xf
	s_nop 1
	v_add_f32_dpp v40, v40, v40 quad_perm:[1,0,3,2] row_mask:0xf bank_mask:0xf
	s_nop 1
	v_add_f32_dpp v40, v40, v40 quad_perm:[2,3,0,1] row_mask:0xf bank_mask:0xf
	s_nop 1
	v_add_f32_dpp v40, v40, v40 row_half_mirror row_mask:0xf bank_mask:0xf
	v_mul_f32_e32 v42, v40, v156
	v_fma_f32 v43, |v42|, s19, 1.0
	v_rcp_f32_e32 v43, v43
	v_cmp_gt_f32_e64 s[8:9], 0, v42
	v_mul_f32_e32 v45, v42, v42
	v_fmamk_f32 v44, v43, 0x3f07dc22, v145
	v_fmaak_f32 v44, v43, v44, 0x3f35f0e3
	v_fmaak_f32 v44, v43, v44, 0xbe11a98e
	v_fmaak_f32 v44, v43, v44, 0x3e027906
	v_mul_f32_e32 v45, 0xbf38aa3b, v45
	v_exp_f32_e32 v45, v45
	v_mul_f32_e32 v43, v43, v44
	v_mul_f32_e32 v43, v45, v43
	v_mul_f32_e32 v44, v42, v43
	v_fma_f32 v42, -v42, v43, v42
	v_cndmask_b32_e64 v42, v42, v44, s[8:9]
	v_mul_f32_e32 v158, v42, v157
	ds_bpermute_b32 v118, v141, v158
	ds_bpermute_b32 v120, v142, v158
	ds_bpermute_b32 v122, v143, v158
	ds_bpermute_b32 v124, v144, v158
	s_waitcnt vmcnt(11)
	v_cvt_scalef32_pk_f32_fp4 v[224:225], v176, 1.0
	v_cvt_scalef32_pk_f32_fp4 v[226:227], v176, 1.0 op_sel:[1,0,0]
	s_waitcnt lgkmcnt(0)
	v_cvt_scalef32_pk_f32_fp4 v[228:229], v176, 1.0 op_sel:[0,1,0]
	v_pk_fma_f32 v[114:115], v[224:225], v[118:119], v[114:115] op_sel_hi:[1,0,1]
	v_cvt_scalef32_pk_f32_fp4 v[230:231], v176, 1.0 op_sel:[1,1,0]
	v_pk_fma_f32 v[110:111], v[226:227], v[118:119], v[110:111] op_sel_hi:[1,0,1]
	v_cvt_scalef32_pk_f32_fp4 v[224:225], v177, 1.0
	v_pk_fma_f32 v[102:103], v[228:229], v[118:119], v[102:103] op_sel_hi:[1,0,1]
	v_cvt_scalef32_pk_f32_fp4 v[226:227], v177, 1.0 op_sel:[1,0,0]
	v_pk_fma_f32 v[100:101], v[230:231], v[118:119], v[100:101] op_sel_hi:[1,0,1]
	v_cvt_scalef32_pk_f32_fp4 v[228:229], v177, 1.0 op_sel:[0,1,0]
	v_pk_fma_f32 v[54:55], v[224:225], v[118:119], v[54:55] op_sel_hi:[1,0,1]
	v_cvt_scalef32_pk_f32_fp4 v[230:231], v177, 1.0 op_sel:[1,1,0]
	v_pk_fma_f32 v[58:59], v[226:227], v[118:119], v[58:59] op_sel_hi:[1,0,1]
	v_cvt_scalef32_pk_f32_fp4 v[224:225], v178, 1.0
	v_pk_fma_f32 v[52:53], v[228:229], v[118:119], v[52:53] op_sel_hi:[1,0,1]
	v_cvt_scalef32_pk_f32_fp4 v[226:227], v178, 1.0 op_sel:[1,0,0]
	v_pk_fma_f32 v[48:49], v[230:231], v[118:119], v[48:49] op_sel_hi:[1,0,1]
	v_cvt_scalef32_pk_f32_fp4 v[228:229], v178, 1.0 op_sel:[0,1,0]
	v_pk_fma_f32 v[108:109], v[224:225], v[118:119], v[108:109] op_sel_hi:[1,0,1]
	v_cvt_scalef32_pk_f32_fp4 v[230:231], v178, 1.0 op_sel:[1,1,0]
	v_pk_fma_f32 v[106:107], v[226:227], v[118:119], v[106:107] op_sel_hi:[1,0,1]
	v_cvt_scalef32_pk_f32_fp4 v[224:225], v179, 1.0
	v_pk_fma_f32 v[98:99], v[228:229], v[118:119], v[98:99] op_sel_hi:[1,0,1]
	v_cvt_scalef32_pk_f32_fp4 v[226:227], v179, 1.0 op_sel:[1,0,0]
	v_pk_fma_f32 v[56:57], v[230:231], v[118:119], v[56:57] op_sel_hi:[1,0,1]
	v_cvt_scalef32_pk_f32_fp4 v[228:229], v179, 1.0 op_sel:[0,1,0]
	v_pk_fma_f32 v[50:51], v[224:225], v[118:119], v[50:51] op_sel_hi:[1,0,1]
	v_cvt_scalef32_pk_f32_fp4 v[230:231], v179, 1.0 op_sel:[1,1,0]
	v_pk_fma_f32 v[116:117], v[226:227], v[118:119], v[116:117] op_sel_hi:[1,0,1]
	v_pk_fma_f32 v[112:113], v[228:229], v[118:119], v[112:113] op_sel_hi:[1,0,1]
	v_pk_fma_f32 v[104:105], v[230:231], v[118:119], v[104:105] op_sel_hi:[1,0,1]
	s_waitcnt vmcnt(10)
	v_cvt_scalef32_pk_f32_fp4 v[224:225], v180, 1.0
	v_cvt_scalef32_pk_f32_fp4 v[226:227], v180, 1.0 op_sel:[1,0,0]
	v_cvt_scalef32_pk_f32_fp4 v[228:229], v180, 1.0 op_sel:[0,1,0]
	v_pk_fma_f32 v[114:115], v[224:225], v[120:121], v[114:115] op_sel_hi:[1,0,1]
	v_cvt_scalef32_pk_f32_fp4 v[230:231], v180, 1.0 op_sel:[1,1,0]
	v_pk_fma_f32 v[110:111], v[226:227], v[120:121], v[110:111] op_sel_hi:[1,0,1]
	v_cvt_scalef32_pk_f32_fp4 v[224:225], v181, 1.0
	v_pk_fma_f32 v[102:103], v[228:229], v[120:121], v[102:103] op_sel_hi:[1,0,1]
	v_cvt_scalef32_pk_f32_fp4 v[226:227], v181, 1.0 op_sel:[1,0,0]
	v_pk_fma_f32 v[100:101], v[230:231], v[120:121], v[100:101] op_sel_hi:[1,0,1]
	v_cvt_scalef32_pk_f32_fp4 v[228:229], v181, 1.0 op_sel:[0,1,0]
	v_pk_fma_f32 v[54:55], v[224:225], v[120:121], v[54:55] op_sel_hi:[1,0,1]
	v_cvt_scalef32_pk_f32_fp4 v[230:231], v181, 1.0 op_sel:[1,1,0]
	v_pk_fma_f32 v[58:59], v[226:227], v[120:121], v[58:59] op_sel_hi:[1,0,1]
	v_cvt_scalef32_pk_f32_fp4 v[224:225], v182, 1.0
	v_pk_fma_f32 v[52:53], v[228:229], v[120:121], v[52:53] op_sel_hi:[1,0,1]
	v_cvt_scalef32_pk_f32_fp4 v[226:227], v182, 1.0 op_sel:[1,0,0]
	v_pk_fma_f32 v[48:49], v[230:231], v[120:121], v[48:49] op_sel_hi:[1,0,1]
	v_cvt_scalef32_pk_f32_fp4 v[228:229], v182, 1.0 op_sel:[0,1,0]
	v_pk_fma_f32 v[108:109], v[224:225], v[120:121], v[108:109] op_sel_hi:[1,0,1]
	v_cvt_scalef32_pk_f32_fp4 v[230:231], v182, 1.0 op_sel:[1,1,0]
	v_pk_fma_f32 v[106:107], v[226:227], v[120:121], v[106:107] op_sel_hi:[1,0,1]
	v_cvt_scalef32_pk_f32_fp4 v[224:225], v183, 1.0
	v_pk_fma_f32 v[98:99], v[228:229], v[120:121], v[98:99] op_sel_hi:[1,0,1]
	v_cvt_scalef32_pk_f32_fp4 v[226:227], v183, 1.0 op_sel:[1,0,0]
	v_pk_fma_f32 v[56:57], v[230:231], v[120:121], v[56:57] op_sel_hi:[1,0,1]
	v_cvt_scalef32_pk_f32_fp4 v[228:229], v183, 1.0 op_sel:[0,1,0]
	v_pk_fma_f32 v[50:51], v[224:225], v[120:121], v[50:51] op_sel_hi:[1,0,1]
	v_cvt_scalef32_pk_f32_fp4 v[230:231], v183, 1.0 op_sel:[1,1,0]
	v_pk_fma_f32 v[116:117], v[226:227], v[120:121], v[116:117] op_sel_hi:[1,0,1]
	v_pk_fma_f32 v[112:113], v[228:229], v[120:121], v[112:113] op_sel_hi:[1,0,1]
	v_pk_fma_f32 v[104:105], v[230:231], v[120:121], v[104:105] op_sel_hi:[1,0,1]
	s_waitcnt vmcnt(9)
	v_cvt_scalef32_pk_f32_fp4 v[224:225], v184, 1.0
	v_cvt_scalef32_pk_f32_fp4 v[226:227], v184, 1.0 op_sel:[1,0,0]
	v_cvt_scalef32_pk_f32_fp4 v[228:229], v184, 1.0 op_sel:[0,1,0]
	v_pk_fma_f32 v[114:115], v[224:225], v[122:123], v[114:115] op_sel_hi:[1,0,1]
	v_cvt_scalef32_pk_f32_fp4 v[230:231], v184, 1.0 op_sel:[1,1,0]
	v_pk_fma_f32 v[110:111], v[226:227], v[122:123], v[110:111] op_sel_hi:[1,0,1]
	v_cvt_scalef32_pk_f32_fp4 v[224:225], v185, 1.0
	v_pk_fma_f32 v[102:103], v[228:229], v[122:123], v[102:103] op_sel_hi:[1,0,1]
	v_cvt_scalef32_pk_f32_fp4 v[226:227], v185, 1.0 op_sel:[1,0,0]
	v_pk_fma_f32 v[100:101], v[230:231], v[122:123], v[100:101] op_sel_hi:[1,0,1]
	v_cvt_scalef32_pk_f32_fp4 v[228:229], v185, 1.0 op_sel:[0,1,0]
	v_pk_fma_f32 v[54:55], v[224:225], v[122:123], v[54:55] op_sel_hi:[1,0,1]
	v_cvt_scalef32_pk_f32_fp4 v[230:231], v185, 1.0 op_sel:[1,1,0]
	v_pk_fma_f32 v[58:59], v[226:227], v[122:123], v[58:59] op_sel_hi:[1,0,1]
	v_cvt_scalef32_pk_f32_fp4 v[224:225], v186, 1.0
	v_pk_fma_f32 v[52:53], v[228:229], v[122:123], v[52:53] op_sel_hi:[1,0,1]
	v_cvt_scalef32_pk_f32_fp4 v[226:227], v186, 1.0 op_sel:[1,0,0]
	v_pk_fma_f32 v[48:49], v[230:231], v[122:123], v[48:49] op_sel_hi:[1,0,1]
	v_cvt_scalef32_pk_f32_fp4 v[228:229], v186, 1.0 op_sel:[0,1,0]
	v_pk_fma_f32 v[108:109], v[224:225], v[122:123], v[108:109] op_sel_hi:[1,0,1]
	v_cvt_scalef32_pk_f32_fp4 v[230:231], v186, 1.0 op_sel:[1,1,0]
	v_pk_fma_f32 v[106:107], v[226:227], v[122:123], v[106:107] op_sel_hi:[1,0,1]
	v_cvt_scalef32_pk_f32_fp4 v[224:225], v187, 1.0
	v_pk_fma_f32 v[98:99], v[228:229], v[122:123], v[98:99] op_sel_hi:[1,0,1]
	v_cvt_scalef32_pk_f32_fp4 v[226:227], v187, 1.0 op_sel:[1,0,0]
	v_pk_fma_f32 v[56:57], v[230:231], v[122:123], v[56:57] op_sel_hi:[1,0,1]
	v_cvt_scalef32_pk_f32_fp4 v[228:229], v187, 1.0 op_sel:[0,1,0]
	v_pk_fma_f32 v[50:51], v[224:225], v[122:123], v[50:51] op_sel_hi:[1,0,1]
	v_cvt_scalef32_pk_f32_fp4 v[230:231], v187, 1.0 op_sel:[1,1,0]
	v_pk_fma_f32 v[116:117], v[226:227], v[122:123], v[116:117] op_sel_hi:[1,0,1]
	v_pk_fma_f32 v[112:113], v[228:229], v[122:123], v[112:113] op_sel_hi:[1,0,1]
	v_pk_fma_f32 v[104:105], v[230:231], v[122:123], v[104:105] op_sel_hi:[1,0,1]
	s_waitcnt vmcnt(8)
	v_cvt_scalef32_pk_f32_fp4 v[224:225], v188, 1.0
	v_cvt_scalef32_pk_f32_fp4 v[226:227], v188, 1.0 op_sel:[1,0,0]
	v_cvt_scalef32_pk_f32_fp4 v[228:229], v188, 1.0 op_sel:[0,1,0]
	v_pk_fma_f32 v[114:115], v[224:225], v[124:125], v[114:115] op_sel_hi:[1,0,1]
	v_cvt_scalef32_pk_f32_fp4 v[230:231], v188, 1.0 op_sel:[1,1,0]
	v_pk_fma_f32 v[110:111], v[226:227], v[124:125], v[110:111] op_sel_hi:[1,0,1]
	v_cvt_scalef32_pk_f32_fp4 v[224:225], v189, 1.0
	v_pk_fma_f32 v[102:103], v[228:229], v[124:125], v[102:103] op_sel_hi:[1,0,1]
	v_cvt_scalef32_pk_f32_fp4 v[226:227], v189, 1.0 op_sel:[1,0,0]
	v_pk_fma_f32 v[100:101], v[230:231], v[124:125], v[100:101] op_sel_hi:[1,0,1]
	v_cvt_scalef32_pk_f32_fp4 v[228:229], v189, 1.0 op_sel:[0,1,0]
	v_pk_fma_f32 v[54:55], v[224:225], v[124:125], v[54:55] op_sel_hi:[1,0,1]
	v_cvt_scalef32_pk_f32_fp4 v[230:231], v189, 1.0 op_sel:[1,1,0]
	v_pk_fma_f32 v[58:59], v[226:227], v[124:125], v[58:59] op_sel_hi:[1,0,1]
	v_cvt_scalef32_pk_f32_fp4 v[224:225], v190, 1.0
	v_pk_fma_f32 v[52:53], v[228:229], v[124:125], v[52:53] op_sel_hi:[1,0,1]
	v_cvt_scalef32_pk_f32_fp4 v[226:227], v190, 1.0 op_sel:[1,0,0]
	v_pk_fma_f32 v[48:49], v[230:231], v[124:125], v[48:49] op_sel_hi:[1,0,1]
	v_cvt_scalef32_pk_f32_fp4 v[228:229], v190, 1.0 op_sel:[0,1,0]
	v_pk_fma_f32 v[108:109], v[224:225], v[124:125], v[108:109] op_sel_hi:[1,0,1]
	v_cvt_scalef32_pk_f32_fp4 v[230:231], v190, 1.0 op_sel:[1,1,0]
	v_pk_fma_f32 v[106:107], v[226:227], v[124:125], v[106:107] op_sel_hi:[1,0,1]
	v_cvt_scalef32_pk_f32_fp4 v[224:225], v191, 1.0
	v_pk_fma_f32 v[98:99], v[228:229], v[124:125], v[98:99] op_sel_hi:[1,0,1]
	v_cvt_scalef32_pk_f32_fp4 v[226:227], v191, 1.0 op_sel:[1,0,0]
	v_pk_fma_f32 v[56:57], v[230:231], v[124:125], v[56:57] op_sel_hi:[1,0,1]
	v_cvt_scalef32_pk_f32_fp4 v[228:229], v191, 1.0 op_sel:[0,1,0]
	v_pk_fma_f32 v[50:51], v[224:225], v[124:125], v[50:51] op_sel_hi:[1,0,1]
	v_cvt_scalef32_pk_f32_fp4 v[230:231], v191, 1.0 op_sel:[1,1,0]
	v_pk_fma_f32 v[116:117], v[226:227], v[124:125], v[116:117] op_sel_hi:[1,0,1]
	v_pk_fma_f32 v[112:113], v[228:229], v[124:125], v[112:113] op_sel_hi:[1,0,1]
	v_pk_fma_f32 v[104:105], v[230:231], v[124:125], v[104:105] op_sel_hi:[1,0,1]
	s_waitcnt lgkmcnt(0)
	v_lshl_add_u32 v250, v240, 9, v241
	v_lshl_add_u32 v251, v242, 9, v241
	v_lshl_add_u32 v252, v246, 9, v241
	v_lshl_add_u32 v253, v248, 9, v241
	global_load_dwordx4 v[160:163], v250, s[98:99]
	global_load_dwordx4 v[164:167], v251, s[98:99]
	global_load_dwordx4 v[168:171], v252, s[98:99]
	global_load_dwordx4 v[172:175], v253, s[98:99]
	global_load_dwordx4 v[176:179], v250, s[100:101]
	global_load_dwordx4 v[180:183], v251, s[100:101]
	global_load_dwordx4 v[184:187], v252, s[100:101]
	global_load_dwordx4 v[188:191], v253, s[100:101]
	s_add_u32 s23, s22, 3
	s_cmp_lt_u32 s23, 8
	s_cselect_b64 s[8:9], -1, 0
	s_and_b32 s23, s23, 7
	s_lshl_b32 s23, s23, 5
	v_cndmask_b32_e64 v126, v96, v94, s[8:9]
	v_lshl_add_u32 v129, v139, 2, s23
	ds_bpermute_b32 v240, v129, v126
	ds_bpermute_b32 v242, v129, v126 offset:8
	ds_bpermute_b32 v246, v129, v126 offset:16
	ds_bpermute_b32 v248, v129, v126 offset:24
	s_add_u32 s23, s22, 1
	s_cmp_lt_u32 s23, 8
	s_cselect_b64 s[8:9], -1, 0
	s_and_b32 s23, s23, 7
	s_lshl_b32 s23, s23, 5
	v_cndmask_b32_e64 v127, v150, v149, s[8:9]
	v_cndmask_b32_e64 v128, v152, v151, s[8:9]
	v_lshl_add_u32 v130, v140, 2, s23
	ds_bpermute_b32 v156, v130, v127
	ds_bpermute_b32 v157, v130, v128
	s_waitcnt vmcnt(14)
	v_cvt_scalef32_pk_f32_fp4 v[224:225], v192, 1.0
	v_cvt_scalef32_pk_f32_fp4 v[226:227], v196, 1.0
	v_cvt_scalef32_pk_f32_fp4 v[228:229], v192, 1.0 op_sel:[1,0,0]
	v_cvt_scalef32_pk_f32_fp4 v[230:231], v196, 1.0 op_sel:[1,0,0]
	v_pk_fma_f32 v[232:233], v[24:25], v[224:225], 0 op_sel_hi:[1,1,0]
	v_pk_fma_f32 v[234:235], v[24:25], v[226:227], 0 op_sel_hi:[1,1,0]
	v_cvt_scalef32_pk_f32_fp4 v[224:225], v192, 1.0 op_sel:[0,1,0]
	v_cvt_scalef32_pk_f32_fp4 v[226:227], v196, 1.0 op_sel:[0,1,0]
	v_pk_fma_f32 v[232:233], v[26:27], v[228:229], v[232:233]
	v_pk_fma_f32 v[234:235], v[26:27], v[230:231], v[234:235]
	v_cvt_scalef32_pk_f32_fp4 v[228:229], v192, 1.0 op_sel:[1,1,0]
	v_cvt_scalef32_pk_f32_fp4 v[230:231], v196, 1.0 op_sel:[1,1,0]
	v_pk_fma_f32 v[232:233], v[12:13], v[224:225], v[232:233]
	v_pk_fma_f32 v[234:235], v[12:13], v[226:227], v[234:235]
	v_cvt_scalef32_pk_f32_fp4 v[224:225], v193, 1.0
	v_cvt_scalef32_pk_f32_fp4 v[226:227], v197, 1.0
	v_pk_fma_f32 v[232:233], v[14:15], v[228:229], v[232:233]
	v_pk_fma_f32 v[234:235], v[14:15], v[230:231], v[234:235]
	v_cvt_scalef32_pk_f32_fp4 v[228:229], v193, 1.0 op_sel:[1,0,0]
	v_cvt_scalef32_pk_f32_fp4 v[230:231], v197, 1.0 op_sel:[1,0,0]
	v_pk_fma_f32 v[232:233], v[4:5], v[224:225], v[232:233]
	v_pk_fma_f32 v[234:235], v[4:5], v[226:227], v[234:235]
	v_cvt_scalef32_pk_f32_fp4 v[224:225], v193, 1.0 op_sel:[0,1,0]
	v_cvt_scalef32_pk_f32_fp4 v[226:227], v197, 1.0 op_sel:[0,1,0]
	v_pk_fma_f32 v[232:233], v[6:7], v[228:229], v[232:233]
	v_pk_fma_f32 v[234:235], v[6:7], v[230:231], v[234:235]
	v_cvt_scalef32_pk_f32_fp4 v[228:229], v193, 1.0 op_sel:[1,1,0]
	v_cvt_scalef32_pk_f32_fp4 v[230:231], v197, 1.0 op_sel:[1,1,0]
	v_pk_fma_f32 v[232:233], v[0:1], v[224:225], v[232:233]
	v_pk_fma_f32 v[234:235], v[0:1], v[226:227], v[234:235]
	v_cvt_scalef32_pk_f32_fp4 v[224:225], v194, 1.0
	v_cvt_scalef32_pk_f32_fp4 v[226:227], v198, 1.0
	v_pk_fma_f32 v[232:233], v[2:3], v[228:229], v[232:233]
	v_pk_fma_f32 v[234:235], v[2:3], v[230:231], v[234:235]
	v_cvt_scalef32_pk_f32_fp4 v[228:229], v194, 1.0 op_sel:[1,0,0]
	v_cvt_scalef32_pk_f32_fp4 v[230:231], v198, 1.0 op_sel:[1,0,0]
	v_pk_fma_f32 v[232:233], v[28:29], v[224:225], v[232:233]
	v_pk_fma_f32 v[234:235], v[28:29], v[226:227], v[234:235]
	v_cvt_scalef32_pk_f32_fp4 v[224:225], v194, 1.0 op_sel:[0,1,0]
	v_cvt_scalef32_pk_f32_fp4 v[226:227], v198, 1.0 op_sel:[0,1,0]
	v_pk_fma_f32 v[232:233], v[30:31], v[228:229], v[232:233]
	v_pk_fma_f32 v[234:235], v[30:31], v[230:231], v[234:235]
	v_cvt_scalef32_pk_f32_fp4 v[228:229], v194, 1.0 op_sel:[1,1,0]
	v_cvt_scalef32_pk_f32_fp4 v[230:231], v198, 1.0 op_sel:[1,1,0]
	v_pk_fma_f32 v[232:233], v[16:17], v[224:225], v[232:233]
	v_pk_fma_f32 v[234:235], v[16:17], v[226:227], v[234:235]
	v_cvt_scalef32_pk_f32_fp4 v[224:225], v195, 1.0
	v_cvt_scalef32_pk_f32_fp4 v[226:227], v199, 1.0
	v_pk_fma_f32 v[232:233], v[18:19], v[228:229], v[232:233]
	v_pk_fma_f32 v[234:235], v[18:19], v[230:231], v[234:235]
	v_cvt_scalef32_pk_f32_fp4 v[228:229], v195, 1.0 op_sel:[1,0,0]
	v_cvt_scalef32_pk_f32_fp4 v[230:231], v199, 1.0 op_sel:[1,0,0]
	v_pk_fma_f32 v[232:233], v[8:9], v[224:225], v[232:233]
	v_pk_fma_f32 v[234:235], v[8:9], v[226:227], v[234:235]
	v_cvt_scalef32_pk_f32_fp4 v[224:225], v195, 1.0 op_sel:[0,1,0]
	v_cvt_scalef32_pk_f32_fp4 v[226:227], v199, 1.0 op_sel:[0,1,0]
	v_pk_fma_f32 v[232:233], v[10:11], v[228:229], v[232:233]
	v_pk_fma_f32 v[234:235], v[10:11], v[230:231], v[234:235]
	v_cvt_scalef32_pk_f32_fp4 v[228:229], v195, 1.0 op_sel:[1,1,0]
	v_cvt_scalef32_pk_f32_fp4 v[230:231], v199, 1.0 op_sel:[1,1,0]
	v_pk_fma_f32 v[232:233], v[20:21], v[224:225], v[232:233]
	v_pk_fma_f32 v[234:235], v[20:21], v[226:227], v[234:235]
	v_pk_fma_f32 v[232:233], v[22:23], v[228:229], v[232:233]
	v_pk_fma_f32 v[234:235], v[22:23], v[230:231], v[234:235]
	v_add_f32_e32 v32, v232, v233
	v_add_f32_e32 v33, v234, v235
	s_waitcnt vmcnt(12)
	v_cvt_scalef32_pk_f32_fp4 v[224:225], v200, 1.0
	v_cvt_scalef32_pk_f32_fp4 v[226:227], v204, 1.0
	v_cvt_scalef32_pk_f32_fp4 v[228:229], v200, 1.0 op_sel:[1,0,0]
	v_cvt_scalef32_pk_f32_fp4 v[230:231], v204, 1.0 op_sel:[1,0,0]
	v_pk_fma_f32 v[236:237], v[24:25], v[224:225], 0 op_sel_hi:[1,1,0]
	v_pk_fma_f32 v[238:239], v[24:25], v[226:227], 0 op_sel_hi:[1,1,0]
	v_cvt_scalef32_pk_f32_fp4 v[224:225], v200, 1.0 op_sel:[0,1,0]
	v_cvt_scalef32_pk_f32_fp4 v[226:227], v204, 1.0 op_sel:[0,1,0]
	v_pk_fma_f32 v[236:237], v[26:27], v[228:229], v[236:237]
	v_pk_fma_f32 v[238:239], v[26:27], v[230:231], v[238:239]
	v_cvt_scalef32_pk_f32_fp4 v[228:229], v200, 1.0 op_sel:[1,1,0]
	v_cvt_scalef32_pk_f32_fp4 v[230:231], v204, 1.0 op_sel:[1,1,0]
	v_pk_fma_f32 v[236:237], v[12:13], v[224:225], v[236:237]
	v_pk_fma_f32 v[238:239], v[12:13], v[226:227], v[238:239]
	v_cvt_scalef32_pk_f32_fp4 v[224:225], v201, 1.0
	v_cvt_scalef32_pk_f32_fp4 v[226:227], v205, 1.0
	v_pk_fma_f32 v[236:237], v[14:15], v[228:229], v[236:237]
	v_pk_fma_f32 v[238:239], v[14:15], v[230:231], v[238:239]
	v_cvt_scalef32_pk_f32_fp4 v[228:229], v201, 1.0 op_sel:[1,0,0]
	v_cvt_scalef32_pk_f32_fp4 v[230:231], v205, 1.0 op_sel:[1,0,0]
	v_pk_fma_f32 v[236:237], v[4:5], v[224:225], v[236:237]
	v_pk_fma_f32 v[238:239], v[4:5], v[226:227], v[238:239]
	v_cvt_scalef32_pk_f32_fp4 v[224:225], v201, 1.0 op_sel:[0,1,0]
	v_cvt_scalef32_pk_f32_fp4 v[226:227], v205, 1.0 op_sel:[0,1,0]
	v_pk_fma_f32 v[236:237], v[6:7], v[228:229], v[236:237]
	v_pk_fma_f32 v[238:239], v[6:7], v[230:231], v[238:239]
	v_cvt_scalef32_pk_f32_fp4 v[228:229], v201, 1.0 op_sel:[1,1,0]
	v_cvt_scalef32_pk_f32_fp4 v[230:231], v205, 1.0 op_sel:[1,1,0]
	v_pk_fma_f32 v[236:237], v[0:1], v[224:225], v[236:237]
	v_pk_fma_f32 v[238:239], v[0:1], v[226:227], v[238:239]
	v_cvt_scalef32_pk_f32_fp4 v[224:225], v202, 1.0
	v_cvt_scalef32_pk_f32_fp4 v[226:227], v206, 1.0
	v_pk_fma_f32 v[236:237], v[2:3], v[228:229], v[236:237]
	v_pk_fma_f32 v[238:239], v[2:3], v[230:231], v[238:239]
	v_cvt_scalef32_pk_f32_fp4 v[228:229], v202, 1.0 op_sel:[1,0,0]
	v_cvt_scalef32_pk_f32_fp4 v[230:231], v206, 1.0 op_sel:[1,0,0]
	v_pk_fma_f32 v[236:237], v[28:29], v[224:225], v[236:237]
	v_pk_fma_f32 v[238:239], v[28:29], v[226:227], v[238:239]
	v_cvt_scalef32_pk_f32_fp4 v[224:225], v202, 1.0 op_sel:[0,1,0]
	v_cvt_scalef32_pk_f32_fp4 v[226:227], v206, 1.0 op_sel:[0,1,0]
	v_pk_fma_f32 v[236:237], v[30:31], v[228:229], v[236:237]
	v_pk_fma_f32 v[238:239], v[30:31], v[230:231], v[238:239]
	v_cvt_scalef32_pk_f32_fp4 v[228:229], v202, 1.0 op_sel:[1,1,0]
	v_cvt_scalef32_pk_f32_fp4 v[230:231], v206, 1.0 op_sel:[1,1,0]
	v_pk_fma_f32 v[236:237], v[16:17], v[224:225], v[236:237]
	v_pk_fma_f32 v[238:239], v[16:17], v[226:227], v[238:239]
	v_cvt_scalef32_pk_f32_fp4 v[224:225], v203, 1.0
	v_cvt_scalef32_pk_f32_fp4 v[226:227], v207, 1.0
	v_pk_fma_f32 v[236:237], v[18:19], v[228:229], v[236:237]
	v_pk_fma_f32 v[238:239], v[18:19], v[230:231], v[238:239]
	v_cvt_scalef32_pk_f32_fp4 v[228:229], v203, 1.0 op_sel:[1,0,0]
	v_cvt_scalef32_pk_f32_fp4 v[230:231], v207, 1.0 op_sel:[1,0,0]
	v_pk_fma_f32 v[236:237], v[8:9], v[224:225], v[236:237]
	v_pk_fma_f32 v[238:239], v[8:9], v[226:227], v[238:239]
	v_cvt_scalef32_pk_f32_fp4 v[224:225], v203, 1.0 op_sel:[0,1,0]
	v_cvt_scalef32_pk_f32_fp4 v[226:227], v207, 1.0 op_sel:[0,1,0]
	v_pk_fma_f32 v[236:237], v[10:11], v[228:229], v[236:237]
	v_pk_fma_f32 v[238:239], v[10:11], v[230:231], v[238:239]
	v_cvt_scalef32_pk_f32_fp4 v[228:229], v203, 1.0 op_sel:[1,1,0]
	v_cvt_scalef32_pk_f32_fp4 v[230:231], v207, 1.0 op_sel:[1,1,0]
	v_pk_fma_f32 v[236:237], v[20:21], v[224:225], v[236:237]
	v_pk_fma_f32 v[238:239], v[20:21], v[226:227], v[238:239]
	v_pk_fma_f32 v[236:237], v[22:23], v[228:229], v[236:237]
	v_pk_fma_f32 v[238:239], v[22:23], v[230:231], v[238:239]
	v_add_f32_e32 v34, v236, v237
	v_add_f32_e32 v35, v238, v239
	v_cndmask_b32_e32 v36, v34, v32, vcc
	v_cndmask_b32_e32 v37, v32, v34, vcc
	v_cndmask_b32_e32 v38, v35, v33, vcc
	v_cndmask_b32_e32 v39, v33, v35, vcc
	ds_bpermute_b32 v37, v61, v37
	ds_bpermute_b32 v39, v61, v39
	s_waitcnt lgkmcnt(0)
	v_add_f32_e32 v36, v36, v37
	v_add_f32_e32 v38, v38, v39
	v_cndmask_b32_e64 v40, v38, v36, s[4:5]
	v_cndmask_b32_e64 v41, v36, v38, s[4:5]
	s_nop 1
	v_add_f32_dpp v40, v41, v40 row_ror:8 row_mask:0xf bank_mask:0xf
	s_nop 1
	v_add_f32_dpp v40, v40, v40 quad_perm:[1,0,3,2] row_mask:0xf bank_mask:0xf
	s_nop 1
	v_add_f32_dpp v40, v40, v40 quad_perm:[2,3,0,1] row_mask:0xf bank_mask:0xf
	s_nop 1
	v_add_f32_dpp v40, v40, v40 row_half_mirror row_mask:0xf bank_mask:0xf
	v_mul_f32_e32 v42, v40, v156
	v_fma_f32 v43, |v42|, s19, 1.0
	v_rcp_f32_e32 v43, v43
	v_cmp_gt_f32_e64 s[8:9], 0, v42
	v_mul_f32_e32 v45, v42, v42
	v_fmamk_f32 v44, v43, 0x3f07dc22, v145
	v_fmaak_f32 v44, v43, v44, 0x3f35f0e3
	v_fmaak_f32 v44, v43, v44, 0xbe11a98e
	v_fmaak_f32 v44, v43, v44, 0x3e027906
	v_mul_f32_e32 v45, 0xbf38aa3b, v45
	v_exp_f32_e32 v45, v45
	v_mul_f32_e32 v43, v43, v44
	v_mul_f32_e32 v43, v45, v43
	v_mul_f32_e32 v44, v42, v43
	v_fma_f32 v42, -v42, v43, v42
	v_cndmask_b32_e64 v42, v42, v44, s[8:9]
	v_mul_f32_e32 v158, v42, v157
	ds_bpermute_b32 v118, v141, v158
	ds_bpermute_b32 v120, v142, v158
	ds_bpermute_b32 v122, v143, v158
	ds_bpermute_b32 v124, v144, v158
	s_waitcnt vmcnt(11)
	v_cvt_scalef32_pk_f32_fp4 v[224:225], v208, 1.0
	v_cvt_scalef32_pk_f32_fp4 v[226:227], v208, 1.0 op_sel:[1,0,0]
	s_waitcnt lgkmcnt(0)
	v_cvt_scalef32_pk_f32_fp4 v[228:229], v208, 1.0 op_sel:[0,1,0]
	v_pk_fma_f32 v[114:115], v[224:225], v[118:119], v[114:115] op_sel_hi:[1,0,1]
	v_cvt_scalef32_pk_f32_fp4 v[230:231], v208, 1.0 op_sel:[1,1,0]
	v_pk_fma_f32 v[110:111], v[226:227], v[118:119], v[110:111] op_sel_hi:[1,0,1]
	v_cvt_scalef32_pk_f32_fp4 v[224:225], v209, 1.0
	v_pk_fma_f32 v[102:103], v[228:229], v[118:119], v[102:103] op_sel_hi:[1,0,1]
	v_cvt_scalef32_pk_f32_fp4 v[226:227], v209, 1.0 op_sel:[1,0,0]
	v_pk_fma_f32 v[100:101], v[230:231], v[118:119], v[100:101] op_sel_hi:[1,0,1]
	v_cvt_scalef32_pk_f32_fp4 v[228:229], v209, 1.0 op_sel:[0,1,0]
	v_pk_fma_f32 v[54:55], v[224:225], v[118:119], v[54:55] op_sel_hi:[1,0,1]
	v_cvt_scalef32_pk_f32_fp4 v[230:231], v209, 1.0 op_sel:[1,1,0]
	v_pk_fma_f32 v[58:59], v[226:227], v[118:119], v[58:59] op_sel_hi:[1,0,1]
	v_cvt_scalef32_pk_f32_fp4 v[224:225], v210, 1.0
	v_pk_fma_f32 v[52:53], v[228:229], v[118:119], v[52:53] op_sel_hi:[1,0,1]
	v_cvt_scalef32_pk_f32_fp4 v[226:227], v210, 1.0 op_sel:[1,0,0]
	v_pk_fma_f32 v[48:49], v[230:231], v[118:119], v[48:49] op_sel_hi:[1,0,1]
	v_cvt_scalef32_pk_f32_fp4 v[228:229], v210, 1.0 op_sel:[0,1,0]
	v_pk_fma_f32 v[108:109], v[224:225], v[118:119], v[108:109] op_sel_hi:[1,0,1]
	v_cvt_scalef32_pk_f32_fp4 v[230:231], v210, 1.0 op_sel:[1,1,0]
	v_pk_fma_f32 v[106:107], v[226:227], v[118:119], v[106:107] op_sel_hi:[1,0,1]
	v_cvt_scalef32_pk_f32_fp4 v[224:225], v211, 1.0
	v_pk_fma_f32 v[98:99], v[228:229], v[118:119], v[98:99] op_sel_hi:[1,0,1]
	v_cvt_scalef32_pk_f32_fp4 v[226:227], v211, 1.0 op_sel:[1,0,0]
	v_pk_fma_f32 v[56:57], v[230:231], v[118:119], v[56:57] op_sel_hi:[1,0,1]
	v_cvt_scalef32_pk_f32_fp4 v[228:229], v211, 1.0 op_sel:[0,1,0]
	v_pk_fma_f32 v[50:51], v[224:225], v[118:119], v[50:51] op_sel_hi:[1,0,1]
	v_cvt_scalef32_pk_f32_fp4 v[230:231], v211, 1.0 op_sel:[1,1,0]
	v_pk_fma_f32 v[116:117], v[226:227], v[118:119], v[116:117] op_sel_hi:[1,0,1]
	v_pk_fma_f32 v[112:113], v[228:229], v[118:119], v[112:113] op_sel_hi:[1,0,1]
	v_pk_fma_f32 v[104:105], v[230:231], v[118:119], v[104:105] op_sel_hi:[1,0,1]
	s_waitcnt vmcnt(10)
	v_cvt_scalef32_pk_f32_fp4 v[224:225], v212, 1.0
	v_cvt_scalef32_pk_f32_fp4 v[226:227], v212, 1.0 op_sel:[1,0,0]
	v_cvt_scalef32_pk_f32_fp4 v[228:229], v212, 1.0 op_sel:[0,1,0]
	v_pk_fma_f32 v[114:115], v[224:225], v[120:121], v[114:115] op_sel_hi:[1,0,1]
	v_cvt_scalef32_pk_f32_fp4 v[230:231], v212, 1.0 op_sel:[1,1,0]
	v_pk_fma_f32 v[110:111], v[226:227], v[120:121], v[110:111] op_sel_hi:[1,0,1]
	v_cvt_scalef32_pk_f32_fp4 v[224:225], v213, 1.0
	v_pk_fma_f32 v[102:103], v[228:229], v[120:121], v[102:103] op_sel_hi:[1,0,1]
	v_cvt_scalef32_pk_f32_fp4 v[226:227], v213, 1.0 op_sel:[1,0,0]
	v_pk_fma_f32 v[100:101], v[230:231], v[120:121], v[100:101] op_sel_hi:[1,0,1]
	v_cvt_scalef32_pk_f32_fp4 v[228:229], v213, 1.0 op_sel:[0,1,0]
	v_pk_fma_f32 v[54:55], v[224:225], v[120:121], v[54:55] op_sel_hi:[1,0,1]
	v_cvt_scalef32_pk_f32_fp4 v[230:231], v213, 1.0 op_sel:[1,1,0]
	v_pk_fma_f32 v[58:59], v[226:227], v[120:121], v[58:59] op_sel_hi:[1,0,1]
	v_cvt_scalef32_pk_f32_fp4 v[224:225], v214, 1.0
	v_pk_fma_f32 v[52:53], v[228:229], v[120:121], v[52:53] op_sel_hi:[1,0,1]
	v_cvt_scalef32_pk_f32_fp4 v[226:227], v214, 1.0 op_sel:[1,0,0]
	v_pk_fma_f32 v[48:49], v[230:231], v[120:121], v[48:49] op_sel_hi:[1,0,1]
	v_cvt_scalef32_pk_f32_fp4 v[228:229], v214, 1.0 op_sel:[0,1,0]
	v_pk_fma_f32 v[108:109], v[224:225], v[120:121], v[108:109] op_sel_hi:[1,0,1]
	v_cvt_scalef32_pk_f32_fp4 v[230:231], v214, 1.0 op_sel:[1,1,0]
	v_pk_fma_f32 v[106:107], v[226:227], v[120:121], v[106:107] op_sel_hi:[1,0,1]
	v_cvt_scalef32_pk_f32_fp4 v[224:225], v215, 1.0
	v_pk_fma_f32 v[98:99], v[228:229], v[120:121], v[98:99] op_sel_hi:[1,0,1]
	v_cvt_scalef32_pk_f32_fp4 v[226:227], v215, 1.0 op_sel:[1,0,0]
	v_pk_fma_f32 v[56:57], v[230:231], v[120:121], v[56:57] op_sel_hi:[1,0,1]
	v_cvt_scalef32_pk_f32_fp4 v[228:229], v215, 1.0 op_sel:[0,1,0]
	v_pk_fma_f32 v[50:51], v[224:225], v[120:121], v[50:51] op_sel_hi:[1,0,1]
	v_cvt_scalef32_pk_f32_fp4 v[230:231], v215, 1.0 op_sel:[1,1,0]
	v_pk_fma_f32 v[116:117], v[226:227], v[120:121], v[116:117] op_sel_hi:[1,0,1]
	v_pk_fma_f32 v[112:113], v[228:229], v[120:121], v[112:113] op_sel_hi:[1,0,1]
	v_pk_fma_f32 v[104:105], v[230:231], v[120:121], v[104:105] op_sel_hi:[1,0,1]
	s_waitcnt vmcnt(9)
	v_cvt_scalef32_pk_f32_fp4 v[224:225], v216, 1.0
	v_cvt_scalef32_pk_f32_fp4 v[226:227], v216, 1.0 op_sel:[1,0,0]
	v_cvt_scalef32_pk_f32_fp4 v[228:229], v216, 1.0 op_sel:[0,1,0]
	v_pk_fma_f32 v[114:115], v[224:225], v[122:123], v[114:115] op_sel_hi:[1,0,1]
	v_cvt_scalef32_pk_f32_fp4 v[230:231], v216, 1.0 op_sel:[1,1,0]
	v_pk_fma_f32 v[110:111], v[226:227], v[122:123], v[110:111] op_sel_hi:[1,0,1]
	v_cvt_scalef32_pk_f32_fp4 v[224:225], v217, 1.0
	v_pk_fma_f32 v[102:103], v[228:229], v[122:123], v[102:103] op_sel_hi:[1,0,1]
	v_cvt_scalef32_pk_f32_fp4 v[226:227], v217, 1.0 op_sel:[1,0,0]
	v_pk_fma_f32 v[100:101], v[230:231], v[122:123], v[100:101] op_sel_hi:[1,0,1]
	v_cvt_scalef32_pk_f32_fp4 v[228:229], v217, 1.0 op_sel:[0,1,0]
	v_pk_fma_f32 v[54:55], v[224:225], v[122:123], v[54:55] op_sel_hi:[1,0,1]
	v_cvt_scalef32_pk_f32_fp4 v[230:231], v217, 1.0 op_sel:[1,1,0]
	v_pk_fma_f32 v[58:59], v[226:227], v[122:123], v[58:59] op_sel_hi:[1,0,1]
	v_cvt_scalef32_pk_f32_fp4 v[224:225], v218, 1.0
	v_pk_fma_f32 v[52:53], v[228:229], v[122:123], v[52:53] op_sel_hi:[1,0,1]
	v_cvt_scalef32_pk_f32_fp4 v[226:227], v218, 1.0 op_sel:[1,0,0]
	v_pk_fma_f32 v[48:49], v[230:231], v[122:123], v[48:49] op_sel_hi:[1,0,1]
	v_cvt_scalef32_pk_f32_fp4 v[228:229], v218, 1.0 op_sel:[0,1,0]
	v_pk_fma_f32 v[108:109], v[224:225], v[122:123], v[108:109] op_sel_hi:[1,0,1]
	v_cvt_scalef32_pk_f32_fp4 v[230:231], v218, 1.0 op_sel:[1,1,0]
	v_pk_fma_f32 v[106:107], v[226:227], v[122:123], v[106:107] op_sel_hi:[1,0,1]
	v_cvt_scalef32_pk_f32_fp4 v[224:225], v219, 1.0
	v_pk_fma_f32 v[98:99], v[228:229], v[122:123], v[98:99] op_sel_hi:[1,0,1]
	v_cvt_scalef32_pk_f32_fp4 v[226:227], v219, 1.0 op_sel:[1,0,0]
	v_pk_fma_f32 v[56:57], v[230:231], v[122:123], v[56:57] op_sel_hi:[1,0,1]
	v_cvt_scalef32_pk_f32_fp4 v[228:229], v219, 1.0 op_sel:[0,1,0]
	v_pk_fma_f32 v[50:51], v[224:225], v[122:123], v[50:51] op_sel_hi:[1,0,1]
	v_cvt_scalef32_pk_f32_fp4 v[230:231], v219, 1.0 op_sel:[1,1,0]
	v_pk_fma_f32 v[116:117], v[226:227], v[122:123], v[116:117] op_sel_hi:[1,0,1]
	v_pk_fma_f32 v[112:113], v[228:229], v[122:123], v[112:113] op_sel_hi:[1,0,1]
	v_pk_fma_f32 v[104:105], v[230:231], v[122:123], v[104:105] op_sel_hi:[1,0,1]
	s_waitcnt vmcnt(8)
	v_cvt_scalef32_pk_f32_fp4 v[224:225], v220, 1.0
	v_cvt_scalef32_pk_f32_fp4 v[226:227], v220, 1.0 op_sel:[1,0,0]
	v_cvt_scalef32_pk_f32_fp4 v[228:229], v220, 1.0 op_sel:[0,1,0]
	v_pk_fma_f32 v[114:115], v[224:225], v[124:125], v[114:115] op_sel_hi:[1,0,1]
	v_cvt_scalef32_pk_f32_fp4 v[230:231], v220, 1.0 op_sel:[1,1,0]
	v_pk_fma_f32 v[110:111], v[226:227], v[124:125], v[110:111] op_sel_hi:[1,0,1]
	v_cvt_scalef32_pk_f32_fp4 v[224:225], v221, 1.0
	v_pk_fma_f32 v[102:103], v[228:229], v[124:125], v[102:103] op_sel_hi:[1,0,1]
	v_cvt_scalef32_pk_f32_fp4 v[226:227], v221, 1.0 op_sel:[1,0,0]
	v_pk_fma_f32 v[100:101], v[230:231], v[124:125], v[100:101] op_sel_hi:[1,0,1]
	v_cvt_scalef32_pk_f32_fp4 v[228:229], v221, 1.0 op_sel:[0,1,0]
	v_pk_fma_f32 v[54:55], v[224:225], v[124:125], v[54:55] op_sel_hi:[1,0,1]
	v_cvt_scalef32_pk_f32_fp4 v[230:231], v221, 1.0 op_sel:[1,1,0]
	v_pk_fma_f32 v[58:59], v[226:227], v[124:125], v[58:59] op_sel_hi:[1,0,1]
	v_cvt_scalef32_pk_f32_fp4 v[224:225], v222, 1.0
	v_pk_fma_f32 v[52:53], v[228:229], v[124:125], v[52:53] op_sel_hi:[1,0,1]
	v_cvt_scalef32_pk_f32_fp4 v[226:227], v222, 1.0 op_sel:[1,0,0]
	v_pk_fma_f32 v[48:49], v[230:231], v[124:125], v[48:49] op_sel_hi:[1,0,1]
	v_cvt_scalef32_pk_f32_fp4 v[228:229], v222, 1.0 op_sel:[0,1,0]
	v_pk_fma_f32 v[108:109], v[224:225], v[124:125], v[108:109] op_sel_hi:[1,0,1]
	v_cvt_scalef32_pk_f32_fp4 v[230:231], v222, 1.0 op_sel:[1,1,0]
	v_pk_fma_f32 v[106:107], v[226:227], v[124:125], v[106:107] op_sel_hi:[1,0,1]
	v_cvt_scalef32_pk_f32_fp4 v[224:225], v223, 1.0
	v_pk_fma_f32 v[98:99], v[228:229], v[124:125], v[98:99] op_sel_hi:[1,0,1]
	v_cvt_scalef32_pk_f32_fp4 v[226:227], v223, 1.0 op_sel:[1,0,0]
	v_pk_fma_f32 v[56:57], v[230:231], v[124:125], v[56:57] op_sel_hi:[1,0,1]
	v_cvt_scalef32_pk_f32_fp4 v[228:229], v223, 1.0 op_sel:[0,1,0]
	v_pk_fma_f32 v[50:51], v[224:225], v[124:125], v[50:51] op_sel_hi:[1,0,1]
	v_cvt_scalef32_pk_f32_fp4 v[230:231], v223, 1.0 op_sel:[1,1,0]
	v_pk_fma_f32 v[116:117], v[226:227], v[124:125], v[116:117] op_sel_hi:[1,0,1]
	v_pk_fma_f32 v[112:113], v[228:229], v[124:125], v[112:113] op_sel_hi:[1,0,1]
	v_pk_fma_f32 v[104:105], v[230:231], v[124:125], v[104:105] op_sel_hi:[1,0,1]
	s_add_u32 s22, s22, 2
	s_cmp_lt_u32 s22, 14
	s_cbranch_scc1 .Lxg_loop_p6
	s_waitcnt lgkmcnt(0)
	v_lshl_add_u32 v250, v240, 9, v241
	v_lshl_add_u32 v251, v242, 9, v241
	v_lshl_add_u32 v252, v246, 9, v241
	v_lshl_add_u32 v253, v248, 9, v241
	global_load_dwordx4 v[192:195], v250, s[98:99]
	global_load_dwordx4 v[196:199], v251, s[98:99]
	global_load_dwordx4 v[200:203], v252, s[98:99]
	global_load_dwordx4 v[204:207], v253, s[98:99]
	global_load_dwordx4 v[208:211], v250, s[100:101]
	global_load_dwordx4 v[212:215], v251, s[100:101]
	global_load_dwordx4 v[216:219], v252, s[100:101]
	global_load_dwordx4 v[220:223], v253, s[100:101]
	s_movk_i32 s23, 0xc0
	v_lshl_add_u32 v130, v140, 2, s23
	ds_bpermute_b32 v156, v130, v150
	ds_bpermute_b32 v157, v130, v152
	s_waitcnt vmcnt(14)
	v_cvt_scalef32_pk_f32_fp4 v[224:225], v160, 1.0
	v_cvt_scalef32_pk_f32_fp4 v[226:227], v164, 1.0
	v_cvt_scalef32_pk_f32_fp4 v[228:229], v160, 1.0 op_sel:[1,0,0]
	v_cvt_scalef32_pk_f32_fp4 v[230:231], v164, 1.0 op_sel:[1,0,0]
	v_pk_fma_f32 v[232:233], v[24:25], v[224:225], 0 op_sel_hi:[1,1,0]
	v_pk_fma_f32 v[234:235], v[24:25], v[226:227], 0 op_sel_hi:[1,1,0]
	v_cvt_scalef32_pk_f32_fp4 v[224:225], v160, 1.0 op_sel:[0,1,0]
	v_cvt_scalef32_pk_f32_fp4 v[226:227], v164, 1.0 op_sel:[0,1,0]
	v_pk_fma_f32 v[232:233], v[26:27], v[228:229], v[232:233]
	v_pk_fma_f32 v[234:235], v[26:27], v[230:231], v[234:235]
	v_cvt_scalef32_pk_f32_fp4 v[228:229], v160, 1.0 op_sel:[1,1,0]
	v_cvt_scalef32_pk_f32_fp4 v[230:231], v164, 1.0 op_sel:[1,1,0]
	v_pk_fma_f32 v[232:233], v[12:13], v[224:225], v[232:233]
	v_pk_fma_f32 v[234:235], v[12:13], v[226:227], v[234:235]
	v_cvt_scalef32_pk_f32_fp4 v[224:225], v161, 1.0
	v_cvt_scalef32_pk_f32_fp4 v[226:227], v165, 1.0
	v_pk_fma_f32 v[232:233], v[14:15], v[228:229], v[232:233]
	v_pk_fma_f32 v[234:235], v[14:15], v[230:231], v[234:235]
	v_cvt_scalef32_pk_f32_fp4 v[228:229], v161, 1.0 op_sel:[1,0,0]
	v_cvt_scalef32_pk_f32_fp4 v[230:231], v165, 1.0 op_sel:[1,0,0]
	v_pk_fma_f32 v[232:233], v[4:5], v[224:225], v[232:233]
	v_pk_fma_f32 v[234:235], v[4:5], v[226:227], v[234:235]
	v_cvt_scalef32_pk_f32_fp4 v[224:225], v161, 1.0 op_sel:[0,1,0]
	v_cvt_scalef32_pk_f32_fp4 v[226:227], v165, 1.0 op_sel:[0,1,0]
	v_pk_fma_f32 v[232:233], v[6:7], v[228:229], v[232:233]
	v_pk_fma_f32 v[234:235], v[6:7], v[230:231], v[234:235]
	v_cvt_scalef32_pk_f32_fp4 v[228:229], v161, 1.0 op_sel:[1,1,0]
	v_cvt_scalef32_pk_f32_fp4 v[230:231], v165, 1.0 op_sel:[1,1,0]
	v_pk_fma_f32 v[232:233], v[0:1], v[224:225], v[232:233]
	v_pk_fma_f32 v[234:235], v[0:1], v[226:227], v[234:235]
	v_cvt_scalef32_pk_f32_fp4 v[224:225], v162, 1.0
	v_cvt_scalef32_pk_f32_fp4 v[226:227], v166, 1.0
	v_pk_fma_f32 v[232:233], v[2:3], v[228:229], v[232:233]
	v_pk_fma_f32 v[234:235], v[2:3], v[230:231], v[234:235]
	v_cvt_scalef32_pk_f32_fp4 v[228:229], v162, 1.0 op_sel:[1,0,0]
	v_cvt_scalef32_pk_f32_fp4 v[230:231], v166, 1.0 op_sel:[1,0,0]
	v_pk_fma_f32 v[232:233], v[28:29], v[224:225], v[232:233]
	v_pk_fma_f32 v[234:235], v[28:29], v[226:227], v[234:235]
	v_cvt_scalef32_pk_f32_fp4 v[224:225], v162, 1.0 op_sel:[0,1,0]
	v_cvt_scalef32_pk_f32_fp4 v[226:227], v166, 1.0 op_sel:[0,1,0]
	v_pk_fma_f32 v[232:233], v[30:31], v[228:229], v[232:233]
	v_pk_fma_f32 v[234:235], v[30:31], v[230:231], v[234:235]
	v_cvt_scalef32_pk_f32_fp4 v[228:229], v162, 1.0 op_sel:[1,1,0]
	v_cvt_scalef32_pk_f32_fp4 v[230:231], v166, 1.0 op_sel:[1,1,0]
	v_pk_fma_f32 v[232:233], v[16:17], v[224:225], v[232:233]
	v_pk_fma_f32 v[234:235], v[16:17], v[226:227], v[234:235]
	v_cvt_scalef32_pk_f32_fp4 v[224:225], v163, 1.0
	v_cvt_scalef32_pk_f32_fp4 v[226:227], v167, 1.0
	v_pk_fma_f32 v[232:233], v[18:19], v[228:229], v[232:233]
	v_pk_fma_f32 v[234:235], v[18:19], v[230:231], v[234:235]
	v_cvt_scalef32_pk_f32_fp4 v[228:229], v163, 1.0 op_sel:[1,0,0]
	v_cvt_scalef32_pk_f32_fp4 v[230:231], v167, 1.0 op_sel:[1,0,0]
	v_pk_fma_f32 v[232:233], v[8:9], v[224:225], v[232:233]
	v_pk_fma_f32 v[234:235], v[8:9], v[226:227], v[234:235]
	v_cvt_scalef32_pk_f32_fp4 v[224:225], v163, 1.0 op_sel:[0,1,0]
	v_cvt_scalef32_pk_f32_fp4 v[226:227], v167, 1.0 op_sel:[0,1,0]
	v_pk_fma_f32 v[232:233], v[10:11], v[228:229], v[232:233]
	v_pk_fma_f32 v[234:235], v[10:11], v[230:231], v[234:235]
	v_cvt_scalef32_pk_f32_fp4 v[228:229], v163, 1.0 op_sel:[1,1,0]
	v_cvt_scalef32_pk_f32_fp4 v[230:231], v167, 1.0 op_sel:[1,1,0]
	v_pk_fma_f32 v[232:233], v[20:21], v[224:225], v[232:233]
	v_pk_fma_f32 v[234:235], v[20:21], v[226:227], v[234:235]
	v_pk_fma_f32 v[232:233], v[22:23], v[228:229], v[232:233]
	v_pk_fma_f32 v[234:235], v[22:23], v[230:231], v[234:235]
	v_add_f32_e32 v32, v232, v233
	v_add_f32_e32 v33, v234, v235
	s_waitcnt vmcnt(12)
	v_cvt_scalef32_pk_f32_fp4 v[224:225], v168, 1.0
	v_cvt_scalef32_pk_f32_fp4 v[226:227], v172, 1.0
	v_cvt_scalef32_pk_f32_fp4 v[228:229], v168, 1.0 op_sel:[1,0,0]
	v_cvt_scalef32_pk_f32_fp4 v[230:231], v172, 1.0 op_sel:[1,0,0]
	v_pk_fma_f32 v[236:237], v[24:25], v[224:225], 0 op_sel_hi:[1,1,0]
	v_pk_fma_f32 v[238:239], v[24:25], v[226:227], 0 op_sel_hi:[1,1,0]
	v_cvt_scalef32_pk_f32_fp4 v[224:225], v168, 1.0 op_sel:[0,1,0]
	v_cvt_scalef32_pk_f32_fp4 v[226:227], v172, 1.0 op_sel:[0,1,0]
	v_pk_fma_f32 v[236:237], v[26:27], v[228:229], v[236:237]
	v_pk_fma_f32 v[238:239], v[26:27], v[230:231], v[238:239]
	v_cvt_scalef32_pk_f32_fp4 v[228:229], v168, 1.0 op_sel:[1,1,0]
	v_cvt_scalef32_pk_f32_fp4 v[230:231], v172, 1.0 op_sel:[1,1,0]
	v_pk_fma_f32 v[236:237], v[12:13], v[224:225], v[236:237]
	v_pk_fma_f32 v[238:239], v[12:13], v[226:227], v[238:239]
	v_cvt_scalef32_pk_f32_fp4 v[224:225], v169, 1.0
	v_cvt_scalef32_pk_f32_fp4 v[226:227], v173, 1.0
	v_pk_fma_f32 v[236:237], v[14:15], v[228:229], v[236:237]
	v_pk_fma_f32 v[238:239], v[14:15], v[230:231], v[238:239]
	v_cvt_scalef32_pk_f32_fp4 v[228:229], v169, 1.0 op_sel:[1,0,0]
	v_cvt_scalef32_pk_f32_fp4 v[230:231], v173, 1.0 op_sel:[1,0,0]
	v_pk_fma_f32 v[236:237], v[4:5], v[224:225], v[236:237]
	v_pk_fma_f32 v[238:239], v[4:5], v[226:227], v[238:239]
	v_cvt_scalef32_pk_f32_fp4 v[224:225], v169, 1.0 op_sel:[0,1,0]
	v_cvt_scalef32_pk_f32_fp4 v[226:227], v173, 1.0 op_sel:[0,1,0]
	v_pk_fma_f32 v[236:237], v[6:7], v[228:229], v[236:237]
	v_pk_fma_f32 v[238:239], v[6:7], v[230:231], v[238:239]
	v_cvt_scalef32_pk_f32_fp4 v[228:229], v169, 1.0 op_sel:[1,1,0]
	v_cvt_scalef32_pk_f32_fp4 v[230:231], v173, 1.0 op_sel:[1,1,0]
	v_pk_fma_f32 v[236:237], v[0:1], v[224:225], v[236:237]
	v_pk_fma_f32 v[238:239], v[0:1], v[226:227], v[238:239]
	v_cvt_scalef32_pk_f32_fp4 v[224:225], v170, 1.0
	v_cvt_scalef32_pk_f32_fp4 v[226:227], v174, 1.0
	v_pk_fma_f32 v[236:237], v[2:3], v[228:229], v[236:237]
	v_pk_fma_f32 v[238:239], v[2:3], v[230:231], v[238:239]
	v_cvt_scalef32_pk_f32_fp4 v[228:229], v170, 1.0 op_sel:[1,0,0]
	v_cvt_scalef32_pk_f32_fp4 v[230:231], v174, 1.0 op_sel:[1,0,0]
	v_pk_fma_f32 v[236:237], v[28:29], v[224:225], v[236:237]
	v_pk_fma_f32 v[238:239], v[28:29], v[226:227], v[238:239]
	v_cvt_scalef32_pk_f32_fp4 v[224:225], v170, 1.0 op_sel:[0,1,0]
	v_cvt_scalef32_pk_f32_fp4 v[226:227], v174, 1.0 op_sel:[0,1,0]
	v_pk_fma_f32 v[236:237], v[30:31], v[228:229], v[236:237]
	v_pk_fma_f32 v[238:239], v[30:31], v[230:231], v[238:239]
	v_cvt_scalef32_pk_f32_fp4 v[228:229], v170, 1.0 op_sel:[1,1,0]
	v_cvt_scalef32_pk_f32_fp4 v[230:231], v174, 1.0 op_sel:[1,1,0]
	v_pk_fma_f32 v[236:237], v[16:17], v[224:225], v[236:237]
	v_pk_fma_f32 v[238:239], v[16:17], v[226:227], v[238:239]
	v_cvt_scalef32_pk_f32_fp4 v[224:225], v171, 1.0
	v_cvt_scalef32_pk_f32_fp4 v[226:227], v175, 1.0
	v_pk_fma_f32 v[236:237], v[18:19], v[228:229], v[236:237]
	v_pk_fma_f32 v[238:239], v[18:19], v[230:231], v[238:239]
	v_cvt_scalef32_pk_f32_fp4 v[228:229], v171, 1.0 op_sel:[1,0,0]
	v_cvt_scalef32_pk_f32_fp4 v[230:231], v175, 1.0 op_sel:[1,0,0]
	v_pk_fma_f32 v[236:237], v[8:9], v[224:225], v[236:237]
	v_pk_fma_f32 v[238:239], v[8:9], v[226:227], v[238:239]
	v_cvt_scalef32_pk_f32_fp4 v[224:225], v171, 1.0 op_sel:[0,1,0]
	v_cvt_scalef32_pk_f32_fp4 v[226:227], v175, 1.0 op_sel:[0,1,0]
	v_pk_fma_f32 v[236:237], v[10:11], v[228:229], v[236:237]
	v_pk_fma_f32 v[238:239], v[10:11], v[230:231], v[238:239]
	v_cvt_scalef32_pk_f32_fp4 v[228:229], v171, 1.0 op_sel:[1,1,0]
	v_cvt_scalef32_pk_f32_fp4 v[230:231], v175, 1.0 op_sel:[1,1,0]
	v_pk_fma_f32 v[236:237], v[20:21], v[224:225], v[236:237]
	v_pk_fma_f32 v[238:239], v[20:21], v[226:227], v[238:239]
	v_pk_fma_f32 v[236:237], v[22:23], v[228:229], v[236:237]
	v_pk_fma_f32 v[238:239], v[22:23], v[230:231], v[238:239]
	v_add_f32_e32 v34, v236, v237
	v_add_f32_e32 v35, v238, v239
	v_cndmask_b32_e32 v36, v34, v32, vcc
	v_cndmask_b32_e32 v37, v32, v34, vcc
	v_cndmask_b32_e32 v38, v35, v33, vcc
	v_cndmask_b32_e32 v39, v33, v35, vcc
	ds_bpermute_b32 v37, v61, v37
	ds_bpermute_b32 v39, v61, v39
	s_waitcnt lgkmcnt(0)
	v_add_f32_e32 v36, v36, v37
	v_add_f32_e32 v38, v38, v39
	v_cndmask_b32_e64 v40, v38, v36, s[4:5]
	v_cndmask_b32_e64 v41, v36, v38, s[4:5]
	s_nop 1
	v_add_f32_dpp v40, v41, v40 row_ror:8 row_mask:0xf bank_mask:0xf
	s_nop 1
	v_add_f32_dpp v40, v40, v40 quad_perm:[1,0,3,2] row_mask:0xf bank_mask:0xf
	s_nop 1
	v_add_f32_dpp v40, v40, v40 quad_perm:[2,3,0,1] row_mask:0xf bank_mask:0xf
	s_nop 1
	v_add_f32_dpp v40, v40, v40 row_half_mirror row_mask:0xf bank_mask:0xf
	v_mul_f32_e32 v42, v40, v156
	v_fma_f32 v43, |v42|, s19, 1.0
	v_rcp_f32_e32 v43, v43
	v_cmp_gt_f32_e64 s[8:9], 0, v42
	v_mul_f32_e32 v45, v42, v42
	v_fmamk_f32 v44, v43, 0x3f07dc22, v145
	v_fmaak_f32 v44, v43, v44, 0x3f35f0e3
	v_fmaak_f32 v44, v43, v44, 0xbe11a98e
	v_fmaak_f32 v44, v43, v44, 0x3e027906
	v_mul_f32_e32 v45, 0xbf38aa3b, v45
	v_exp_f32_e32 v45, v45
	v_mul_f32_e32 v43, v43, v44
	v_mul_f32_e32 v43, v45, v43
	v_mul_f32_e32 v44, v42, v43
	v_fma_f32 v42, -v42, v43, v42
	v_cndmask_b32_e64 v42, v42, v44, s[8:9]
	v_mul_f32_e32 v158, v42, v157
	ds_bpermute_b32 v118, v141, v158
	ds_bpermute_b32 v120, v142, v158
	ds_bpermute_b32 v122, v143, v158
	ds_bpermute_b32 v124, v144, v158
	s_waitcnt vmcnt(11)
	v_cvt_scalef32_pk_f32_fp4 v[224:225], v176, 1.0
	v_cvt_scalef32_pk_f32_fp4 v[226:227], v176, 1.0 op_sel:[1,0,0]
	s_waitcnt lgkmcnt(0)
	v_cvt_scalef32_pk_f32_fp4 v[228:229], v176, 1.0 op_sel:[0,1,0]
	v_pk_fma_f32 v[114:115], v[224:225], v[118:119], v[114:115] op_sel_hi:[1,0,1]
	v_cvt_scalef32_pk_f32_fp4 v[230:231], v176, 1.0 op_sel:[1,1,0]
	v_pk_fma_f32 v[110:111], v[226:227], v[118:119], v[110:111] op_sel_hi:[1,0,1]
	v_cvt_scalef32_pk_f32_fp4 v[224:225], v177, 1.0
	v_pk_fma_f32 v[102:103], v[228:229], v[118:119], v[102:103] op_sel_hi:[1,0,1]
	v_cvt_scalef32_pk_f32_fp4 v[226:227], v177, 1.0 op_sel:[1,0,0]
	v_pk_fma_f32 v[100:101], v[230:231], v[118:119], v[100:101] op_sel_hi:[1,0,1]
	v_cvt_scalef32_pk_f32_fp4 v[228:229], v177, 1.0 op_sel:[0,1,0]
	v_pk_fma_f32 v[54:55], v[224:225], v[118:119], v[54:55] op_sel_hi:[1,0,1]
	v_cvt_scalef32_pk_f32_fp4 v[230:231], v177, 1.0 op_sel:[1,1,0]
	v_pk_fma_f32 v[58:59], v[226:227], v[118:119], v[58:59] op_sel_hi:[1,0,1]
	v_cvt_scalef32_pk_f32_fp4 v[224:225], v178, 1.0
	v_pk_fma_f32 v[52:53], v[228:229], v[118:119], v[52:53] op_sel_hi:[1,0,1]
	v_cvt_scalef32_pk_f32_fp4 v[226:227], v178, 1.0 op_sel:[1,0,0]
	v_pk_fma_f32 v[48:49], v[230:231], v[118:119], v[48:49] op_sel_hi:[1,0,1]
	v_cvt_scalef32_pk_f32_fp4 v[228:229], v178, 1.0 op_sel:[0,1,0]
	v_pk_fma_f32 v[108:109], v[224:225], v[118:119], v[108:109] op_sel_hi:[1,0,1]
	v_cvt_scalef32_pk_f32_fp4 v[230:231], v178, 1.0 op_sel:[1,1,0]
	v_pk_fma_f32 v[106:107], v[226:227], v[118:119], v[106:107] op_sel_hi:[1,0,1]
	v_cvt_scalef32_pk_f32_fp4 v[224:225], v179, 1.0
	v_pk_fma_f32 v[98:99], v[228:229], v[118:119], v[98:99] op_sel_hi:[1,0,1]
	v_cvt_scalef32_pk_f32_fp4 v[226:227], v179, 1.0 op_sel:[1,0,0]
	v_pk_fma_f32 v[56:57], v[230:231], v[118:119], v[56:57] op_sel_hi:[1,0,1]
	v_cvt_scalef32_pk_f32_fp4 v[228:229], v179, 1.0 op_sel:[0,1,0]
	v_pk_fma_f32 v[50:51], v[224:225], v[118:119], v[50:51] op_sel_hi:[1,0,1]
	v_cvt_scalef32_pk_f32_fp4 v[230:231], v179, 1.0 op_sel:[1,1,0]
	v_pk_fma_f32 v[116:117], v[226:227], v[118:119], v[116:117] op_sel_hi:[1,0,1]
	v_pk_fma_f32 v[112:113], v[228:229], v[118:119], v[112:113] op_sel_hi:[1,0,1]
	v_pk_fma_f32 v[104:105], v[230:231], v[118:119], v[104:105] op_sel_hi:[1,0,1]
	s_waitcnt vmcnt(10)
	v_cvt_scalef32_pk_f32_fp4 v[224:225], v180, 1.0
	v_cvt_scalef32_pk_f32_fp4 v[226:227], v180, 1.0 op_sel:[1,0,0]
	v_cvt_scalef32_pk_f32_fp4 v[228:229], v180, 1.0 op_sel:[0,1,0]
	v_pk_fma_f32 v[114:115], v[224:225], v[120:121], v[114:115] op_sel_hi:[1,0,1]
	v_cvt_scalef32_pk_f32_fp4 v[230:231], v180, 1.0 op_sel:[1,1,0]
	v_pk_fma_f32 v[110:111], v[226:227], v[120:121], v[110:111] op_sel_hi:[1,0,1]
	v_cvt_scalef32_pk_f32_fp4 v[224:225], v181, 1.0
	v_pk_fma_f32 v[102:103], v[228:229], v[120:121], v[102:103] op_sel_hi:[1,0,1]
	v_cvt_scalef32_pk_f32_fp4 v[226:227], v181, 1.0 op_sel:[1,0,0]
	v_pk_fma_f32 v[100:101], v[230:231], v[120:121], v[100:101] op_sel_hi:[1,0,1]
	v_cvt_scalef32_pk_f32_fp4 v[228:229], v181, 1.0 op_sel:[0,1,0]
	v_pk_fma_f32 v[54:55], v[224:225], v[120:121], v[54:55] op_sel_hi:[1,0,1]
	v_cvt_scalef32_pk_f32_fp4 v[230:231], v181, 1.0 op_sel:[1,1,0]
	v_pk_fma_f32 v[58:59], v[226:227], v[120:121], v[58:59] op_sel_hi:[1,0,1]
	v_cvt_scalef32_pk_f32_fp4 v[224:225], v182, 1.0
	v_pk_fma_f32 v[52:53], v[228:229], v[120:121], v[52:53] op_sel_hi:[1,0,1]
	v_cvt_scalef32_pk_f32_fp4 v[226:227], v182, 1.0 op_sel:[1,0,0]
	v_pk_fma_f32 v[48:49], v[230:231], v[120:121], v[48:49] op_sel_hi:[1,0,1]
	v_cvt_scalef32_pk_f32_fp4 v[228:229], v182, 1.0 op_sel:[0,1,0]
	v_pk_fma_f32 v[108:109], v[224:225], v[120:121], v[108:109] op_sel_hi:[1,0,1]
	v_cvt_scalef32_pk_f32_fp4 v[230:231], v182, 1.0 op_sel:[1,1,0]
	v_pk_fma_f32 v[106:107], v[226:227], v[120:121], v[106:107] op_sel_hi:[1,0,1]
	v_cvt_scalef32_pk_f32_fp4 v[224:225], v183, 1.0
	v_pk_fma_f32 v[98:99], v[228:229], v[120:121], v[98:99] op_sel_hi:[1,0,1]
	v_cvt_scalef32_pk_f32_fp4 v[226:227], v183, 1.0 op_sel:[1,0,0]
	v_pk_fma_f32 v[56:57], v[230:231], v[120:121], v[56:57] op_sel_hi:[1,0,1]
	v_cvt_scalef32_pk_f32_fp4 v[228:229], v183, 1.0 op_sel:[0,1,0]
	v_pk_fma_f32 v[50:51], v[224:225], v[120:121], v[50:51] op_sel_hi:[1,0,1]
	v_cvt_scalef32_pk_f32_fp4 v[230:231], v183, 1.0 op_sel:[1,1,0]
	v_pk_fma_f32 v[116:117], v[226:227], v[120:121], v[116:117] op_sel_hi:[1,0,1]
	v_pk_fma_f32 v[112:113], v[228:229], v[120:121], v[112:113] op_sel_hi:[1,0,1]
	v_pk_fma_f32 v[104:105], v[230:231], v[120:121], v[104:105] op_sel_hi:[1,0,1]
	s_waitcnt vmcnt(9)
	v_cvt_scalef32_pk_f32_fp4 v[224:225], v184, 1.0
	v_cvt_scalef32_pk_f32_fp4 v[226:227], v184, 1.0 op_sel:[1,0,0]
	v_cvt_scalef32_pk_f32_fp4 v[228:229], v184, 1.0 op_sel:[0,1,0]
	v_pk_fma_f32 v[114:115], v[224:225], v[122:123], v[114:115] op_sel_hi:[1,0,1]
	v_cvt_scalef32_pk_f32_fp4 v[230:231], v184, 1.0 op_sel:[1,1,0]
	v_pk_fma_f32 v[110:111], v[226:227], v[122:123], v[110:111] op_sel_hi:[1,0,1]
	v_cvt_scalef32_pk_f32_fp4 v[224:225], v185, 1.0
	v_pk_fma_f32 v[102:103], v[228:229], v[122:123], v[102:103] op_sel_hi:[1,0,1]
	v_cvt_scalef32_pk_f32_fp4 v[226:227], v185, 1.0 op_sel:[1,0,0]
	v_pk_fma_f32 v[100:101], v[230:231], v[122:123], v[100:101] op_sel_hi:[1,0,1]
	v_cvt_scalef32_pk_f32_fp4 v[228:229], v185, 1.0 op_sel:[0,1,0]
	v_pk_fma_f32 v[54:55], v[224:225], v[122:123], v[54:55] op_sel_hi:[1,0,1]
	v_cvt_scalef32_pk_f32_fp4 v[230:231], v185, 1.0 op_sel:[1,1,0]
	v_pk_fma_f32 v[58:59], v[226:227], v[122:123], v[58:59] op_sel_hi:[1,0,1]
	v_cvt_scalef32_pk_f32_fp4 v[224:225], v186, 1.0
	v_pk_fma_f32 v[52:53], v[228:229], v[122:123], v[52:53] op_sel_hi:[1,0,1]
	v_cvt_scalef32_pk_f32_fp4 v[226:227], v186, 1.0 op_sel:[1,0,0]
	v_pk_fma_f32 v[48:49], v[230:231], v[122:123], v[48:49] op_sel_hi:[1,0,1]
	v_cvt_scalef32_pk_f32_fp4 v[228:229], v186, 1.0 op_sel:[0,1,0]
	v_pk_fma_f32 v[108:109], v[224:225], v[122:123], v[108:109] op_sel_hi:[1,0,1]
	v_cvt_scalef32_pk_f32_fp4 v[230:231], v186, 1.0 op_sel:[1,1,0]
	v_pk_fma_f32 v[106:107], v[226:227], v[122:123], v[106:107] op_sel_hi:[1,0,1]
	v_cvt_scalef32_pk_f32_fp4 v[224:225], v187, 1.0
	v_pk_fma_f32 v[98:99], v[228:229], v[122:123], v[98:99] op_sel_hi:[1,0,1]
	v_cvt_scalef32_pk_f32_fp4 v[226:227], v187, 1.0 op_sel:[1,0,0]
	v_pk_fma_f32 v[56:57], v[230:231], v[122:123], v[56:57] op_sel_hi:[1,0,1]
	v_cvt_scalef32_pk_f32_fp4 v[228:229], v187, 1.0 op_sel:[0,1,0]
	v_pk_fma_f32 v[50:51], v[224:225], v[122:123], v[50:51] op_sel_hi:[1,0,1]
	v_cvt_scalef32_pk_f32_fp4 v[230:231], v187, 1.0 op_sel:[1,1,0]
	v_pk_fma_f32 v[116:117], v[226:227], v[122:123], v[116:117] op_sel_hi:[1,0,1]
	v_pk_fma_f32 v[112:113], v[228:229], v[122:123], v[112:113] op_sel_hi:[1,0,1]
	v_pk_fma_f32 v[104:105], v[230:231], v[122:123], v[104:105] op_sel_hi:[1,0,1]
	s_waitcnt vmcnt(8)
	v_cvt_scalef32_pk_f32_fp4 v[224:225], v188, 1.0
	v_cvt_scalef32_pk_f32_fp4 v[226:227], v188, 1.0 op_sel:[1,0,0]
	v_cvt_scalef32_pk_f32_fp4 v[228:229], v188, 1.0 op_sel:[0,1,0]
	v_pk_fma_f32 v[114:115], v[224:225], v[124:125], v[114:115] op_sel_hi:[1,0,1]
	v_cvt_scalef32_pk_f32_fp4 v[230:231], v188, 1.0 op_sel:[1,1,0]
	v_pk_fma_f32 v[110:111], v[226:227], v[124:125], v[110:111] op_sel_hi:[1,0,1]
	v_cvt_scalef32_pk_f32_fp4 v[224:225], v189, 1.0
	v_pk_fma_f32 v[102:103], v[228:229], v[124:125], v[102:103] op_sel_hi:[1,0,1]
	v_cvt_scalef32_pk_f32_fp4 v[226:227], v189, 1.0 op_sel:[1,0,0]
	v_pk_fma_f32 v[100:101], v[230:231], v[124:125], v[100:101] op_sel_hi:[1,0,1]
	v_cvt_scalef32_pk_f32_fp4 v[228:229], v189, 1.0 op_sel:[0,1,0]
	v_pk_fma_f32 v[54:55], v[224:225], v[124:125], v[54:55] op_sel_hi:[1,0,1]
	v_cvt_scalef32_pk_f32_fp4 v[230:231], v189, 1.0 op_sel:[1,1,0]
	v_pk_fma_f32 v[58:59], v[226:227], v[124:125], v[58:59] op_sel_hi:[1,0,1]
	v_cvt_scalef32_pk_f32_fp4 v[224:225], v190, 1.0
	v_pk_fma_f32 v[52:53], v[228:229], v[124:125], v[52:53] op_sel_hi:[1,0,1]
	v_cvt_scalef32_pk_f32_fp4 v[226:227], v190, 1.0 op_sel:[1,0,0]
	v_pk_fma_f32 v[48:49], v[230:231], v[124:125], v[48:49] op_sel_hi:[1,0,1]
	v_cvt_scalef32_pk_f32_fp4 v[228:229], v190, 1.0 op_sel:[0,1,0]
	v_pk_fma_f32 v[108:109], v[224:225], v[124:125], v[108:109] op_sel_hi:[1,0,1]
	v_cvt_scalef32_pk_f32_fp4 v[230:231], v190, 1.0 op_sel:[1,1,0]
	v_pk_fma_f32 v[106:107], v[226:227], v[124:125], v[106:107] op_sel_hi:[1,0,1]
	v_cvt_scalef32_pk_f32_fp4 v[224:225], v191, 1.0
	v_pk_fma_f32 v[98:99], v[228:229], v[124:125], v[98:99] op_sel_hi:[1,0,1]
	v_cvt_scalef32_pk_f32_fp4 v[226:227], v191, 1.0 op_sel:[1,0,0]
	v_pk_fma_f32 v[56:57], v[230:231], v[124:125], v[56:57] op_sel_hi:[1,0,1]
	v_cvt_scalef32_pk_f32_fp4 v[228:229], v191, 1.0 op_sel:[0,1,0]
	v_pk_fma_f32 v[50:51], v[224:225], v[124:125], v[50:51] op_sel_hi:[1,0,1]
	v_cvt_scalef32_pk_f32_fp4 v[230:231], v191, 1.0 op_sel:[1,1,0]
	v_pk_fma_f32 v[116:117], v[226:227], v[124:125], v[116:117] op_sel_hi:[1,0,1]
	v_pk_fma_f32 v[112:113], v[228:229], v[124:125], v[112:113] op_sel_hi:[1,0,1]
	v_pk_fma_f32 v[104:105], v[230:231], v[124:125], v[104:105] op_sel_hi:[1,0,1]
	s_waitcnt lgkmcnt(0)
	s_movk_i32 s23, 0xe0
	v_lshl_add_u32 v130, v140, 2, s23
	ds_bpermute_b32 v156, v130, v150
	ds_bpermute_b32 v157, v130, v152
	s_waitcnt vmcnt(6)
	v_cvt_scalef32_pk_f32_fp4 v[224:225], v192, 1.0
	v_cvt_scalef32_pk_f32_fp4 v[226:227], v196, 1.0
	v_cvt_scalef32_pk_f32_fp4 v[228:229], v192, 1.0 op_sel:[1,0,0]
	v_cvt_scalef32_pk_f32_fp4 v[230:231], v196, 1.0 op_sel:[1,0,0]
	v_pk_fma_f32 v[232:233], v[24:25], v[224:225], 0 op_sel_hi:[1,1,0]
	v_pk_fma_f32 v[234:235], v[24:25], v[226:227], 0 op_sel_hi:[1,1,0]
	v_cvt_scalef32_pk_f32_fp4 v[224:225], v192, 1.0 op_sel:[0,1,0]
	v_cvt_scalef32_pk_f32_fp4 v[226:227], v196, 1.0 op_sel:[0,1,0]
	v_pk_fma_f32 v[232:233], v[26:27], v[228:229], v[232:233]
	v_pk_fma_f32 v[234:235], v[26:27], v[230:231], v[234:235]
	v_cvt_scalef32_pk_f32_fp4 v[228:229], v192, 1.0 op_sel:[1,1,0]
	v_cvt_scalef32_pk_f32_fp4 v[230:231], v196, 1.0 op_sel:[1,1,0]
	v_pk_fma_f32 v[232:233], v[12:13], v[224:225], v[232:233]
	v_pk_fma_f32 v[234:235], v[12:13], v[226:227], v[234:235]
	v_cvt_scalef32_pk_f32_fp4 v[224:225], v193, 1.0
	v_cvt_scalef32_pk_f32_fp4 v[226:227], v197, 1.0
	v_pk_fma_f32 v[232:233], v[14:15], v[228:229], v[232:233]
	v_pk_fma_f32 v[234:235], v[14:15], v[230:231], v[234:235]
	v_cvt_scalef32_pk_f32_fp4 v[228:229], v193, 1.0 op_sel:[1,0,0]
	v_cvt_scalef32_pk_f32_fp4 v[230:231], v197, 1.0 op_sel:[1,0,0]
	v_pk_fma_f32 v[232:233], v[4:5], v[224:225], v[232:233]
	v_pk_fma_f32 v[234:235], v[4:5], v[226:227], v[234:235]
	v_cvt_scalef32_pk_f32_fp4 v[224:225], v193, 1.0 op_sel:[0,1,0]
	v_cvt_scalef32_pk_f32_fp4 v[226:227], v197, 1.0 op_sel:[0,1,0]
	v_pk_fma_f32 v[232:233], v[6:7], v[228:229], v[232:233]
	v_pk_fma_f32 v[234:235], v[6:7], v[230:231], v[234:235]
	v_cvt_scalef32_pk_f32_fp4 v[228:229], v193, 1.0 op_sel:[1,1,0]
	v_cvt_scalef32_pk_f32_fp4 v[230:231], v197, 1.0 op_sel:[1,1,0]
	v_pk_fma_f32 v[232:233], v[0:1], v[224:225], v[232:233]
	v_pk_fma_f32 v[234:235], v[0:1], v[226:227], v[234:235]
	v_cvt_scalef32_pk_f32_fp4 v[224:225], v194, 1.0
	v_cvt_scalef32_pk_f32_fp4 v[226:227], v198, 1.0
	v_pk_fma_f32 v[232:233], v[2:3], v[228:229], v[232:233]
	v_pk_fma_f32 v[234:235], v[2:3], v[230:231], v[234:235]
	v_cvt_scalef32_pk_f32_fp4 v[228:229], v194, 1.0 op_sel:[1,0,0]
	v_cvt_scalef32_pk_f32_fp4 v[230:231], v198, 1.0 op_sel:[1,0,0]
	v_pk_fma_f32 v[232:233], v[28:29], v[224:225], v[232:233]
	v_pk_fma_f32 v[234:235], v[28:29], v[226:227], v[234:235]
	v_cvt_scalef32_pk_f32_fp4 v[224:225], v194, 1.0 op_sel:[0,1,0]
	v_cvt_scalef32_pk_f32_fp4 v[226:227], v198, 1.0 op_sel:[0,1,0]
	v_pk_fma_f32 v[232:233], v[30:31], v[228:229], v[232:233]
	v_pk_fma_f32 v[234:235], v[30:31], v[230:231], v[234:235]
	v_cvt_scalef32_pk_f32_fp4 v[228:229], v194, 1.0 op_sel:[1,1,0]
	v_cvt_scalef32_pk_f32_fp4 v[230:231], v198, 1.0 op_sel:[1,1,0]
	v_pk_fma_f32 v[232:233], v[16:17], v[224:225], v[232:233]
	v_pk_fma_f32 v[234:235], v[16:17], v[226:227], v[234:235]
	v_cvt_scalef32_pk_f32_fp4 v[224:225], v195, 1.0
	v_cvt_scalef32_pk_f32_fp4 v[226:227], v199, 1.0
	v_pk_fma_f32 v[232:233], v[18:19], v[228:229], v[232:233]
	v_pk_fma_f32 v[234:235], v[18:19], v[230:231], v[234:235]
	v_cvt_scalef32_pk_f32_fp4 v[228:229], v195, 1.0 op_sel:[1,0,0]
	v_cvt_scalef32_pk_f32_fp4 v[230:231], v199, 1.0 op_sel:[1,0,0]
	v_pk_fma_f32 v[232:233], v[8:9], v[224:225], v[232:233]
	v_pk_fma_f32 v[234:235], v[8:9], v[226:227], v[234:235]
	v_cvt_scalef32_pk_f32_fp4 v[224:225], v195, 1.0 op_sel:[0,1,0]
	v_cvt_scalef32_pk_f32_fp4 v[226:227], v199, 1.0 op_sel:[0,1,0]
	v_pk_fma_f32 v[232:233], v[10:11], v[228:229], v[232:233]
	v_pk_fma_f32 v[234:235], v[10:11], v[230:231], v[234:235]
	v_cvt_scalef32_pk_f32_fp4 v[228:229], v195, 1.0 op_sel:[1,1,0]
	v_cvt_scalef32_pk_f32_fp4 v[230:231], v199, 1.0 op_sel:[1,1,0]
	v_pk_fma_f32 v[232:233], v[20:21], v[224:225], v[232:233]
	v_pk_fma_f32 v[234:235], v[20:21], v[226:227], v[234:235]
	v_pk_fma_f32 v[232:233], v[22:23], v[228:229], v[232:233]
	v_pk_fma_f32 v[234:235], v[22:23], v[230:231], v[234:235]
	v_add_f32_e32 v32, v232, v233
	v_add_f32_e32 v33, v234, v235
	s_waitcnt vmcnt(4)
	v_cvt_scalef32_pk_f32_fp4 v[224:225], v200, 1.0
	v_cvt_scalef32_pk_f32_fp4 v[226:227], v204, 1.0
	v_cvt_scalef32_pk_f32_fp4 v[228:229], v200, 1.0 op_sel:[1,0,0]
	v_cvt_scalef32_pk_f32_fp4 v[230:231], v204, 1.0 op_sel:[1,0,0]
	v_pk_fma_f32 v[236:237], v[24:25], v[224:225], 0 op_sel_hi:[1,1,0]
	v_pk_fma_f32 v[238:239], v[24:25], v[226:227], 0 op_sel_hi:[1,1,0]
	v_cvt_scalef32_pk_f32_fp4 v[224:225], v200, 1.0 op_sel:[0,1,0]
	v_cvt_scalef32_pk_f32_fp4 v[226:227], v204, 1.0 op_sel:[0,1,0]
	v_pk_fma_f32 v[236:237], v[26:27], v[228:229], v[236:237]
	v_pk_fma_f32 v[238:239], v[26:27], v[230:231], v[238:239]
	v_cvt_scalef32_pk_f32_fp4 v[228:229], v200, 1.0 op_sel:[1,1,0]
	v_cvt_scalef32_pk_f32_fp4 v[230:231], v204, 1.0 op_sel:[1,1,0]
	v_pk_fma_f32 v[236:237], v[12:13], v[224:225], v[236:237]
	v_pk_fma_f32 v[238:239], v[12:13], v[226:227], v[238:239]
	v_cvt_scalef32_pk_f32_fp4 v[224:225], v201, 1.0
	v_cvt_scalef32_pk_f32_fp4 v[226:227], v205, 1.0
	v_pk_fma_f32 v[236:237], v[14:15], v[228:229], v[236:237]
	v_pk_fma_f32 v[238:239], v[14:15], v[230:231], v[238:239]
	v_cvt_scalef32_pk_f32_fp4 v[228:229], v201, 1.0 op_sel:[1,0,0]
	v_cvt_scalef32_pk_f32_fp4 v[230:231], v205, 1.0 op_sel:[1,0,0]
	v_pk_fma_f32 v[236:237], v[4:5], v[224:225], v[236:237]
	v_pk_fma_f32 v[238:239], v[4:5], v[226:227], v[238:239]
	v_cvt_scalef32_pk_f32_fp4 v[224:225], v201, 1.0 op_sel:[0,1,0]
	v_cvt_scalef32_pk_f32_fp4 v[226:227], v205, 1.0 op_sel:[0,1,0]
	v_pk_fma_f32 v[236:237], v[6:7], v[228:229], v[236:237]
	v_pk_fma_f32 v[238:239], v[6:7], v[230:231], v[238:239]
	v_cvt_scalef32_pk_f32_fp4 v[228:229], v201, 1.0 op_sel:[1,1,0]
	v_cvt_scalef32_pk_f32_fp4 v[230:231], v205, 1.0 op_sel:[1,1,0]
	v_pk_fma_f32 v[236:237], v[0:1], v[224:225], v[236:237]
	v_pk_fma_f32 v[238:239], v[0:1], v[226:227], v[238:239]
	v_cvt_scalef32_pk_f32_fp4 v[224:225], v202, 1.0
	v_cvt_scalef32_pk_f32_fp4 v[226:227], v206, 1.0
	v_pk_fma_f32 v[236:237], v[2:3], v[228:229], v[236:237]
	v_pk_fma_f32 v[238:239], v[2:3], v[230:231], v[238:239]
	v_cvt_scalef32_pk_f32_fp4 v[228:229], v202, 1.0 op_sel:[1,0,0]
	v_cvt_scalef32_pk_f32_fp4 v[230:231], v206, 1.0 op_sel:[1,0,0]
	v_pk_fma_f32 v[236:237], v[28:29], v[224:225], v[236:237]
	v_pk_fma_f32 v[238:239], v[28:29], v[226:227], v[238:239]
	v_cvt_scalef32_pk_f32_fp4 v[224:225], v202, 1.0 op_sel:[0,1,0]
	v_cvt_scalef32_pk_f32_fp4 v[226:227], v206, 1.0 op_sel:[0,1,0]
	v_pk_fma_f32 v[236:237], v[30:31], v[228:229], v[236:237]
	v_pk_fma_f32 v[238:239], v[30:31], v[230:231], v[238:239]
	v_cvt_scalef32_pk_f32_fp4 v[228:229], v202, 1.0 op_sel:[1,1,0]
	v_cvt_scalef32_pk_f32_fp4 v[230:231], v206, 1.0 op_sel:[1,1,0]
	v_pk_fma_f32 v[236:237], v[16:17], v[224:225], v[236:237]
	v_pk_fma_f32 v[238:239], v[16:17], v[226:227], v[238:239]
	v_cvt_scalef32_pk_f32_fp4 v[224:225], v203, 1.0
	v_cvt_scalef32_pk_f32_fp4 v[226:227], v207, 1.0
	v_pk_fma_f32 v[236:237], v[18:19], v[228:229], v[236:237]
	v_pk_fma_f32 v[238:239], v[18:19], v[230:231], v[238:239]
	v_cvt_scalef32_pk_f32_fp4 v[228:229], v203, 1.0 op_sel:[1,0,0]
	v_cvt_scalef32_pk_f32_fp4 v[230:231], v207, 1.0 op_sel:[1,0,0]
	v_pk_fma_f32 v[236:237], v[8:9], v[224:225], v[236:237]
	v_pk_fma_f32 v[238:239], v[8:9], v[226:227], v[238:239]
	v_cvt_scalef32_pk_f32_fp4 v[224:225], v203, 1.0 op_sel:[0,1,0]
	v_cvt_scalef32_pk_f32_fp4 v[226:227], v207, 1.0 op_sel:[0,1,0]
	v_pk_fma_f32 v[236:237], v[10:11], v[228:229], v[236:237]
	v_pk_fma_f32 v[238:239], v[10:11], v[230:231], v[238:239]
	v_cvt_scalef32_pk_f32_fp4 v[228:229], v203, 1.0 op_sel:[1,1,0]
	v_cvt_scalef32_pk_f32_fp4 v[230:231], v207, 1.0 op_sel:[1,1,0]
	v_pk_fma_f32 v[236:237], v[20:21], v[224:225], v[236:237]
	v_pk_fma_f32 v[238:239], v[20:21], v[226:227], v[238:239]
	v_pk_fma_f32 v[236:237], v[22:23], v[228:229], v[236:237]
	v_pk_fma_f32 v[238:239], v[22:23], v[230:231], v[238:239]
	v_add_f32_e32 v34, v236, v237
	v_add_f32_e32 v35, v238, v239
	v_cndmask_b32_e32 v36, v34, v32, vcc
	v_cndmask_b32_e32 v37, v32, v34, vcc
	v_cndmask_b32_e32 v38, v35, v33, vcc
	v_cndmask_b32_e32 v39, v33, v35, vcc
	ds_bpermute_b32 v37, v61, v37
	ds_bpermute_b32 v39, v61, v39
	s_waitcnt lgkmcnt(0)
	v_add_f32_e32 v36, v36, v37
	v_add_f32_e32 v38, v38, v39
	v_cndmask_b32_e64 v40, v38, v36, s[4:5]
	v_cndmask_b32_e64 v41, v36, v38, s[4:5]
	s_nop 1
	v_add_f32_dpp v40, v41, v40 row_ror:8 row_mask:0xf bank_mask:0xf
	s_nop 1
	v_add_f32_dpp v40, v40, v40 quad_perm:[1,0,3,2] row_mask:0xf bank_mask:0xf
	s_nop 1
	v_add_f32_dpp v40, v40, v40 quad_perm:[2,3,0,1] row_mask:0xf bank_mask:0xf
	s_nop 1
	v_add_f32_dpp v40, v40, v40 row_half_mirror row_mask:0xf bank_mask:0xf
	v_mul_f32_e32 v42, v40, v156
	v_fma_f32 v43, |v42|, s19, 1.0
	v_rcp_f32_e32 v43, v43
	v_cmp_gt_f32_e64 s[8:9], 0, v42
	v_mul_f32_e32 v45, v42, v42
	v_fmamk_f32 v44, v43, 0x3f07dc22, v145
	v_fmaak_f32 v44, v43, v44, 0x3f35f0e3
	v_fmaak_f32 v44, v43, v44, 0xbe11a98e
	v_fmaak_f32 v44, v43, v44, 0x3e027906
	v_mul_f32_e32 v45, 0xbf38aa3b, v45
	v_exp_f32_e32 v45, v45
	v_mul_f32_e32 v43, v43, v44
	v_mul_f32_e32 v43, v45, v43
	v_mul_f32_e32 v44, v42, v43
	v_fma_f32 v42, -v42, v43, v42
	v_cndmask_b32_e64 v42, v42, v44, s[8:9]
	v_mul_f32_e32 v158, v42, v157
	ds_bpermute_b32 v118, v141, v158
	ds_bpermute_b32 v120, v142, v158
	ds_bpermute_b32 v122, v143, v158
	ds_bpermute_b32 v124, v144, v158
	s_waitcnt vmcnt(3)
	v_cvt_scalef32_pk_f32_fp4 v[224:225], v208, 1.0
	v_cvt_scalef32_pk_f32_fp4 v[226:227], v208, 1.0 op_sel:[1,0,0]
	s_waitcnt lgkmcnt(0)
	v_cvt_scalef32_pk_f32_fp4 v[228:229], v208, 1.0 op_sel:[0,1,0]
	v_pk_fma_f32 v[114:115], v[224:225], v[118:119], v[114:115] op_sel_hi:[1,0,1]
	v_cvt_scalef32_pk_f32_fp4 v[230:231], v208, 1.0 op_sel:[1,1,0]
	v_pk_fma_f32 v[110:111], v[226:227], v[118:119], v[110:111] op_sel_hi:[1,0,1]
	v_cvt_scalef32_pk_f32_fp4 v[224:225], v209, 1.0
	v_pk_fma_f32 v[102:103], v[228:229], v[118:119], v[102:103] op_sel_hi:[1,0,1]
	v_cvt_scalef32_pk_f32_fp4 v[226:227], v209, 1.0 op_sel:[1,0,0]
	v_pk_fma_f32 v[100:101], v[230:231], v[118:119], v[100:101] op_sel_hi:[1,0,1]
	v_cvt_scalef32_pk_f32_fp4 v[228:229], v209, 1.0 op_sel:[0,1,0]
	v_pk_fma_f32 v[54:55], v[224:225], v[118:119], v[54:55] op_sel_hi:[1,0,1]
	v_cvt_scalef32_pk_f32_fp4 v[230:231], v209, 1.0 op_sel:[1,1,0]
	v_pk_fma_f32 v[58:59], v[226:227], v[118:119], v[58:59] op_sel_hi:[1,0,1]
	v_cvt_scalef32_pk_f32_fp4 v[224:225], v210, 1.0
	v_pk_fma_f32 v[52:53], v[228:229], v[118:119], v[52:53] op_sel_hi:[1,0,1]
	v_cvt_scalef32_pk_f32_fp4 v[226:227], v210, 1.0 op_sel:[1,0,0]
	v_pk_fma_f32 v[48:49], v[230:231], v[118:119], v[48:49] op_sel_hi:[1,0,1]
	v_cvt_scalef32_pk_f32_fp4 v[228:229], v210, 1.0 op_sel:[0,1,0]
	v_pk_fma_f32 v[108:109], v[224:225], v[118:119], v[108:109] op_sel_hi:[1,0,1]
	v_cvt_scalef32_pk_f32_fp4 v[230:231], v210, 1.0 op_sel:[1,1,0]
	v_pk_fma_f32 v[106:107], v[226:227], v[118:119], v[106:107] op_sel_hi:[1,0,1]
	v_cvt_scalef32_pk_f32_fp4 v[224:225], v211, 1.0
	v_pk_fma_f32 v[98:99], v[228:229], v[118:119], v[98:99] op_sel_hi:[1,0,1]
	v_cvt_scalef32_pk_f32_fp4 v[226:227], v211, 1.0 op_sel:[1,0,0]
	v_pk_fma_f32 v[56:57], v[230:231], v[118:119], v[56:57] op_sel_hi:[1,0,1]
	v_cvt_scalef32_pk_f32_fp4 v[228:229], v211, 1.0 op_sel:[0,1,0]
	v_pk_fma_f32 v[50:51], v[224:225], v[118:119], v[50:51] op_sel_hi:[1,0,1]
	v_cvt_scalef32_pk_f32_fp4 v[230:231], v211, 1.0 op_sel:[1,1,0]
	v_pk_fma_f32 v[116:117], v[226:227], v[118:119], v[116:117] op_sel_hi:[1,0,1]
	v_pk_fma_f32 v[112:113], v[228:229], v[118:119], v[112:113] op_sel_hi:[1,0,1]
	v_pk_fma_f32 v[104:105], v[230:231], v[118:119], v[104:105] op_sel_hi:[1,0,1]
	s_waitcnt vmcnt(2)
	v_cvt_scalef32_pk_f32_fp4 v[224:225], v212, 1.0
	v_cvt_scalef32_pk_f32_fp4 v[226:227], v212, 1.0 op_sel:[1,0,0]
	v_cvt_scalef32_pk_f32_fp4 v[228:229], v212, 1.0 op_sel:[0,1,0]
	v_pk_fma_f32 v[114:115], v[224:225], v[120:121], v[114:115] op_sel_hi:[1,0,1]
	v_cvt_scalef32_pk_f32_fp4 v[230:231], v212, 1.0 op_sel:[1,1,0]
	v_pk_fma_f32 v[110:111], v[226:227], v[120:121], v[110:111] op_sel_hi:[1,0,1]
	v_cvt_scalef32_pk_f32_fp4 v[224:225], v213, 1.0
	v_pk_fma_f32 v[102:103], v[228:229], v[120:121], v[102:103] op_sel_hi:[1,0,1]
	v_cvt_scalef32_pk_f32_fp4 v[226:227], v213, 1.0 op_sel:[1,0,0]
	v_pk_fma_f32 v[100:101], v[230:231], v[120:121], v[100:101] op_sel_hi:[1,0,1]
	v_cvt_scalef32_pk_f32_fp4 v[228:229], v213, 1.0 op_sel:[0,1,0]
	v_pk_fma_f32 v[54:55], v[224:225], v[120:121], v[54:55] op_sel_hi:[1,0,1]
	v_cvt_scalef32_pk_f32_fp4 v[230:231], v213, 1.0 op_sel:[1,1,0]
	v_pk_fma_f32 v[58:59], v[226:227], v[120:121], v[58:59] op_sel_hi:[1,0,1]
	v_cvt_scalef32_pk_f32_fp4 v[224:225], v214, 1.0
	v_pk_fma_f32 v[52:53], v[228:229], v[120:121], v[52:53] op_sel_hi:[1,0,1]
	v_cvt_scalef32_pk_f32_fp4 v[226:227], v214, 1.0 op_sel:[1,0,0]
	v_pk_fma_f32 v[48:49], v[230:231], v[120:121], v[48:49] op_sel_hi:[1,0,1]
	v_cvt_scalef32_pk_f32_fp4 v[228:229], v214, 1.0 op_sel:[0,1,0]
	v_pk_fma_f32 v[108:109], v[224:225], v[120:121], v[108:109] op_sel_hi:[1,0,1]
	v_cvt_scalef32_pk_f32_fp4 v[230:231], v214, 1.0 op_sel:[1,1,0]
	v_pk_fma_f32 v[106:107], v[226:227], v[120:121], v[106:107] op_sel_hi:[1,0,1]
	v_cvt_scalef32_pk_f32_fp4 v[224:225], v215, 1.0
	v_pk_fma_f32 v[98:99], v[228:229], v[120:121], v[98:99] op_sel_hi:[1,0,1]
	v_cvt_scalef32_pk_f32_fp4 v[226:227], v215, 1.0 op_sel:[1,0,0]
	v_pk_fma_f32 v[56:57], v[230:231], v[120:121], v[56:57] op_sel_hi:[1,0,1]
	v_cvt_scalef32_pk_f32_fp4 v[228:229], v215, 1.0 op_sel:[0,1,0]
	v_pk_fma_f32 v[50:51], v[224:225], v[120:121], v[50:51] op_sel_hi:[1,0,1]
	v_cvt_scalef32_pk_f32_fp4 v[230:231], v215, 1.0 op_sel:[1,1,0]
	v_pk_fma_f32 v[116:117], v[226:227], v[120:121], v[116:117] op_sel_hi:[1,0,1]
	v_pk_fma_f32 v[112:113], v[228:229], v[120:121], v[112:113] op_sel_hi:[1,0,1]
	v_pk_fma_f32 v[104:105], v[230:231], v[120:121], v[104:105] op_sel_hi:[1,0,1]
	s_waitcnt vmcnt(1)
	v_cvt_scalef32_pk_f32_fp4 v[224:225], v216, 1.0
	v_cvt_scalef32_pk_f32_fp4 v[226:227], v216, 1.0 op_sel:[1,0,0]
	v_cvt_scalef32_pk_f32_fp4 v[228:229], v216, 1.0 op_sel:[0,1,0]
	v_pk_fma_f32 v[114:115], v[224:225], v[122:123], v[114:115] op_sel_hi:[1,0,1]
	v_cvt_scalef32_pk_f32_fp4 v[230:231], v216, 1.0 op_sel:[1,1,0]
	v_pk_fma_f32 v[110:111], v[226:227], v[122:123], v[110:111] op_sel_hi:[1,0,1]
	v_cvt_scalef32_pk_f32_fp4 v[224:225], v217, 1.0
	v_pk_fma_f32 v[102:103], v[228:229], v[122:123], v[102:103] op_sel_hi:[1,0,1]
	v_cvt_scalef32_pk_f32_fp4 v[226:227], v217, 1.0 op_sel:[1,0,0]
	v_pk_fma_f32 v[100:101], v[230:231], v[122:123], v[100:101] op_sel_hi:[1,0,1]
	v_cvt_scalef32_pk_f32_fp4 v[228:229], v217, 1.0 op_sel:[0,1,0]
	v_pk_fma_f32 v[54:55], v[224:225], v[122:123], v[54:55] op_sel_hi:[1,0,1]
	v_cvt_scalef32_pk_f32_fp4 v[230:231], v217, 1.0 op_sel:[1,1,0]
	v_pk_fma_f32 v[58:59], v[226:227], v[122:123], v[58:59] op_sel_hi:[1,0,1]
	v_cvt_scalef32_pk_f32_fp4 v[224:225], v218, 1.0
	v_pk_fma_f32 v[52:53], v[228:229], v[122:123], v[52:53] op_sel_hi:[1,0,1]
	v_cvt_scalef32_pk_f32_fp4 v[226:227], v218, 1.0 op_sel:[1,0,0]
	v_pk_fma_f32 v[48:49], v[230:231], v[122:123], v[48:49] op_sel_hi:[1,0,1]
	v_cvt_scalef32_pk_f32_fp4 v[228:229], v218, 1.0 op_sel:[0,1,0]
	v_pk_fma_f32 v[108:109], v[224:225], v[122:123], v[108:109] op_sel_hi:[1,0,1]
	v_cvt_scalef32_pk_f32_fp4 v[230:231], v218, 1.0 op_sel:[1,1,0]
	v_pk_fma_f32 v[106:107], v[226:227], v[122:123], v[106:107] op_sel_hi:[1,0,1]
	v_cvt_scalef32_pk_f32_fp4 v[224:225], v219, 1.0
	v_pk_fma_f32 v[98:99], v[228:229], v[122:123], v[98:99] op_sel_hi:[1,0,1]
	v_cvt_scalef32_pk_f32_fp4 v[226:227], v219, 1.0 op_sel:[1,0,0]
	v_pk_fma_f32 v[56:57], v[230:231], v[122:123], v[56:57] op_sel_hi:[1,0,1]
	v_cvt_scalef32_pk_f32_fp4 v[228:229], v219, 1.0 op_sel:[0,1,0]
	v_pk_fma_f32 v[50:51], v[224:225], v[122:123], v[50:51] op_sel_hi:[1,0,1]
	v_cvt_scalef32_pk_f32_fp4 v[230:231], v219, 1.0 op_sel:[1,1,0]
	v_pk_fma_f32 v[116:117], v[226:227], v[122:123], v[116:117] op_sel_hi:[1,0,1]
	v_pk_fma_f32 v[112:113], v[228:229], v[122:123], v[112:113] op_sel_hi:[1,0,1]
	v_pk_fma_f32 v[104:105], v[230:231], v[122:123], v[104:105] op_sel_hi:[1,0,1]
	s_waitcnt vmcnt(0)
	v_cvt_scalef32_pk_f32_fp4 v[224:225], v220, 1.0
	v_cvt_scalef32_pk_f32_fp4 v[226:227], v220, 1.0 op_sel:[1,0,0]
	v_cvt_scalef32_pk_f32_fp4 v[228:229], v220, 1.0 op_sel:[0,1,0]
	v_pk_fma_f32 v[114:115], v[224:225], v[124:125], v[114:115] op_sel_hi:[1,0,1]
	v_cvt_scalef32_pk_f32_fp4 v[230:231], v220, 1.0 op_sel:[1,1,0]
	v_pk_fma_f32 v[110:111], v[226:227], v[124:125], v[110:111] op_sel_hi:[1,0,1]
	v_cvt_scalef32_pk_f32_fp4 v[224:225], v221, 1.0
	v_pk_fma_f32 v[102:103], v[228:229], v[124:125], v[102:103] op_sel_hi:[1,0,1]
	v_cvt_scalef32_pk_f32_fp4 v[226:227], v221, 1.0 op_sel:[1,0,0]
	v_pk_fma_f32 v[100:101], v[230:231], v[124:125], v[100:101] op_sel_hi:[1,0,1]
	v_cvt_scalef32_pk_f32_fp4 v[228:229], v221, 1.0 op_sel:[0,1,0]
	v_pk_fma_f32 v[54:55], v[224:225], v[124:125], v[54:55] op_sel_hi:[1,0,1]
	v_cvt_scalef32_pk_f32_fp4 v[230:231], v221, 1.0 op_sel:[1,1,0]
	v_pk_fma_f32 v[58:59], v[226:227], v[124:125], v[58:59] op_sel_hi:[1,0,1]
	v_cvt_scalef32_pk_f32_fp4 v[224:225], v222, 1.0
	v_pk_fma_f32 v[52:53], v[228:229], v[124:125], v[52:53] op_sel_hi:[1,0,1]
	v_cvt_scalef32_pk_f32_fp4 v[226:227], v222, 1.0 op_sel:[1,0,0]
	v_pk_fma_f32 v[48:49], v[230:231], v[124:125], v[48:49] op_sel_hi:[1,0,1]
	v_cvt_scalef32_pk_f32_fp4 v[228:229], v222, 1.0 op_sel:[0,1,0]
	v_pk_fma_f32 v[108:109], v[224:225], v[124:125], v[108:109] op_sel_hi:[1,0,1]
	v_cvt_scalef32_pk_f32_fp4 v[230:231], v222, 1.0 op_sel:[1,1,0]
	v_pk_fma_f32 v[106:107], v[226:227], v[124:125], v[106:107] op_sel_hi:[1,0,1]
	v_cvt_scalef32_pk_f32_fp4 v[224:225], v223, 1.0
	v_pk_fma_f32 v[98:99], v[228:229], v[124:125], v[98:99] op_sel_hi:[1,0,1]
	v_cvt_scalef32_pk_f32_fp4 v[226:227], v223, 1.0 op_sel:[1,0,0]
	v_pk_fma_f32 v[56:57], v[230:231], v[124:125], v[56:57] op_sel_hi:[1,0,1]
	v_cvt_scalef32_pk_f32_fp4 v[228:229], v223, 1.0 op_sel:[0,1,0]
	v_pk_fma_f32 v[50:51], v[224:225], v[124:125], v[50:51] op_sel_hi:[1,0,1]
	v_cvt_scalef32_pk_f32_fp4 v[230:231], v223, 1.0 op_sel:[1,1,0]
	v_pk_fma_f32 v[116:117], v[226:227], v[124:125], v[116:117] op_sel_hi:[1,0,1]
	v_pk_fma_f32 v[112:113], v[228:229], v[124:125], v[112:113] op_sel_hi:[1,0,1]
	v_pk_fma_f32 v[104:105], v[230:231], v[124:125], v[104:105] op_sel_hi:[1,0,1]
	ds_bpermute_b32 v32, v138, v114
	ds_bpermute_b32 v33, v138, v115
	ds_bpermute_b32 v128, v138, v112
	ds_bpermute_b32 v129, v138, v113
	ds_bpermute_b32 v118, v138, v108
	ds_bpermute_b32 v119, v138, v109
	ds_bpermute_b32 v34, v138, v110
	ds_bpermute_b32 v35, v138, v111
	ds_bpermute_b32 v120, v138, v106
	ds_bpermute_b32 v121, v138, v107
	s_waitcnt lgkmcnt(8)
	v_pk_add_f32 v[32:33], v[114:115], v[32:33]
	s_waitcnt lgkmcnt(6)
	v_pk_add_f32 v[112:113], v[112:113], v[128:129]
	v_pk_fma_f32 v[24:25], v[24:25], s[18:19], v[32:33] op_sel_hi:[1,0,1]
	v_pk_fma_f32 v[20:21], v[20:21], s[18:19], v[112:113] op_sel_hi:[1,0,1]
	ds_bpermute_b32 v112, v138, v104
	ds_bpermute_b32 v113, v138, v105
	v_add_f32_e32 v32, 0, v24
	ds_bpermute_b32 v36, v138, v102
	ds_bpermute_b32 v37, v138, v103
	v_add_f32_e32 v94, v32, v25
	s_waitcnt lgkmcnt(8)
	v_pk_add_f32 v[32:33], v[108:109], v[118:119]
	ds_bpermute_b32 v122, v138, v98
	ds_bpermute_b32 v123, v138, v99
	v_pk_fma_f32 v[28:29], v[28:29], s[18:19], v[32:33] op_sel_hi:[1,0,1]
	s_waitcnt lgkmcnt(8)
	v_pk_add_f32 v[32:33], v[110:111], v[34:35]
	ds_bpermute_b32 v38, v138, v100
	v_pk_fma_f32 v[26:27], v[26:27], s[18:19], v[32:33] op_sel_hi:[1,0,1]
	s_waitcnt lgkmcnt(7)
	v_pk_add_f32 v[32:33], v[106:107], v[120:121]
	ds_bpermute_b32 v39, v138, v101
	v_pk_fma_f32 v[30:31], v[30:31], s[18:19], v[32:33] op_sel_hi:[1,0,1]
	v_add_f32_e32 v32, v94, v26
	ds_bpermute_b32 v124, v138, v56
	ds_bpermute_b32 v125, v138, v57
	v_add_f32_e32 v34, v32, v27
	s_waitcnt lgkmcnt(8)
	v_pk_add_f32 v[32:33], v[104:105], v[112:113]
	ds_bpermute_b32 v40, v138, v54
	v_pk_fma_f32 v[22:23], v[22:23], s[18:19], v[32:33] op_sel_hi:[1,0,1]
	s_waitcnt lgkmcnt(7)
	v_pk_add_f32 v[32:33], v[102:103], v[36:37]
	ds_bpermute_b32 v41, v138, v55
	v_pk_fma_f32 v[12:13], v[12:13], s[18:19], v[32:33] op_sel_hi:[1,0,1]
	s_waitcnt lgkmcnt(6)
	v_pk_add_f32 v[32:33], v[98:99], v[122:123]
	ds_bpermute_b32 v132, v138, v50
	ds_bpermute_b32 v133, v138, v51
	v_pk_fma_f32 v[16:17], v[16:17], s[18:19], v[32:33] op_sel_hi:[1,0,1]
	v_add_f32_e32 v32, v34, v12
	v_add_f32_e32 v34, v32, v13
	s_waitcnt lgkmcnt(6)
	v_pk_add_f32 v[32:33], v[100:101], v[38:39]
	ds_bpermute_b32 v42, v138, v58
	ds_bpermute_b32 v43, v138, v59
	v_pk_fma_f32 v[14:15], v[14:15], s[18:19], v[32:33] op_sel_hi:[1,0,1]
	s_waitcnt lgkmcnt(6)
	v_pk_add_f32 v[32:33], v[56:57], v[124:125]
	ds_bpermute_b32 v44, v138, v52
	v_pk_fma_f32 v[18:19], v[18:19], s[18:19], v[32:33] op_sel_hi:[1,0,1]
	v_add_f32_e32 v32, v34, v14
	v_add_f32_e32 v34, v32, v15
	s_waitcnt lgkmcnt(5)
	v_pk_add_f32 v[32:33], v[54:55], v[40:41]
	ds_bpermute_b32 v45, v138, v53
	v_pk_fma_f32 v[32:33], v[4:5], s[18:19], v[32:33] op_sel_hi:[1,0,1]
	s_waitcnt lgkmcnt(4)
	v_pk_add_f32 v[4:5], v[50:51], v[132:133]
	ds_bpermute_b32 v46, v138, v48
	v_pk_fma_f32 v[8:9], v[8:9], s[18:19], v[4:5] op_sel_hi:[1,0,1]
	v_add_f32_e32 v4, v34, v32
	v_add_f32_e32 v36, v4, v33
	s_waitcnt lgkmcnt(3)
	v_pk_add_f32 v[4:5], v[58:59], v[42:43]
	ds_bpermute_b32 v47, v138, v49
	v_pk_fma_f32 v[34:35], v[6:7], s[18:19], v[4:5] op_sel_hi:[1,0,1]
	ds_bpermute_b32 v126, v138, v116
	v_add_f32_e32 v4, v36, v34
	v_add_f32_e32 v6, v4, v35
	s_waitcnt lgkmcnt(3)
	v_pk_add_f32 v[4:5], v[52:53], v[44:45]
	ds_bpermute_b32 v127, v138, v117
	v_pk_fma_f32 v[36:37], v[0:1], s[18:19], v[4:5] op_sel_hi:[1,0,1]
	v_mov_b32_e32 v94, v147
	v_add_f32_e32 v0, v6, v36
	v_add_f32_e32 v4, v0, v37
	s_waitcnt lgkmcnt(2)
	v_pk_add_f32 v[0:1], v[48:49], v[46:47]
	s_waitcnt lgkmcnt(0)
	v_pk_add_f32 v[116:117], v[116:117], v[126:127]
	v_pk_fma_f32 v[38:39], v[2:3], s[18:19], v[0:1] op_sel_hi:[1,0,1]
	v_pk_fma_f32 v[10:11], v[10:11], s[18:19], v[116:117] op_sel_hi:[1,0,1]
	v_add_f32_e32 v0, v4, v38
	v_add_f32_e32 v0, v0, v39
	v_add_f32_e32 v0, v0, v28
	v_add_f32_e32 v0, v0, v29
	v_add_f32_e32 v0, v0, v30
	v_add_f32_e32 v0, v0, v31
	v_add_f32_e32 v0, v0, v16
	v_add_f32_e32 v0, v0, v17
	v_add_f32_e32 v0, v0, v18
	v_add_f32_e32 v0, v0, v19
	v_add_f32_e32 v0, v0, v8
	v_add_f32_e32 v0, v0, v9
	v_add_f32_e32 v0, v0, v10
	v_add_f32_e32 v0, v0, v11
	v_add_f32_e32 v0, v0, v20
	v_add_f32_e32 v0, v0, v21
	v_add_f32_e32 v0, v0, v22
	v_add_f32_e32 v0, v0, v23
	ds_bpermute_b32 v1, v61, v0
	v_mov_b32_e32 v96, v148
	s_waitcnt lgkmcnt(0)
	v_add_f32_e32 v0, v0, v1
	ds_bpermute_b32 v1, v63, v0
	s_waitcnt lgkmcnt(0)
	v_add_f32_e32 v0, v0, v1
	ds_bpermute_b32 v1, v131, v0
	s_waitcnt lgkmcnt(0)
	v_add_f32_e32 v0, v0, v1
	ds_bpermute_b32 v1, v136, v0
	s_waitcnt lgkmcnt(0)
	v_add_f32_e32 v40, v0, v1
	ds_bpermute_b32 v41, v137, v40
	global_load_dwordx4 v[0:3], v[70:71], off
	global_load_dwordx4 v[4:7], v[72:73], off
	s_waitcnt lgkmcnt(0)
	v_add_f32_e32 v40, v40, v41
	v_mul_f32_e32 v40, 0x3a800000, v40
	v_pk_add_f32 v[24:25], v[24:25], v[40:41] op_sel_hi:[1,0] neg_lo:[0,1] neg_hi:[0,1]
	v_pk_add_f32 v[26:27], v[26:27], v[40:41] op_sel_hi:[1,0] neg_lo:[0,1] neg_hi:[0,1]
	v_pk_mul_f32 v[42:43], v[24:25], v[24:25]
	v_pk_mul_f32 v[44:45], v[26:27], v[26:27]
	v_add_f32_e32 v42, v42, v43
	v_pk_add_f32 v[12:13], v[12:13], v[40:41] op_sel_hi:[1,0] neg_lo:[0,1] neg_hi:[0,1]
	v_add_f32_e32 v42, v44, v42
	v_pk_mul_f32 v[46:47], v[12:13], v[12:13]
	v_add_f32_e32 v42, v45, v42
	v_pk_add_f32 v[14:15], v[14:15], v[40:41] op_sel_hi:[1,0] neg_lo:[0,1] neg_hi:[0,1]
	v_add_f32_e32 v42, v46, v42
	v_pk_mul_f32 v[48:49], v[14:15], v[14:15]
	v_add_f32_e32 v42, v47, v42
	v_pk_add_f32 v[32:33], v[32:33], v[40:41] op_sel_hi:[1,0] neg_lo:[0,1] neg_hi:[0,1]
	v_add_f32_e32 v42, v48, v42
	v_pk_mul_f32 v[50:51], v[32:33], v[32:33]
	v_add_f32_e32 v42, v49, v42
	v_pk_add_f32 v[34:35], v[34:35], v[40:41] op_sel_hi:[1,0] neg_lo:[0,1] neg_hi:[0,1]
	v_add_f32_e32 v42, v50, v42
	v_pk_mul_f32 v[52:53], v[34:35], v[34:35]
	v_add_f32_e32 v42, v51, v42
	v_pk_add_f32 v[36:37], v[36:37], v[40:41] op_sel_hi:[1,0] neg_lo:[0,1] neg_hi:[0,1]
	v_add_f32_e32 v42, v52, v42
	v_pk_mul_f32 v[54:55], v[36:37], v[36:37]
	v_add_f32_e32 v42, v53, v42
	v_pk_add_f32 v[38:39], v[38:39], v[40:41] op_sel_hi:[1,0] neg_lo:[0,1] neg_hi:[0,1]
	v_add_f32_e32 v42, v54, v42
	v_pk_mul_f32 v[56:57], v[38:39], v[38:39]
	v_add_f32_e32 v42, v55, v42
	v_pk_add_f32 v[28:29], v[28:29], v[40:41] op_sel_hi:[1,0] neg_lo:[0,1] neg_hi:[0,1]
	v_add_f32_e32 v42, v56, v42
	v_pk_mul_f32 v[58:59], v[28:29], v[28:29]
	v_add_f32_e32 v42, v57, v42
	v_pk_add_f32 v[30:31], v[30:31], v[40:41] op_sel_hi:[1,0] neg_lo:[0,1] neg_hi:[0,1]
	v_add_f32_e32 v42, v58, v42
	v_pk_mul_f32 v[98:99], v[30:31], v[30:31]
	v_add_f32_e32 v42, v59, v42
	v_pk_add_f32 v[16:17], v[16:17], v[40:41] op_sel_hi:[1,0] neg_lo:[0,1] neg_hi:[0,1]
	v_add_f32_e32 v42, v98, v42
	v_pk_mul_f32 v[100:101], v[16:17], v[16:17]
	v_add_f32_e32 v42, v99, v42
	v_pk_add_f32 v[18:19], v[18:19], v[40:41] op_sel_hi:[1,0] neg_lo:[0,1] neg_hi:[0,1]
	v_add_f32_e32 v42, v100, v42
	v_pk_mul_f32 v[102:103], v[18:19], v[18:19]
	v_add_f32_e32 v42, v101, v42
	v_pk_add_f32 v[104:105], v[8:9], v[40:41] op_sel_hi:[1,0] neg_lo:[0,1] neg_hi:[0,1]
	v_add_f32_e32 v42, v102, v42
	v_pk_mul_f32 v[8:9], v[104:105], v[104:105]
	v_add_f32_e32 v42, v103, v42
	v_pk_add_f32 v[106:107], v[10:11], v[40:41] op_sel_hi:[1,0] neg_lo:[0,1] neg_hi:[0,1]
	v_add_f32_e32 v8, v8, v42
	v_pk_mul_f32 v[10:11], v[106:107], v[106:107]
	v_add_f32_e32 v8, v9, v8
	v_pk_add_f32 v[20:21], v[20:21], v[40:41] op_sel_hi:[1,0] neg_lo:[0,1] neg_hi:[0,1]
	v_add_f32_e32 v8, v10, v8
	v_pk_mul_f32 v[108:109], v[20:21], v[20:21]
	v_add_f32_e32 v8, v11, v8
	v_pk_add_f32 v[22:23], v[22:23], v[40:41] op_sel_hi:[1,0] neg_lo:[0,1] neg_hi:[0,1]
	v_add_f32_e32 v8, v108, v8
	v_pk_mul_f32 v[40:41], v[22:23], v[22:23]
	v_add_f32_e32 v8, v109, v8
	v_add_f32_e32 v8, v40, v8
	v_add_f32_e32 v8, v41, v8
	ds_bpermute_b32 v9, v61, v8
	v_lshl_add_u64 v[40:41], v[92:93], 0, v[64:65]
	v_cndmask_b32_e64 v13, v17, v13, s[6:7]
	v_cndmask_b32_e64 v12, v16, v12, s[6:7]
	v_cndmask_b32_e64 v15, v19, v15, s[6:7]
	s_waitcnt lgkmcnt(0)
	v_add_f32_e32 v8, v8, v9
	ds_bpermute_b32 v9, v63, v8
	v_cndmask_b32_e64 v14, v18, v14, s[6:7]
	v_cndmask_b32_e64 v17, v105, v33, s[6:7]
	v_cndmask_b32_e64 v16, v104, v32, s[6:7]
	v_cndmask_b32_e64 v19, v107, v35, s[6:7]
	s_waitcnt lgkmcnt(0)
	v_add_f32_e32 v8, v8, v9
	ds_bpermute_b32 v9, v131, v8
	v_cndmask_b32_e64 v18, v106, v34, s[6:7]
	v_cndmask_b32_e64 v21, v21, v37, s[6:7]
	v_cndmask_b32_e64 v20, v20, v36, s[6:7]
	v_cndmask_b32_e64 v23, v23, v39, s[6:7]
	s_waitcnt lgkmcnt(0)
	v_add_f32_e32 v8, v8, v9
	ds_bpermute_b32 v9, v136, v8
	v_cndmask_b32_e64 v22, v22, v38, s[6:7]
	v_mov_b32_e32 v32, v97
	s_waitcnt lgkmcnt(0)
	v_add_f32_e32 v8, v8, v9
	ds_bpermute_b32 v9, v137, v8
	s_waitcnt lgkmcnt(0)
	v_add_f32_e32 v8, v8, v9
	v_fmamk_f32 v8, v8, 0x3a800000, v146
	v_mul_f32_e32 v9, 0x4b800000, v8
	v_cmp_gt_f32_e64 s[0:1], s20, v8
	s_nop 1
	v_cndmask_b32_e64 v8, v8, v9, s[0:1]
	v_rsq_f32_e32 v8, v8
	s_nop 0
	v_mul_f32_e32 v9, 0x45800000, v8
	v_cndmask_b32_e64 v42, v8, v9, s[0:1]
	v_cndmask_b32_e64 v9, v29, v25, s[6:7]
	v_cndmask_b32_e64 v8, v28, v24, s[6:7]
	v_pk_mul_f32 v[8:9], v[8:9], v[42:43] op_sel_hi:[1,0]
	v_pk_mul_f32 v[12:13], v[12:13], v[42:43] op_sel_hi:[1,0]
	s_waitcnt vmcnt(0)
	v_pk_fma_f32 v[0:1], v[0:1], v[8:9], v[4:5]
	v_cndmask_b32_e64 v5, v31, v27, s[6:7]
	v_cndmask_b32_e64 v4, v30, v26, s[6:7]
	v_pk_mul_f32 v[4:5], v[4:5], v[42:43] op_sel_hi:[1,0]
	v_pk_mul_f32 v[14:15], v[14:15], v[42:43] op_sel_hi:[1,0]
	v_pk_fma_f32 v[2:3], v[2:3], v[4:5], v[6:7]
	global_store_dwordx4 v[40:41], v[0:3], off
	global_load_dwordx4 v[4:7], v[74:75], off
	global_load_dwordx4 v[8:11], v[76:77], off
	v_pk_mul_f32 v[16:17], v[16:17], v[42:43] op_sel_hi:[1,0]
	v_pk_mul_f32 v[18:19], v[18:19], v[42:43] op_sel_hi:[1,0]
	v_lshlrev_b64 v[24:25], 11, v[90:91]
	v_pk_mul_f32 v[20:21], v[20:21], v[42:43] op_sel_hi:[1,0]
	v_pk_mul_f32 v[22:23], v[22:23], v[42:43] op_sel_hi:[1,0]
	v_lshl_add_u64 v[24:25], v[86:87], 0, v[24:25]
	v_cvt_pk_bf16_f32 v0, v0, v1
	v_cvt_pk_bf16_f32 v1, v2, v3
	s_waitcnt vmcnt(0)
	v_pk_fma_f32 v[4:5], v[4:5], v[12:13], v[8:9]
	v_pk_fma_f32 v[6:7], v[6:7], v[14:15], v[10:11]
	global_store_dwordx4 v[40:41], v[4:7], off offset:16
	global_load_dwordx4 v[8:11], v[78:79], off
	global_load_dwordx4 v[12:15], v[80:81], off
	v_cvt_pk_bf16_f32 v2, v4, v5
	v_cvt_pk_bf16_f32 v3, v6, v7
	s_waitcnt vmcnt(0)
	v_pk_fma_f32 v[8:9], v[8:9], v[16:17], v[12:13]
	v_pk_fma_f32 v[10:11], v[10:11], v[18:19], v[14:15]
	global_store_dwordx4 v[40:41], v[8:11], off offset:32
	global_load_dwordx4 v[12:15], v[82:83], off
	global_load_dwordx4 v[16:19], v[84:85], off
	v_cvt_pk_bf16_f32 v4, v8, v9
	v_cvt_pk_bf16_f32 v5, v10, v11
	s_waitcnt vmcnt(0)
	v_pk_fma_f32 v[6:7], v[12:13], v[20:21], v[16:17]
	v_pk_fma_f32 v[8:9], v[14:15], v[22:23], v[18:19]
	global_store_dwordx4 v[40:41], v[6:9], off offset:48
	s_nop 1
	v_cvt_pk_bf16_f32 v6, v6, v7
	v_cvt_pk_bf16_f32 v7, v8, v9
	global_store_dwordx4 v[24:25], v[0:3], off
	global_store_dwordx4 v[24:25], v[4:7], off offset:16
	s_andn2_b64 exec, exec, s[16:17]
	s_cbranch_execnz .LBB0_389

.LBB0_698:
	v_mov_b32_e32 v34, v60
	v_ashrrev_i32_e32 v35, 31, v34
	v_lshlrev_b64 v[90:91], 12, v[34:35]
	v_lshl_add_u64 v[36:37], v[86:87], 0, v[90:91]
	v_add_u32_e32 v60, s14, v34
	global_load_dwordx4 v[12:15], v[36:37], off offset:16
	global_load_dwordx4 v[24:27], v[36:37], off
	global_load_dwordx4 v[4:7], v[36:37], off offset:32
	global_load_dwordx4 v[0:3], v[36:37], off offset:48
	global_load_dwordx4 v[20:23], v[36:37], off offset:112
	global_load_dwordx4 v[8:11], v[36:37], off offset:96
	global_load_dwordx4 v[16:19], v[36:37], off offset:80
	global_load_dwordx4 v[28:31], v[36:37], off offset:64
	v_cmp_gt_i32_e64 s[4:5], s13, v60
	s_waitcnt vmcnt(9)
	v_mov_b32_e32 v33, v93
	v_ashrrev_i32_e32 v93, 31, v92
	v_cndmask_b32_e64 v34, v34, v60, s[4:5]
	v_ashrrev_i32_e32 v35, 31, v34
	v_lshlrev_b64 v[36:37], 2, v[92:93]
	v_ashrrev_i32_e32 v95, 31, v94
	v_lshlrev_b64 v[34:35], 9, v[34:35]
	v_lshl_add_u64 v[38:39], s[6:7], 0, v[36:37]
	v_lshlrev_b64 v[40:41], 2, v[94:95]
	v_lshl_add_u64 v[36:37], s[8:9], 0, v[36:37]
	v_lshl_or_b32 v34, v62, 2, v34
	v_lshl_add_u64 v[42:43], s[6:7], 0, v[40:41]
	global_load_dword v146, v[38:39], off
	global_load_dword v147, v[42:43], off
	v_lshl_add_u64 v[38:39], s[8:9], 0, v[40:41]
	global_load_dword v40, v[36:37], off
	global_load_dword v41, v[38:39], off
	v_lshl_add_u64 v[36:37], s[46:47], 0, v[34:35]
	v_lshl_add_u64 v[34:35], s[44:45], 0, v[34:35]
	global_load_dword v144, v[36:37], off
	global_load_dword v145, v[36:37], off offset:256
	global_load_dword v93, v[34:35], off
	global_load_dword v95, v[34:35], off offset:256
	v_cmp_lt_i32_e64 s[4:5], s15, v60
	s_mov_b32 s18, 0
	v_mov_b32_e32 v48, 0
	v_mov_b32_e32 v49, v65
	v_mov_b32_e32 v106, 0
	v_mov_b32_e32 v107, v65
	v_mov_b32_e32 v102, 0
	v_mov_b32_e32 v103, v65
	v_mov_b32_e32 v96, 0
	v_mov_b32_e32 v97, v65
	v_mov_b32_e32 v56, 0
	v_mov_b32_e32 v57, v65
	v_mov_b32_e32 v50, 0
	v_mov_b32_e32 v51, v65
	v_mov_b32_e32 v53, 0
	v_mov_b32_e32 v52, v65
	v_mov_b32_e32 v59, 0
	v_mov_b32_e32 v58, v65
	v_mov_b32_e32 v55, 0
	v_mov_b32_e32 v54, v65
	v_mov_b32_e32 v99, 0
	v_mov_b32_e32 v98, v65
	v_mov_b32_e32 v105, 0
	v_mov_b32_e32 v104, v65
	v_mov_b32_e32 v109, 0
	v_mov_b32_e32 v108, v65
	v_mov_b32_e32 v113, 0
	v_mov_b32_e32 v112, v65
	s_mov_b32 s19, 0
	v_mov_b32_e32 v100, 0
	v_mov_b32_e32 v101, v65
	s_or_b64 s[10:11], s[4:5], s[10:11]
	v_mov_b32_e32 v110, 0
	v_mov_b32_e32 v111, v65
	v_mov_b32_e32 v114, 0
	v_mov_b32_e32 v115, v65
	s_waitcnt vmcnt(5)
	v_mul_f32_e32 v148, v33, v40
	s_waitcnt vmcnt(4)
	v_mul_f32_e32 v149, v32, v41
	v_readfirstlane_b32 s98, v66
	v_readfirstlane_b32 s99, v67
	v_readfirstlane_b32 s100, v68
	v_readfirstlane_b32 s101, v69
	v_and_b32_e32 v241, 31, v62
	v_lshlrev_b32_e32 v241, 4, v241
	s_mov_b32 s19, 0
	v_lshlrev_b32_e32 v129, 2, v136
	ds_bpermute_b32 v240, v129, v92
	ds_bpermute_b32 v242, v129, v92 offset:8
	ds_bpermute_b32 v246, v129, v92 offset:16
	ds_bpermute_b32 v248, v129, v92 offset:24
	s_waitcnt lgkmcnt(0)
	v_lshl_add_u32 v250, v240, 9, v241
	v_lshl_add_u32 v251, v242, 9, v241
	v_lshl_add_u32 v252, v246, 9, v241
	v_lshl_add_u32 v253, v248, 9, v241
	global_load_dwordx4 v[160:163], v250, s[98:99]
	global_load_dwordx4 v[164:167], v251, s[98:99]
	global_load_dwordx4 v[168:171], v252, s[98:99]
	global_load_dwordx4 v[172:175], v253, s[98:99]
	global_load_dwordx4 v[176:179], v250, s[100:101]
	global_load_dwordx4 v[180:183], v251, s[100:101]
	global_load_dwordx4 v[184:187], v252, s[100:101]
	global_load_dwordx4 v[188:191], v253, s[100:101]
	v_add_u32_e32 v129, 32, v129
	ds_bpermute_b32 v240, v129, v92
	ds_bpermute_b32 v242, v129, v92 offset:8
	ds_bpermute_b32 v246, v129, v92 offset:16
	ds_bpermute_b32 v248, v129, v92 offset:24
.Lxg_loop_p12:
	s_waitcnt lgkmcnt(0)
	v_lshl_add_u32 v250, v240, 9, v241
	v_lshl_add_u32 v251, v242, 9, v241
	v_lshl_add_u32 v252, v246, 9, v241
	v_lshl_add_u32 v253, v248, 9, v241
	global_load_dwordx4 v[192:195], v250, s[98:99]
	global_load_dwordx4 v[196:199], v251, s[98:99]
	global_load_dwordx4 v[200:203], v252, s[98:99]
	global_load_dwordx4 v[204:207], v253, s[98:99]
	global_load_dwordx4 v[208:211], v250, s[100:101]
	global_load_dwordx4 v[212:215], v251, s[100:101]
	global_load_dwordx4 v[216:219], v252, s[100:101]
	global_load_dwordx4 v[220:223], v253, s[100:101]
	s_add_u32 s20, s19, 2
	s_cmp_lt_u32 s20, 8
	s_cselect_b64 s[4:5], -1, 0
	s_and_b32 s20, s20, 7
	s_lshl_b32 s20, s20, 5
	v_cndmask_b32_e64 v126, v94, v92, s[4:5]
	v_lshl_add_u32 v129, v136, 2, s20
	ds_bpermute_b32 v240, v129, v126
	ds_bpermute_b32 v242, v129, v126 offset:8
	ds_bpermute_b32 v246, v129, v126 offset:16
	ds_bpermute_b32 v248, v129, v126 offset:24
	s_add_u32 s20, s19, 0
	s_cmp_lt_u32 s20, 8
	s_cselect_b64 s[4:5], -1, 0
	s_and_b32 s20, s20, 7
	s_lshl_b32 s20, s20, 5
	v_cndmask_b32_e64 v127, v147, v146, s[4:5]
	v_cndmask_b32_e64 v128, v149, v148, s[4:5]
	v_lshl_add_u32 v130, v137, 2, s20
	ds_bpermute_b32 v156, v130, v127
	ds_bpermute_b32 v157, v130, v128
	s_waitcnt vmcnt(14)
	v_cvt_scalef32_pk_f32_fp4 v[224:225], v160, 1.0
	v_cvt_scalef32_pk_f32_fp4 v[226:227], v164, 1.0
	v_cvt_scalef32_pk_f32_fp4 v[228:229], v160, 1.0 op_sel:[1,0,0]
	v_cvt_scalef32_pk_f32_fp4 v[230:231], v164, 1.0 op_sel:[1,0,0]
	v_pk_fma_f32 v[232:233], v[24:25], v[224:225], 0 op_sel_hi:[1,1,0]
	v_pk_fma_f32 v[234:235], v[24:25], v[226:227], 0 op_sel_hi:[1,1,0]
	v_cvt_scalef32_pk_f32_fp4 v[224:225], v160, 1.0 op_sel:[0,1,0]
	v_cvt_scalef32_pk_f32_fp4 v[226:227], v164, 1.0 op_sel:[0,1,0]
	v_pk_fma_f32 v[232:233], v[26:27], v[228:229], v[232:233]
	v_pk_fma_f32 v[234:235], v[26:27], v[230:231], v[234:235]
	v_cvt_scalef32_pk_f32_fp4 v[228:229], v160, 1.0 op_sel:[1,1,0]
	v_cvt_scalef32_pk_f32_fp4 v[230:231], v164, 1.0 op_sel:[1,1,0]
	v_pk_fma_f32 v[232:233], v[12:13], v[224:225], v[232:233]
	v_pk_fma_f32 v[234:235], v[12:13], v[226:227], v[234:235]
	v_cvt_scalef32_pk_f32_fp4 v[224:225], v161, 1.0
	v_cvt_scalef32_pk_f32_fp4 v[226:227], v165, 1.0
	v_pk_fma_f32 v[232:233], v[14:15], v[228:229], v[232:233]
	v_pk_fma_f32 v[234:235], v[14:15], v[230:231], v[234:235]
	v_cvt_scalef32_pk_f32_fp4 v[228:229], v161, 1.0 op_sel:[1,0,0]
	v_cvt_scalef32_pk_f32_fp4 v[230:231], v165, 1.0 op_sel:[1,0,0]
	v_pk_fma_f32 v[232:233], v[4:5], v[224:225], v[232:233]
	v_pk_fma_f32 v[234:235], v[4:5], v[226:227], v[234:235]
	v_cvt_scalef32_pk_f32_fp4 v[224:225], v161, 1.0 op_sel:[0,1,0]
	v_cvt_scalef32_pk_f32_fp4 v[226:227], v165, 1.0 op_sel:[0,1,0]
	v_pk_fma_f32 v[232:233], v[6:7], v[228:229], v[232:233]
	v_pk_fma_f32 v[234:235], v[6:7], v[230:231], v[234:235]
	v_cvt_scalef32_pk_f32_fp4 v[228:229], v161, 1.0 op_sel:[1,1,0]
	v_cvt_scalef32_pk_f32_fp4 v[230:231], v165, 1.0 op_sel:[1,1,0]
	v_pk_fma_f32 v[232:233], v[0:1], v[224:225], v[232:233]
	v_pk_fma_f32 v[234:235], v[0:1], v[226:227], v[234:235]
	v_cvt_scalef32_pk_f32_fp4 v[224:225], v162, 1.0
	v_cvt_scalef32_pk_f32_fp4 v[226:227], v166, 1.0
	v_pk_fma_f32 v[232:233], v[2:3], v[228:229], v[232:233]
	v_pk_fma_f32 v[234:235], v[2:3], v[230:231], v[234:235]
	v_cvt_scalef32_pk_f32_fp4 v[228:229], v162, 1.0 op_sel:[1,0,0]
	v_cvt_scalef32_pk_f32_fp4 v[230:231], v166, 1.0 op_sel:[1,0,0]
	v_pk_fma_f32 v[232:233], v[28:29], v[224:225], v[232:233]
	v_pk_fma_f32 v[234:235], v[28:29], v[226:227], v[234:235]
	v_cvt_scalef32_pk_f32_fp4 v[224:225], v162, 1.0 op_sel:[0,1,0]
	v_cvt_scalef32_pk_f32_fp4 v[226:227], v166, 1.0 op_sel:[0,1,0]
	v_pk_fma_f32 v[232:233], v[30:31], v[228:229], v[232:233]
	v_pk_fma_f32 v[234:235], v[30:31], v[230:231], v[234:235]
	v_cvt_scalef32_pk_f32_fp4 v[228:229], v162, 1.0 op_sel:[1,1,0]
	v_cvt_scalef32_pk_f32_fp4 v[230:231], v166, 1.0 op_sel:[1,1,0]
	v_pk_fma_f32 v[232:233], v[16:17], v[224:225], v[232:233]
	v_pk_fma_f32 v[234:235], v[16:17], v[226:227], v[234:235]
	v_cvt_scalef32_pk_f32_fp4 v[224:225], v163, 1.0
	v_cvt_scalef32_pk_f32_fp4 v[226:227], v167, 1.0
	v_pk_fma_f32 v[232:233], v[18:19], v[228:229], v[232:233]
	v_pk_fma_f32 v[234:235], v[18:19], v[230:231], v[234:235]
	v_cvt_scalef32_pk_f32_fp4 v[228:229], v163, 1.0 op_sel:[1,0,0]
	v_cvt_scalef32_pk_f32_fp4 v[230:231], v167, 1.0 op_sel:[1,0,0]
	v_pk_fma_f32 v[232:233], v[8:9], v[224:225], v[232:233]
	v_pk_fma_f32 v[234:235], v[8:9], v[226:227], v[234:235]
	v_cvt_scalef32_pk_f32_fp4 v[224:225], v163, 1.0 op_sel:[0,1,0]
	v_cvt_scalef32_pk_f32_fp4 v[226:227], v167, 1.0 op_sel:[0,1,0]
	v_pk_fma_f32 v[232:233], v[10:11], v[228:229], v[232:233]
	v_pk_fma_f32 v[234:235], v[10:11], v[230:231], v[234:235]
	v_cvt_scalef32_pk_f32_fp4 v[228:229], v163, 1.0 op_sel:[1,1,0]
	v_cvt_scalef32_pk_f32_fp4 v[230:231], v167, 1.0 op_sel:[1,1,0]
	v_pk_fma_f32 v[232:233], v[20:21], v[224:225], v[232:233]
	v_pk_fma_f32 v[234:235], v[20:21], v[226:227], v[234:235]
	v_pk_fma_f32 v[232:233], v[22:23], v[228:229], v[232:233]
	v_pk_fma_f32 v[234:235], v[22:23], v[230:231], v[234:235]
	v_add_f32_e32 v32, v232, v233
	v_add_f32_e32 v33, v234, v235
	s_waitcnt vmcnt(12)
	v_cvt_scalef32_pk_f32_fp4 v[224:225], v168, 1.0
	v_cvt_scalef32_pk_f32_fp4 v[226:227], v172, 1.0
	v_cvt_scalef32_pk_f32_fp4 v[228:229], v168, 1.0 op_sel:[1,0,0]
	v_cvt_scalef32_pk_f32_fp4 v[230:231], v172, 1.0 op_sel:[1,0,0]
	v_pk_fma_f32 v[236:237], v[24:25], v[224:225], 0 op_sel_hi:[1,1,0]
	v_pk_fma_f32 v[238:239], v[24:25], v[226:227], 0 op_sel_hi:[1,1,0]
	v_cvt_scalef32_pk_f32_fp4 v[224:225], v168, 1.0 op_sel:[0,1,0]
	v_cvt_scalef32_pk_f32_fp4 v[226:227], v172, 1.0 op_sel:[0,1,0]
	v_pk_fma_f32 v[236:237], v[26:27], v[228:229], v[236:237]
	v_pk_fma_f32 v[238:239], v[26:27], v[230:231], v[238:239]
	v_cvt_scalef32_pk_f32_fp4 v[228:229], v168, 1.0 op_sel:[1,1,0]
	v_cvt_scalef32_pk_f32_fp4 v[230:231], v172, 1.0 op_sel:[1,1,0]
	v_pk_fma_f32 v[236:237], v[12:13], v[224:225], v[236:237]
	v_pk_fma_f32 v[238:239], v[12:13], v[226:227], v[238:239]
	v_cvt_scalef32_pk_f32_fp4 v[224:225], v169, 1.0
	v_cvt_scalef32_pk_f32_fp4 v[226:227], v173, 1.0
	v_pk_fma_f32 v[236:237], v[14:15], v[228:229], v[236:237]
	v_pk_fma_f32 v[238:239], v[14:15], v[230:231], v[238:239]
	v_cvt_scalef32_pk_f32_fp4 v[228:229], v169, 1.0 op_sel:[1,0,0]
	v_cvt_scalef32_pk_f32_fp4 v[230:231], v173, 1.0 op_sel:[1,0,0]
	v_pk_fma_f32 v[236:237], v[4:5], v[224:225], v[236:237]
	v_pk_fma_f32 v[238:239], v[4:5], v[226:227], v[238:239]
	v_cvt_scalef32_pk_f32_fp4 v[224:225], v169, 1.0 op_sel:[0,1,0]
	v_cvt_scalef32_pk_f32_fp4 v[226:227], v173, 1.0 op_sel:[0,1,0]
	v_pk_fma_f32 v[236:237], v[6:7], v[228:229], v[236:237]
	v_pk_fma_f32 v[238:239], v[6:7], v[230:231], v[238:239]
	v_cvt_scalef32_pk_f32_fp4 v[228:229], v169, 1.0 op_sel:[1,1,0]
	v_cvt_scalef32_pk_f32_fp4 v[230:231], v173, 1.0 op_sel:[1,1,0]
	v_pk_fma_f32 v[236:237], v[0:1], v[224:225], v[236:237]
	v_pk_fma_f32 v[238:239], v[0:1], v[226:227], v[238:239]
	v_cvt_scalef32_pk_f32_fp4 v[224:225], v170, 1.0
	v_cvt_scalef32_pk_f32_fp4 v[226:227], v174, 1.0
	v_pk_fma_f32 v[236:237], v[2:3], v[228:229], v[236:237]
	v_pk_fma_f32 v[238:239], v[2:3], v[230:231], v[238:239]
	v_cvt_scalef32_pk_f32_fp4 v[228:229], v170, 1.0 op_sel:[1,0,0]
	v_cvt_scalef32_pk_f32_fp4 v[230:231], v174, 1.0 op_sel:[1,0,0]
	v_pk_fma_f32 v[236:237], v[28:29], v[224:225], v[236:237]
	v_pk_fma_f32 v[238:239], v[28:29], v[226:227], v[238:239]
	v_cvt_scalef32_pk_f32_fp4 v[224:225], v170, 1.0 op_sel:[0,1,0]
	v_cvt_scalef32_pk_f32_fp4 v[226:227], v174, 1.0 op_sel:[0,1,0]
	v_pk_fma_f32 v[236:237], v[30:31], v[228:229], v[236:237]
	v_pk_fma_f32 v[238:239], v[30:31], v[230:231], v[238:239]
	v_cvt_scalef32_pk_f32_fp4 v[228:229], v170, 1.0 op_sel:[1,1,0]
	v_cvt_scalef32_pk_f32_fp4 v[230:231], v174, 1.0 op_sel:[1,1,0]
	v_pk_fma_f32 v[236:237], v[16:17], v[224:225], v[236:237]
	v_pk_fma_f32 v[238:239], v[16:17], v[226:227], v[238:239]
	v_cvt_scalef32_pk_f32_fp4 v[224:225], v171, 1.0
	v_cvt_scalef32_pk_f32_fp4 v[226:227], v175, 1.0
	v_pk_fma_f32 v[236:237], v[18:19], v[228:229], v[236:237]
	v_pk_fma_f32 v[238:239], v[18:19], v[230:231], v[238:239]
	v_cvt_scalef32_pk_f32_fp4 v[228:229], v171, 1.0 op_sel:[1,0,0]
	v_cvt_scalef32_pk_f32_fp4 v[230:231], v175, 1.0 op_sel:[1,0,0]
	v_pk_fma_f32 v[236:237], v[8:9], v[224:225], v[236:237]
	v_pk_fma_f32 v[238:239], v[8:9], v[226:227], v[238:239]
	v_cvt_scalef32_pk_f32_fp4 v[224:225], v171, 1.0 op_sel:[0,1,0]
	v_cvt_scalef32_pk_f32_fp4 v[226:227], v175, 1.0 op_sel:[0,1,0]
	v_pk_fma_f32 v[236:237], v[10:11], v[228:229], v[236:237]
	v_pk_fma_f32 v[238:239], v[10:11], v[230:231], v[238:239]
	v_cvt_scalef32_pk_f32_fp4 v[228:229], v171, 1.0 op_sel:[1,1,0]
	v_cvt_scalef32_pk_f32_fp4 v[230:231], v175, 1.0 op_sel:[1,1,0]
	v_pk_fma_f32 v[236:237], v[20:21], v[224:225], v[236:237]
	v_pk_fma_f32 v[238:239], v[20:21], v[226:227], v[238:239]
	v_pk_fma_f32 v[236:237], v[22:23], v[228:229], v[236:237]
	v_pk_fma_f32 v[238:239], v[22:23], v[230:231], v[238:239]
	v_add_f32_e32 v34, v236, v237
	v_add_f32_e32 v35, v238, v239
	v_cndmask_b32_e32 v36, v34, v32, vcc
	v_cndmask_b32_e32 v37, v32, v34, vcc
	v_cndmask_b32_e32 v38, v35, v33, vcc
	v_cndmask_b32_e32 v39, v33, v35, vcc
	ds_bpermute_b32 v37, v61, v37
	ds_bpermute_b32 v39, v61, v39
	s_waitcnt lgkmcnt(0)
	v_add_f32_e32 v36, v36, v37
	v_add_f32_e32 v38, v38, v39
	v_cndmask_b32_e64 v40, v38, v36, s[0:1]
	v_cndmask_b32_e64 v41, v36, v38, s[0:1]
	s_nop 1
	v_add_f32_dpp v40, v41, v40 row_ror:8 row_mask:0xf bank_mask:0xf
	s_nop 1
	v_add_f32_dpp v40, v40, v40 quad_perm:[1,0,3,2] row_mask:0xf bank_mask:0xf
	s_nop 1
	v_add_f32_dpp v40, v40, v40 quad_perm:[2,3,0,1] row_mask:0xf bank_mask:0xf
	s_nop 1
	v_add_f32_dpp v40, v40, v40 row_half_mirror row_mask:0xf bank_mask:0xf
	v_mul_f32_e32 v42, v40, v156
	v_fma_f32 v43, |v42|, s16, 1.0
	v_rcp_f32_e32 v43, v43
	v_cmp_gt_f32_e64 s[4:5], 0, v42
	v_mul_f32_e32 v45, v42, v42
	v_fmamk_f32 v44, v43, 0x3f07dc22, v142
	v_fmaak_f32 v44, v43, v44, 0x3f35f0e3
	v_fmaak_f32 v44, v43, v44, 0xbe11a98e
	v_fmaak_f32 v44, v43, v44, 0x3e027906
	v_mul_f32_e32 v45, 0xbf38aa3b, v45
	v_exp_f32_e32 v45, v45
	v_mul_f32_e32 v43, v43, v44
	v_mul_f32_e32 v43, v45, v43
	v_mul_f32_e32 v44, v42, v43
	v_fma_f32 v42, -v42, v43, v42
	v_cndmask_b32_e64 v42, v42, v44, s[4:5]
	v_mul_f32_e32 v158, v42, v157
	ds_bpermute_b32 v118, v138, v158
	ds_bpermute_b32 v120, v139, v158
	ds_bpermute_b32 v122, v140, v158
	ds_bpermute_b32 v124, v141, v158
	s_waitcnt vmcnt(11)
	v_cvt_scalef32_pk_f32_fp4 v[224:225], v176, 1.0
	v_cvt_scalef32_pk_f32_fp4 v[226:227], v176, 1.0 op_sel:[1,0,0]
	s_waitcnt lgkmcnt(0)
	v_cvt_scalef32_pk_f32_fp4 v[228:229], v176, 1.0 op_sel:[0,1,0]
	v_pk_fma_f32 v[112:113], v[224:225], v[118:119], v[112:113] op_sel_hi:[1,0,1]
	v_cvt_scalef32_pk_f32_fp4 v[230:231], v176, 1.0 op_sel:[1,1,0]
	v_pk_fma_f32 v[108:109], v[226:227], v[118:119], v[108:109] op_sel_hi:[1,0,1]
	v_cvt_scalef32_pk_f32_fp4 v[224:225], v177, 1.0
	v_pk_fma_f32 v[104:105], v[228:229], v[118:119], v[104:105] op_sel_hi:[1,0,1]
	v_cvt_scalef32_pk_f32_fp4 v[226:227], v177, 1.0 op_sel:[1,0,0]
	v_pk_fma_f32 v[98:99], v[230:231], v[118:119], v[98:99] op_sel_hi:[1,0,1]
	v_cvt_scalef32_pk_f32_fp4 v[228:229], v177, 1.0 op_sel:[0,1,0]
	v_pk_fma_f32 v[54:55], v[224:225], v[118:119], v[54:55] op_sel_hi:[1,0,1]
	v_cvt_scalef32_pk_f32_fp4 v[230:231], v177, 1.0 op_sel:[1,1,0]
	v_pk_fma_f32 v[58:59], v[226:227], v[118:119], v[58:59] op_sel_hi:[1,0,1]
	v_cvt_scalef32_pk_f32_fp4 v[224:225], v178, 1.0
	v_pk_fma_f32 v[52:53], v[228:229], v[118:119], v[52:53] op_sel_hi:[1,0,1]
	v_cvt_scalef32_pk_f32_fp4 v[226:227], v178, 1.0 op_sel:[1,0,0]
	v_pk_fma_f32 v[48:49], v[230:231], v[118:119], v[48:49] op_sel_hi:[1,0,1]
	v_cvt_scalef32_pk_f32_fp4 v[228:229], v178, 1.0 op_sel:[0,1,0]
	v_pk_fma_f32 v[106:107], v[224:225], v[118:119], v[106:107] op_sel_hi:[1,0,1]
	v_cvt_scalef32_pk_f32_fp4 v[230:231], v178, 1.0 op_sel:[1,1,0]
	v_pk_fma_f32 v[102:103], v[226:227], v[118:119], v[102:103] op_sel_hi:[1,0,1]
	v_cvt_scalef32_pk_f32_fp4 v[224:225], v179, 1.0
	v_pk_fma_f32 v[96:97], v[228:229], v[118:119], v[96:97] op_sel_hi:[1,0,1]
	v_cvt_scalef32_pk_f32_fp4 v[226:227], v179, 1.0 op_sel:[1,0,0]
	v_pk_fma_f32 v[56:57], v[230:231], v[118:119], v[56:57] op_sel_hi:[1,0,1]
	v_cvt_scalef32_pk_f32_fp4 v[228:229], v179, 1.0 op_sel:[0,1,0]
	v_pk_fma_f32 v[50:51], v[224:225], v[118:119], v[50:51] op_sel_hi:[1,0,1]
	v_cvt_scalef32_pk_f32_fp4 v[230:231], v179, 1.0 op_sel:[1,1,0]
	v_pk_fma_f32 v[114:115], v[226:227], v[118:119], v[114:115] op_sel_hi:[1,0,1]
	v_pk_fma_f32 v[110:111], v[228:229], v[118:119], v[110:111] op_sel_hi:[1,0,1]
	v_pk_fma_f32 v[100:101], v[230:231], v[118:119], v[100:101] op_sel_hi:[1,0,1]
	s_waitcnt vmcnt(10)
	v_cvt_scalef32_pk_f32_fp4 v[224:225], v180, 1.0
	v_cvt_scalef32_pk_f32_fp4 v[226:227], v180, 1.0 op_sel:[1,0,0]
	v_cvt_scalef32_pk_f32_fp4 v[228:229], v180, 1.0 op_sel:[0,1,0]
	v_pk_fma_f32 v[112:113], v[224:225], v[120:121], v[112:113] op_sel_hi:[1,0,1]
	v_cvt_scalef32_pk_f32_fp4 v[230:231], v180, 1.0 op_sel:[1,1,0]
	v_pk_fma_f32 v[108:109], v[226:227], v[120:121], v[108:109] op_sel_hi:[1,0,1]
	v_cvt_scalef32_pk_f32_fp4 v[224:225], v181, 1.0
	v_pk_fma_f32 v[104:105], v[228:229], v[120:121], v[104:105] op_sel_hi:[1,0,1]
	v_cvt_scalef32_pk_f32_fp4 v[226:227], v181, 1.0 op_sel:[1,0,0]
	v_pk_fma_f32 v[98:99], v[230:231], v[120:121], v[98:99] op_sel_hi:[1,0,1]
	v_cvt_scalef32_pk_f32_fp4 v[228:229], v181, 1.0 op_sel:[0,1,0]
	v_pk_fma_f32 v[54:55], v[224:225], v[120:121], v[54:55] op_sel_hi:[1,0,1]
	v_cvt_scalef32_pk_f32_fp4 v[230:231], v181, 1.0 op_sel:[1,1,0]
	v_pk_fma_f32 v[58:59], v[226:227], v[120:121], v[58:59] op_sel_hi:[1,0,1]
	v_cvt_scalef32_pk_f32_fp4 v[224:225], v182, 1.0
	v_pk_fma_f32 v[52:53], v[228:229], v[120:121], v[52:53] op_sel_hi:[1,0,1]
	v_cvt_scalef32_pk_f32_fp4 v[226:227], v182, 1.0 op_sel:[1,0,0]
	v_pk_fma_f32 v[48:49], v[230:231], v[120:121], v[48:49] op_sel_hi:[1,0,1]
	v_cvt_scalef32_pk_f32_fp4 v[228:229], v182, 1.0 op_sel:[0,1,0]
	v_pk_fma_f32 v[106:107], v[224:225], v[120:121], v[106:107] op_sel_hi:[1,0,1]
	v_cvt_scalef32_pk_f32_fp4 v[230:231], v182, 1.0 op_sel:[1,1,0]
	v_pk_fma_f32 v[102:103], v[226:227], v[120:121], v[102:103] op_sel_hi:[1,0,1]
	v_cvt_scalef32_pk_f32_fp4 v[224:225], v183, 1.0
	v_pk_fma_f32 v[96:97], v[228:229], v[120:121], v[96:97] op_sel_hi:[1,0,1]
	v_cvt_scalef32_pk_f32_fp4 v[226:227], v183, 1.0 op_sel:[1,0,0]
	v_pk_fma_f32 v[56:57], v[230:231], v[120:121], v[56:57] op_sel_hi:[1,0,1]
	v_cvt_scalef32_pk_f32_fp4 v[228:229], v183, 1.0 op_sel:[0,1,0]
	v_pk_fma_f32 v[50:51], v[224:225], v[120:121], v[50:51] op_sel_hi:[1,0,1]
	v_cvt_scalef32_pk_f32_fp4 v[230:231], v183, 1.0 op_sel:[1,1,0]
	v_pk_fma_f32 v[114:115], v[226:227], v[120:121], v[114:115] op_sel_hi:[1,0,1]
	v_pk_fma_f32 v[110:111], v[228:229], v[120:121], v[110:111] op_sel_hi:[1,0,1]
	v_pk_fma_f32 v[100:101], v[230:231], v[120:121], v[100:101] op_sel_hi:[1,0,1]
	s_waitcnt vmcnt(9)
	v_cvt_scalef32_pk_f32_fp4 v[224:225], v184, 1.0
	v_cvt_scalef32_pk_f32_fp4 v[226:227], v184, 1.0 op_sel:[1,0,0]
	v_cvt_scalef32_pk_f32_fp4 v[228:229], v184, 1.0 op_sel:[0,1,0]
	v_pk_fma_f32 v[112:113], v[224:225], v[122:123], v[112:113] op_sel_hi:[1,0,1]
	v_cvt_scalef32_pk_f32_fp4 v[230:231], v184, 1.0 op_sel:[1,1,0]
	v_pk_fma_f32 v[108:109], v[226:227], v[122:123], v[108:109] op_sel_hi:[1,0,1]
	v_cvt_scalef32_pk_f32_fp4 v[224:225], v185, 1.0
	v_pk_fma_f32 v[104:105], v[228:229], v[122:123], v[104:105] op_sel_hi:[1,0,1]
	v_cvt_scalef32_pk_f32_fp4 v[226:227], v185, 1.0 op_sel:[1,0,0]
	v_pk_fma_f32 v[98:99], v[230:231], v[122:123], v[98:99] op_sel_hi:[1,0,1]
	v_cvt_scalef32_pk_f32_fp4 v[228:229], v185, 1.0 op_sel:[0,1,0]
	v_pk_fma_f32 v[54:55], v[224:225], v[122:123], v[54:55] op_sel_hi:[1,0,1]
	v_cvt_scalef32_pk_f32_fp4 v[230:231], v185, 1.0 op_sel:[1,1,0]
	v_pk_fma_f32 v[58:59], v[226:227], v[122:123], v[58:59] op_sel_hi:[1,0,1]
	v_cvt_scalef32_pk_f32_fp4 v[224:225], v186, 1.0
	v_pk_fma_f32 v[52:53], v[228:229], v[122:123], v[52:53] op_sel_hi:[1,0,1]
	v_cvt_scalef32_pk_f32_fp4 v[226:227], v186, 1.0 op_sel:[1,0,0]
	v_pk_fma_f32 v[48:49], v[230:231], v[122:123], v[48:49] op_sel_hi:[1,0,1]
	v_cvt_scalef32_pk_f32_fp4 v[228:229], v186, 1.0 op_sel:[0,1,0]
	v_pk_fma_f32 v[106:107], v[224:225], v[122:123], v[106:107] op_sel_hi:[1,0,1]
	v_cvt_scalef32_pk_f32_fp4 v[230:231], v186, 1.0 op_sel:[1,1,0]
	v_pk_fma_f32 v[102:103], v[226:227], v[122:123], v[102:103] op_sel_hi:[1,0,1]
	v_cvt_scalef32_pk_f32_fp4 v[224:225], v187, 1.0
	v_pk_fma_f32 v[96:97], v[228:229], v[122:123], v[96:97] op_sel_hi:[1,0,1]
	v_cvt_scalef32_pk_f32_fp4 v[226:227], v187, 1.0 op_sel:[1,0,0]
	v_pk_fma_f32 v[56:57], v[230:231], v[122:123], v[56:57] op_sel_hi:[1,0,1]
	v_cvt_scalef32_pk_f32_fp4 v[228:229], v187, 1.0 op_sel:[0,1,0]
	v_pk_fma_f32 v[50:51], v[224:225], v[122:123], v[50:51] op_sel_hi:[1,0,1]
	v_cvt_scalef32_pk_f32_fp4 v[230:231], v187, 1.0 op_sel:[1,1,0]
	v_pk_fma_f32 v[114:115], v[226:227], v[122:123], v[114:115] op_sel_hi:[1,0,1]
	v_pk_fma_f32 v[110:111], v[228:229], v[122:123], v[110:111] op_sel_hi:[1,0,1]
	v_pk_fma_f32 v[100:101], v[230:231], v[122:123], v[100:101] op_sel_hi:[1,0,1]
	s_waitcnt vmcnt(8)
	v_cvt_scalef32_pk_f32_fp4 v[224:225], v188, 1.0
	v_cvt_scalef32_pk_f32_fp4 v[226:227], v188, 1.0 op_sel:[1,0,0]
	v_cvt_scalef32_pk_f32_fp4 v[228:229], v188, 1.0 op_sel:[0,1,0]
	v_pk_fma_f32 v[112:113], v[224:225], v[124:125], v[112:113] op_sel_hi:[1,0,1]
	v_cvt_scalef32_pk_f32_fp4 v[230:231], v188, 1.0 op_sel:[1,1,0]
	v_pk_fma_f32 v[108:109], v[226:227], v[124:125], v[108:109] op_sel_hi:[1,0,1]
	v_cvt_scalef32_pk_f32_fp4 v[224:225], v189, 1.0
	v_pk_fma_f32 v[104:105], v[228:229], v[124:125], v[104:105] op_sel_hi:[1,0,1]
	v_cvt_scalef32_pk_f32_fp4 v[226:227], v189, 1.0 op_sel:[1,0,0]
	v_pk_fma_f32 v[98:99], v[230:231], v[124:125], v[98:99] op_sel_hi:[1,0,1]
	v_cvt_scalef32_pk_f32_fp4 v[228:229], v189, 1.0 op_sel:[0,1,0]
	v_pk_fma_f32 v[54:55], v[224:225], v[124:125], v[54:55] op_sel_hi:[1,0,1]
	v_cvt_scalef32_pk_f32_fp4 v[230:231], v189, 1.0 op_sel:[1,1,0]
	v_pk_fma_f32 v[58:59], v[226:227], v[124:125], v[58:59] op_sel_hi:[1,0,1]
	v_cvt_scalef32_pk_f32_fp4 v[224:225], v190, 1.0
	v_pk_fma_f32 v[52:53], v[228:229], v[124:125], v[52:53] op_sel_hi:[1,0,1]
	v_cvt_scalef32_pk_f32_fp4 v[226:227], v190, 1.0 op_sel:[1,0,0]
	v_pk_fma_f32 v[48:49], v[230:231], v[124:125], v[48:49] op_sel_hi:[1,0,1]
	v_cvt_scalef32_pk_f32_fp4 v[228:229], v190, 1.0 op_sel:[0,1,0]
	v_pk_fma_f32 v[106:107], v[224:225], v[124:125], v[106:107] op_sel_hi:[1,0,1]
	v_cvt_scalef32_pk_f32_fp4 v[230:231], v190, 1.0 op_sel:[1,1,0]
	v_pk_fma_f32 v[102:103], v[226:227], v[124:125], v[102:103] op_sel_hi:[1,0,1]
	v_cvt_scalef32_pk_f32_fp4 v[224:225], v191, 1.0
	v_pk_fma_f32 v[96:97], v[228:229], v[124:125], v[96:97] op_sel_hi:[1,0,1]
	v_cvt_scalef32_pk_f32_fp4 v[226:227], v191, 1.0 op_sel:[1,0,0]
	v_pk_fma_f32 v[56:57], v[230:231], v[124:125], v[56:57] op_sel_hi:[1,0,1]
	v_cvt_scalef32_pk_f32_fp4 v[228:229], v191, 1.0 op_sel:[0,1,0]
	v_pk_fma_f32 v[50:51], v[224:225], v[124:125], v[50:51] op_sel_hi:[1,0,1]
	v_cvt_scalef32_pk_f32_fp4 v[230:231], v191, 1.0 op_sel:[1,1,0]
	v_pk_fma_f32 v[114:115], v[226:227], v[124:125], v[114:115] op_sel_hi:[1,0,1]
	v_pk_fma_f32 v[110:111], v[228:229], v[124:125], v[110:111] op_sel_hi:[1,0,1]
	v_pk_fma_f32 v[100:101], v[230:231], v[124:125], v[100:101] op_sel_hi:[1,0,1]
	s_waitcnt lgkmcnt(0)
	v_lshl_add_u32 v250, v240, 9, v241
	v_lshl_add_u32 v251, v242, 9, v241
	v_lshl_add_u32 v252, v246, 9, v241
	v_lshl_add_u32 v253, v248, 9, v241
	global_load_dwordx4 v[160:163], v250, s[98:99]
	global_load_dwordx4 v[164:167], v251, s[98:99]
	global_load_dwordx4 v[168:171], v252, s[98:99]
	global_load_dwordx4 v[172:175], v253, s[98:99]
	global_load_dwordx4 v[176:179], v250, s[100:101]
	global_load_dwordx4 v[180:183], v251, s[100:101]
	global_load_dwordx4 v[184:187], v252, s[100:101]
	global_load_dwordx4 v[188:191], v253, s[100:101]
	s_add_u32 s20, s19, 3
	s_cmp_lt_u32 s20, 8
	s_cselect_b64 s[4:5], -1, 0
	s_and_b32 s20, s20, 7
	s_lshl_b32 s20, s20, 5
	v_cndmask_b32_e64 v126, v94, v92, s[4:5]
	v_lshl_add_u32 v129, v136, 2, s20
	ds_bpermute_b32 v240, v129, v126
	ds_bpermute_b32 v242, v129, v126 offset:8
	ds_bpermute_b32 v246, v129, v126 offset:16
	ds_bpermute_b32 v248, v129, v126 offset:24
	s_add_u32 s20, s19, 1
	s_cmp_lt_u32 s20, 8
	s_cselect_b64 s[4:5], -1, 0
	s_and_b32 s20, s20, 7
	s_lshl_b32 s20, s20, 5
	v_cndmask_b32_e64 v127, v147, v146, s[4:5]
	v_cndmask_b32_e64 v128, v149, v148, s[4:5]
	v_lshl_add_u32 v130, v137, 2, s20
	ds_bpermute_b32 v156, v130, v127
	ds_bpermute_b32 v157, v130, v128
	s_waitcnt vmcnt(14)
	v_cvt_scalef32_pk_f32_fp4 v[224:225], v192, 1.0
	v_cvt_scalef32_pk_f32_fp4 v[226:227], v196, 1.0
	v_cvt_scalef32_pk_f32_fp4 v[228:229], v192, 1.0 op_sel:[1,0,0]
	v_cvt_scalef32_pk_f32_fp4 v[230:231], v196, 1.0 op_sel:[1,0,0]
	v_pk_fma_f32 v[232:233], v[24:25], v[224:225], 0 op_sel_hi:[1,1,0]
	v_pk_fma_f32 v[234:235], v[24:25], v[226:227], 0 op_sel_hi:[1,1,0]
	v_cvt_scalef32_pk_f32_fp4 v[224:225], v192, 1.0 op_sel:[0,1,0]
	v_cvt_scalef32_pk_f32_fp4 v[226:227], v196, 1.0 op_sel:[0,1,0]
	v_pk_fma_f32 v[232:233], v[26:27], v[228:229], v[232:233]
	v_pk_fma_f32 v[234:235], v[26:27], v[230:231], v[234:235]
	v_cvt_scalef32_pk_f32_fp4 v[228:229], v192, 1.0 op_sel:[1,1,0]
	v_cvt_scalef32_pk_f32_fp4 v[230:231], v196, 1.0 op_sel:[1,1,0]
	v_pk_fma_f32 v[232:233], v[12:13], v[224:225], v[232:233]
	v_pk_fma_f32 v[234:235], v[12:13], v[226:227], v[234:235]
	v_cvt_scalef32_pk_f32_fp4 v[224:225], v193, 1.0
	v_cvt_scalef32_pk_f32_fp4 v[226:227], v197, 1.0
	v_pk_fma_f32 v[232:233], v[14:15], v[228:229], v[232:233]
	v_pk_fma_f32 v[234:235], v[14:15], v[230:231], v[234:235]
	v_cvt_scalef32_pk_f32_fp4 v[228:229], v193, 1.0 op_sel:[1,0,0]
	v_cvt_scalef32_pk_f32_fp4 v[230:231], v197, 1.0 op_sel:[1,0,0]
	v_pk_fma_f32 v[232:233], v[4:5], v[224:225], v[232:233]
	v_pk_fma_f32 v[234:235], v[4:5], v[226:227], v[234:235]
	v_cvt_scalef32_pk_f32_fp4 v[224:225], v193, 1.0 op_sel:[0,1,0]
	v_cvt_scalef32_pk_f32_fp4 v[226:227], v197, 1.0 op_sel:[0,1,0]
	v_pk_fma_f32 v[232:233], v[6:7], v[228:229], v[232:233]
	v_pk_fma_f32 v[234:235], v[6:7], v[230:231], v[234:235]
	v_cvt_scalef32_pk_f32_fp4 v[228:229], v193, 1.0 op_sel:[1,1,0]
	v_cvt_scalef32_pk_f32_fp4 v[230:231], v197, 1.0 op_sel:[1,1,0]
	v_pk_fma_f32 v[232:233], v[0:1], v[224:225], v[232:233]
	v_pk_fma_f32 v[234:235], v[0:1], v[226:227], v[234:235]
	v_cvt_scalef32_pk_f32_fp4 v[224:225], v194, 1.0
	v_cvt_scalef32_pk_f32_fp4 v[226:227], v198, 1.0
	v_pk_fma_f32 v[232:233], v[2:3], v[228:229], v[232:233]
	v_pk_fma_f32 v[234:235], v[2:3], v[230:231], v[234:235]
	v_cvt_scalef32_pk_f32_fp4 v[228:229], v194, 1.0 op_sel:[1,0,0]
	v_cvt_scalef32_pk_f32_fp4 v[230:231], v198, 1.0 op_sel:[1,0,0]
	v_pk_fma_f32 v[232:233], v[28:29], v[224:225], v[232:233]
	v_pk_fma_f32 v[234:235], v[28:29], v[226:227], v[234:235]
	v_cvt_scalef32_pk_f32_fp4 v[224:225], v194, 1.0 op_sel:[0,1,0]
	v_cvt_scalef32_pk_f32_fp4 v[226:227], v198, 1.0 op_sel:[0,1,0]
	v_pk_fma_f32 v[232:233], v[30:31], v[228:229], v[232:233]
	v_pk_fma_f32 v[234:235], v[30:31], v[230:231], v[234:235]
	v_cvt_scalef32_pk_f32_fp4 v[228:229], v194, 1.0 op_sel:[1,1,0]
	v_cvt_scalef32_pk_f32_fp4 v[230:231], v198, 1.0 op_sel:[1,1,0]
	v_pk_fma_f32 v[232:233], v[16:17], v[224:225], v[232:233]
	v_pk_fma_f32 v[234:235], v[16:17], v[226:227], v[234:235]
	v_cvt_scalef32_pk_f32_fp4 v[224:225], v195, 1.0
	v_cvt_scalef32_pk_f32_fp4 v[226:227], v199, 1.0
	v_pk_fma_f32 v[232:233], v[18:19], v[228:229], v[232:233]
	v_pk_fma_f32 v[234:235], v[18:19], v[230:231], v[234:235]
	v_cvt_scalef32_pk_f32_fp4 v[228:229], v195, 1.0 op_sel:[1,0,0]
	v_cvt_scalef32_pk_f32_fp4 v[230:231], v199, 1.0 op_sel:[1,0,0]
	v_pk_fma_f32 v[232:233], v[8:9], v[224:225], v[232:233]
	v_pk_fma_f32 v[234:235], v[8:9], v[226:227], v[234:235]
	v_cvt_scalef32_pk_f32_fp4 v[224:225], v195, 1.0 op_sel:[0,1,0]
	v_cvt_scalef32_pk_f32_fp4 v[226:227], v199, 1.0 op_sel:[0,1,0]
	v_pk_fma_f32 v[232:233], v[10:11], v[228:229], v[232:233]
	v_pk_fma_f32 v[234:235], v[10:11], v[230:231], v[234:235]
	v_cvt_scalef32_pk_f32_fp4 v[228:229], v195, 1.0 op_sel:[1,1,0]
	v_cvt_scalef32_pk_f32_fp4 v[230:231], v199, 1.0 op_sel:[1,1,0]
	v_pk_fma_f32 v[232:233], v[20:21], v[224:225], v[232:233]
	v_pk_fma_f32 v[234:235], v[20:21], v[226:227], v[234:235]
	v_pk_fma_f32 v[232:233], v[22:23], v[228:229], v[232:233]
	v_pk_fma_f32 v[234:235], v[22:23], v[230:231], v[234:235]
	v_add_f32_e32 v32, v232, v233
	v_add_f32_e32 v33, v234, v235
	s_waitcnt vmcnt(12)
	v_cvt_scalef32_pk_f32_fp4 v[224:225], v200, 1.0
	v_cvt_scalef32_pk_f32_fp4 v[226:227], v204, 1.0
	v_cvt_scalef32_pk_f32_fp4 v[228:229], v200, 1.0 op_sel:[1,0,0]
	v_cvt_scalef32_pk_f32_fp4 v[230:231], v204, 1.0 op_sel:[1,0,0]
	v_pk_fma_f32 v[236:237], v[24:25], v[224:225], 0 op_sel_hi:[1,1,0]
	v_pk_fma_f32 v[238:239], v[24:25], v[226:227], 0 op_sel_hi:[1,1,0]
	v_cvt_scalef32_pk_f32_fp4 v[224:225], v200, 1.0 op_sel:[0,1,0]
	v_cvt_scalef32_pk_f32_fp4 v[226:227], v204, 1.0 op_sel:[0,1,0]
	v_pk_fma_f32 v[236:237], v[26:27], v[228:229], v[236:237]
	v_pk_fma_f32 v[238:239], v[26:27], v[230:231], v[238:239]
	v_cvt_scalef32_pk_f32_fp4 v[228:229], v200, 1.0 op_sel:[1,1,0]
	v_cvt_scalef32_pk_f32_fp4 v[230:231], v204, 1.0 op_sel:[1,1,0]
	v_pk_fma_f32 v[236:237], v[12:13], v[224:225], v[236:237]
	v_pk_fma_f32 v[238:239], v[12:13], v[226:227], v[238:239]
	v_cvt_scalef32_pk_f32_fp4 v[224:225], v201, 1.0
	v_cvt_scalef32_pk_f32_fp4 v[226:227], v205, 1.0
	v_pk_fma_f32 v[236:237], v[14:15], v[228:229], v[236:237]
	v_pk_fma_f32 v[238:239], v[14:15], v[230:231], v[238:239]
	v_cvt_scalef32_pk_f32_fp4 v[228:229], v201, 1.0 op_sel:[1,0,0]
	v_cvt_scalef32_pk_f32_fp4 v[230:231], v205, 1.0 op_sel:[1,0,0]
	v_pk_fma_f32 v[236:237], v[4:5], v[224:225], v[236:237]
	v_pk_fma_f32 v[238:239], v[4:5], v[226:227], v[238:239]
	v_cvt_scalef32_pk_f32_fp4 v[224:225], v201, 1.0 op_sel:[0,1,0]
	v_cvt_scalef32_pk_f32_fp4 v[226:227], v205, 1.0 op_sel:[0,1,0]
	v_pk_fma_f32 v[236:237], v[6:7], v[228:229], v[236:237]
	v_pk_fma_f32 v[238:239], v[6:7], v[230:231], v[238:239]
	v_cvt_scalef32_pk_f32_fp4 v[228:229], v201, 1.0 op_sel:[1,1,0]
	v_cvt_scalef32_pk_f32_fp4 v[230:231], v205, 1.0 op_sel:[1,1,0]
	v_pk_fma_f32 v[236:237], v[0:1], v[224:225], v[236:237]
	v_pk_fma_f32 v[238:239], v[0:1], v[226:227], v[238:239]
	v_cvt_scalef32_pk_f32_fp4 v[224:225], v202, 1.0
	v_cvt_scalef32_pk_f32_fp4 v[226:227], v206, 1.0
	v_pk_fma_f32 v[236:237], v[2:3], v[228:229], v[236:237]
	v_pk_fma_f32 v[238:239], v[2:3], v[230:231], v[238:239]
	v_cvt_scalef32_pk_f32_fp4 v[228:229], v202, 1.0 op_sel:[1,0,0]
	v_cvt_scalef32_pk_f32_fp4 v[230:231], v206, 1.0 op_sel:[1,0,0]
	v_pk_fma_f32 v[236:237], v[28:29], v[224:225], v[236:237]
	v_pk_fma_f32 v[238:239], v[28:29], v[226:227], v[238:239]
	v_cvt_scalef32_pk_f32_fp4 v[224:225], v202, 1.0 op_sel:[0,1,0]
	v_cvt_scalef32_pk_f32_fp4 v[226:227], v206, 1.0 op_sel:[0,1,0]
	v_pk_fma_f32 v[236:237], v[30:31], v[228:229], v[236:237]
	v_pk_fma_f32 v[238:239], v[30:31], v[230:231], v[238:239]
	v_cvt_scalef32_pk_f32_fp4 v[228:229], v202, 1.0 op_sel:[1,1,0]
	v_cvt_scalef32_pk_f32_fp4 v[230:231], v206, 1.0 op_sel:[1,1,0]
	v_pk_fma_f32 v[236:237], v[16:17], v[224:225], v[236:237]
	v_pk_fma_f32 v[238:239], v[16:17], v[226:227], v[238:239]
	v_cvt_scalef32_pk_f32_fp4 v[224:225], v203, 1.0
	v_cvt_scalef32_pk_f32_fp4 v[226:227], v207, 1.0
	v_pk_fma_f32 v[236:237], v[18:19], v[228:229], v[236:237]
	v_pk_fma_f32 v[238:239], v[18:19], v[230:231], v[238:239]
	v_cvt_scalef32_pk_f32_fp4 v[228:229], v203, 1.0 op_sel:[1,0,0]
	v_cvt_scalef32_pk_f32_fp4 v[230:231], v207, 1.0 op_sel:[1,0,0]
	v_pk_fma_f32 v[236:237], v[8:9], v[224:225], v[236:237]
	v_pk_fma_f32 v[238:239], v[8:9], v[226:227], v[238:239]
	v_cvt_scalef32_pk_f32_fp4 v[224:225], v203, 1.0 op_sel:[0,1,0]
	v_cvt_scalef32_pk_f32_fp4 v[226:227], v207, 1.0 op_sel:[0,1,0]
	v_pk_fma_f32 v[236:237], v[10:11], v[228:229], v[236:237]
	v_pk_fma_f32 v[238:239], v[10:11], v[230:231], v[238:239]
	v_cvt_scalef32_pk_f32_fp4 v[228:229], v203, 1.0 op_sel:[1,1,0]
	v_cvt_scalef32_pk_f32_fp4 v[230:231], v207, 1.0 op_sel:[1,1,0]
	v_pk_fma_f32 v[236:237], v[20:21], v[224:225], v[236:237]
	v_pk_fma_f32 v[238:239], v[20:21], v[226:227], v[238:239]
	v_pk_fma_f32 v[236:237], v[22:23], v[228:229], v[236:237]
	v_pk_fma_f32 v[238:239], v[22:23], v[230:231], v[238:239]
	v_add_f32_e32 v34, v236, v237
	v_add_f32_e32 v35, v238, v239
	v_cndmask_b32_e32 v36, v34, v32, vcc
	v_cndmask_b32_e32 v37, v32, v34, vcc
	v_cndmask_b32_e32 v38, v35, v33, vcc
	v_cndmask_b32_e32 v39, v33, v35, vcc
	ds_bpermute_b32 v37, v61, v37
	ds_bpermute_b32 v39, v61, v39
	s_waitcnt lgkmcnt(0)
	v_add_f32_e32 v36, v36, v37
	v_add_f32_e32 v38, v38, v39
	v_cndmask_b32_e64 v40, v38, v36, s[0:1]
	v_cndmask_b32_e64 v41, v36, v38, s[0:1]
	s_nop 1
	v_add_f32_dpp v40, v41, v40 row_ror:8 row_mask:0xf bank_mask:0xf
	s_nop 1
	v_add_f32_dpp v40, v40, v40 quad_perm:[1,0,3,2] row_mask:0xf bank_mask:0xf
	s_nop 1
	v_add_f32_dpp v40, v40, v40 quad_perm:[2,3,0,1] row_mask:0xf bank_mask:0xf
	s_nop 1
	v_add_f32_dpp v40, v40, v40 row_half_mirror row_mask:0xf bank_mask:0xf
	v_mul_f32_e32 v42, v40, v156
	v_fma_f32 v43, |v42|, s16, 1.0
	v_rcp_f32_e32 v43, v43
	v_cmp_gt_f32_e64 s[4:5], 0, v42
	v_mul_f32_e32 v45, v42, v42
	v_fmamk_f32 v44, v43, 0x3f07dc22, v142
	v_fmaak_f32 v44, v43, v44, 0x3f35f0e3
	v_fmaak_f32 v44, v43, v44, 0xbe11a98e
	v_fmaak_f32 v44, v43, v44, 0x3e027906
	v_mul_f32_e32 v45, 0xbf38aa3b, v45
	v_exp_f32_e32 v45, v45
	v_mul_f32_e32 v43, v43, v44
	v_mul_f32_e32 v43, v45, v43
	v_mul_f32_e32 v44, v42, v43
	v_fma_f32 v42, -v42, v43, v42
	v_cndmask_b32_e64 v42, v42, v44, s[4:5]
	v_mul_f32_e32 v158, v42, v157
	ds_bpermute_b32 v118, v138, v158
	ds_bpermute_b32 v120, v139, v158
	ds_bpermute_b32 v122, v140, v158
	ds_bpermute_b32 v124, v141, v158
	s_waitcnt vmcnt(11)
	v_cvt_scalef32_pk_f32_fp4 v[224:225], v208, 1.0
	v_cvt_scalef32_pk_f32_fp4 v[226:227], v208, 1.0 op_sel:[1,0,0]
	s_waitcnt lgkmcnt(0)
	v_cvt_scalef32_pk_f32_fp4 v[228:229], v208, 1.0 op_sel:[0,1,0]
	v_pk_fma_f32 v[112:113], v[224:225], v[118:119], v[112:113] op_sel_hi:[1,0,1]
	v_cvt_scalef32_pk_f32_fp4 v[230:231], v208, 1.0 op_sel:[1,1,0]
	v_pk_fma_f32 v[108:109], v[226:227], v[118:119], v[108:109] op_sel_hi:[1,0,1]
	v_cvt_scalef32_pk_f32_fp4 v[224:225], v209, 1.0
	v_pk_fma_f32 v[104:105], v[228:229], v[118:119], v[104:105] op_sel_hi:[1,0,1]
	v_cvt_scalef32_pk_f32_fp4 v[226:227], v209, 1.0 op_sel:[1,0,0]
	v_pk_fma_f32 v[98:99], v[230:231], v[118:119], v[98:99] op_sel_hi:[1,0,1]
	v_cvt_scalef32_pk_f32_fp4 v[228:229], v209, 1.0 op_sel:[0,1,0]
	v_pk_fma_f32 v[54:55], v[224:225], v[118:119], v[54:55] op_sel_hi:[1,0,1]
	v_cvt_scalef32_pk_f32_fp4 v[230:231], v209, 1.0 op_sel:[1,1,0]
	v_pk_fma_f32 v[58:59], v[226:227], v[118:119], v[58:59] op_sel_hi:[1,0,1]
	v_cvt_scalef32_pk_f32_fp4 v[224:225], v210, 1.0
	v_pk_fma_f32 v[52:53], v[228:229], v[118:119], v[52:53] op_sel_hi:[1,0,1]
	v_cvt_scalef32_pk_f32_fp4 v[226:227], v210, 1.0 op_sel:[1,0,0]
	v_pk_fma_f32 v[48:49], v[230:231], v[118:119], v[48:49] op_sel_hi:[1,0,1]
	v_cvt_scalef32_pk_f32_fp4 v[228:229], v210, 1.0 op_sel:[0,1,0]
	v_pk_fma_f32 v[106:107], v[224:225], v[118:119], v[106:107] op_sel_hi:[1,0,1]
	v_cvt_scalef32_pk_f32_fp4 v[230:231], v210, 1.0 op_sel:[1,1,0]
	v_pk_fma_f32 v[102:103], v[226:227], v[118:119], v[102:103] op_sel_hi:[1,0,1]
	v_cvt_scalef32_pk_f32_fp4 v[224:225], v211, 1.0
	v_pk_fma_f32 v[96:97], v[228:229], v[118:119], v[96:97] op_sel_hi:[1,0,1]
	v_cvt_scalef32_pk_f32_fp4 v[226:227], v211, 1.0 op_sel:[1,0,0]
	v_pk_fma_f32 v[56:57], v[230:231], v[118:119], v[56:57] op_sel_hi:[1,0,1]
	v_cvt_scalef32_pk_f32_fp4 v[228:229], v211, 1.0 op_sel:[0,1,0]
	v_pk_fma_f32 v[50:51], v[224:225], v[118:119], v[50:51] op_sel_hi:[1,0,1]
	v_cvt_scalef32_pk_f32_fp4 v[230:231], v211, 1.0 op_sel:[1,1,0]
	v_pk_fma_f32 v[114:115], v[226:227], v[118:119], v[114:115] op_sel_hi:[1,0,1]
	v_pk_fma_f32 v[110:111], v[228:229], v[118:119], v[110:111] op_sel_hi:[1,0,1]
	v_pk_fma_f32 v[100:101], v[230:231], v[118:119], v[100:101] op_sel_hi:[1,0,1]
	s_waitcnt vmcnt(10)
	v_cvt_scalef32_pk_f32_fp4 v[224:225], v212, 1.0
	v_cvt_scalef32_pk_f32_fp4 v[226:227], v212, 1.0 op_sel:[1,0,0]
	v_cvt_scalef32_pk_f32_fp4 v[228:229], v212, 1.0 op_sel:[0,1,0]
	v_pk_fma_f32 v[112:113], v[224:225], v[120:121], v[112:113] op_sel_hi:[1,0,1]
	v_cvt_scalef32_pk_f32_fp4 v[230:231], v212, 1.0 op_sel:[1,1,0]
	v_pk_fma_f32 v[108:109], v[226:227], v[120:121], v[108:109] op_sel_hi:[1,0,1]
	v_cvt_scalef32_pk_f32_fp4 v[224:225], v213, 1.0
	v_pk_fma_f32 v[104:105], v[228:229], v[120:121], v[104:105] op_sel_hi:[1,0,1]
	v_cvt_scalef32_pk_f32_fp4 v[226:227], v213, 1.0 op_sel:[1,0,0]
	v_pk_fma_f32 v[98:99], v[230:231], v[120:121], v[98:99] op_sel_hi:[1,0,1]
	v_cvt_scalef32_pk_f32_fp4 v[228:229], v213, 1.0 op_sel:[0,1,0]
	v_pk_fma_f32 v[54:55], v[224:225], v[120:121], v[54:55] op_sel_hi:[1,0,1]
	v_cvt_scalef32_pk_f32_fp4 v[230:231], v213, 1.0 op_sel:[1,1,0]
	v_pk_fma_f32 v[58:59], v[226:227], v[120:121], v[58:59] op_sel_hi:[1,0,1]
	v_cvt_scalef32_pk_f32_fp4 v[224:225], v214, 1.0
	v_pk_fma_f32 v[52:53], v[228:229], v[120:121], v[52:53] op_sel_hi:[1,0,1]
	v_cvt_scalef32_pk_f32_fp4 v[226:227], v214, 1.0 op_sel:[1,0,0]
	v_pk_fma_f32 v[48:49], v[230:231], v[120:121], v[48:49] op_sel_hi:[1,0,1]
	v_cvt_scalef32_pk_f32_fp4 v[228:229], v214, 1.0 op_sel:[0,1,0]
	v_pk_fma_f32 v[106:107], v[224:225], v[120:121], v[106:107] op_sel_hi:[1,0,1]
	v_cvt_scalef32_pk_f32_fp4 v[230:231], v214, 1.0 op_sel:[1,1,0]
	v_pk_fma_f32 v[102:103], v[226:227], v[120:121], v[102:103] op_sel_hi:[1,0,1]
	v_cvt_scalef32_pk_f32_fp4 v[224:225], v215, 1.0
	v_pk_fma_f32 v[96:97], v[228:229], v[120:121], v[96:97] op_sel_hi:[1,0,1]
	v_cvt_scalef32_pk_f32_fp4 v[226:227], v215, 1.0 op_sel:[1,0,0]
	v_pk_fma_f32 v[56:57], v[230:231], v[120:121], v[56:57] op_sel_hi:[1,0,1]
	v_cvt_scalef32_pk_f32_fp4 v[228:229], v215, 1.0 op_sel:[0,1,0]
	v_pk_fma_f32 v[50:51], v[224:225], v[120:121], v[50:51] op_sel_hi:[1,0,1]
	v_cvt_scalef32_pk_f32_fp4 v[230:231], v215, 1.0 op_sel:[1,1,0]
	v_pk_fma_f32 v[114:115], v[226:227], v[120:121], v[114:115] op_sel_hi:[1,0,1]
	v_pk_fma_f32 v[110:111], v[228:229], v[120:121], v[110:111] op_sel_hi:[1,0,1]
	v_pk_fma_f32 v[100:101], v[230:231], v[120:121], v[100:101] op_sel_hi:[1,0,1]
	s_waitcnt vmcnt(9)
	v_cvt_scalef32_pk_f32_fp4 v[224:225], v216, 1.0
	v_cvt_scalef32_pk_f32_fp4 v[226:227], v216, 1.0 op_sel:[1,0,0]
	v_cvt_scalef32_pk_f32_fp4 v[228:229], v216, 1.0 op_sel:[0,1,0]
	v_pk_fma_f32 v[112:113], v[224:225], v[122:123], v[112:113] op_sel_hi:[1,0,1]
	v_cvt_scalef32_pk_f32_fp4 v[230:231], v216, 1.0 op_sel:[1,1,0]
	v_pk_fma_f32 v[108:109], v[226:227], v[122:123], v[108:109] op_sel_hi:[1,0,1]
	v_cvt_scalef32_pk_f32_fp4 v[224:225], v217, 1.0
	v_pk_fma_f32 v[104:105], v[228:229], v[122:123], v[104:105] op_sel_hi:[1,0,1]
	v_cvt_scalef32_pk_f32_fp4 v[226:227], v217, 1.0 op_sel:[1,0,0]
	v_pk_fma_f32 v[98:99], v[230:231], v[122:123], v[98:99] op_sel_hi:[1,0,1]
	v_cvt_scalef32_pk_f32_fp4 v[228:229], v217, 1.0 op_sel:[0,1,0]
	v_pk_fma_f32 v[54:55], v[224:225], v[122:123], v[54:55] op_sel_hi:[1,0,1]
	v_cvt_scalef32_pk_f32_fp4 v[230:231], v217, 1.0 op_sel:[1,1,0]
	v_pk_fma_f32 v[58:59], v[226:227], v[122:123], v[58:59] op_sel_hi:[1,0,1]
	v_cvt_scalef32_pk_f32_fp4 v[224:225], v218, 1.0
	v_pk_fma_f32 v[52:53], v[228:229], v[122:123], v[52:53] op_sel_hi:[1,0,1]
	v_cvt_scalef32_pk_f32_fp4 v[226:227], v218, 1.0 op_sel:[1,0,0]
	v_pk_fma_f32 v[48:49], v[230:231], v[122:123], v[48:49] op_sel_hi:[1,0,1]
	v_cvt_scalef32_pk_f32_fp4 v[228:229], v218, 1.0 op_sel:[0,1,0]
	v_pk_fma_f32 v[106:107], v[224:225], v[122:123], v[106:107] op_sel_hi:[1,0,1]
	v_cvt_scalef32_pk_f32_fp4 v[230:231], v218, 1.0 op_sel:[1,1,0]
	v_pk_fma_f32 v[102:103], v[226:227], v[122:123], v[102:103] op_sel_hi:[1,0,1]
	v_cvt_scalef32_pk_f32_fp4 v[224:225], v219, 1.0
	v_pk_fma_f32 v[96:97], v[228:229], v[122:123], v[96:97] op_sel_hi:[1,0,1]
	v_cvt_scalef32_pk_f32_fp4 v[226:227], v219, 1.0 op_sel:[1,0,0]
	v_pk_fma_f32 v[56:57], v[230:231], v[122:123], v[56:57] op_sel_hi:[1,0,1]
	v_cvt_scalef32_pk_f32_fp4 v[228:229], v219, 1.0 op_sel:[0,1,0]
	v_pk_fma_f32 v[50:51], v[224:225], v[122:123], v[50:51] op_sel_hi:[1,0,1]
	v_cvt_scalef32_pk_f32_fp4 v[230:231], v219, 1.0 op_sel:[1,1,0]
	v_pk_fma_f32 v[114:115], v[226:227], v[122:123], v[114:115] op_sel_hi:[1,0,1]
	v_pk_fma_f32 v[110:111], v[228:229], v[122:123], v[110:111] op_sel_hi:[1,0,1]
	v_pk_fma_f32 v[100:101], v[230:231], v[122:123], v[100:101] op_sel_hi:[1,0,1]
	s_waitcnt vmcnt(8)
	v_cvt_scalef32_pk_f32_fp4 v[224:225], v220, 1.0
	v_cvt_scalef32_pk_f32_fp4 v[226:227], v220, 1.0 op_sel:[1,0,0]
	v_cvt_scalef32_pk_f32_fp4 v[228:229], v220, 1.0 op_sel:[0,1,0]
	v_pk_fma_f32 v[112:113], v[224:225], v[124:125], v[112:113] op_sel_hi:[1,0,1]
	v_cvt_scalef32_pk_f32_fp4 v[230:231], v220, 1.0 op_sel:[1,1,0]
	v_pk_fma_f32 v[108:109], v[226:227], v[124:125], v[108:109] op_sel_hi:[1,0,1]
	v_cvt_scalef32_pk_f32_fp4 v[224:225], v221, 1.0
	v_pk_fma_f32 v[104:105], v[228:229], v[124:125], v[104:105] op_sel_hi:[1,0,1]
	v_cvt_scalef32_pk_f32_fp4 v[226:227], v221, 1.0 op_sel:[1,0,0]
	v_pk_fma_f32 v[98:99], v[230:231], v[124:125], v[98:99] op_sel_hi:[1,0,1]
	v_cvt_scalef32_pk_f32_fp4 v[228:229], v221, 1.0 op_sel:[0,1,0]
	v_pk_fma_f32 v[54:55], v[224:225], v[124:125], v[54:55] op_sel_hi:[1,0,1]
	v_cvt_scalef32_pk_f32_fp4 v[230:231], v221, 1.0 op_sel:[1,1,0]
	v_pk_fma_f32 v[58:59], v[226:227], v[124:125], v[58:59] op_sel_hi:[1,0,1]
	v_cvt_scalef32_pk_f32_fp4 v[224:225], v222, 1.0
	v_pk_fma_f32 v[52:53], v[228:229], v[124:125], v[52:53] op_sel_hi:[1,0,1]
	v_cvt_scalef32_pk_f32_fp4 v[226:227], v222, 1.0 op_sel:[1,0,0]
	v_pk_fma_f32 v[48:49], v[230:231], v[124:125], v[48:49] op_sel_hi:[1,0,1]
	v_cvt_scalef32_pk_f32_fp4 v[228:229], v222, 1.0 op_sel:[0,1,0]
	v_pk_fma_f32 v[106:107], v[224:225], v[124:125], v[106:107] op_sel_hi:[1,0,1]
	v_cvt_scalef32_pk_f32_fp4 v[230:231], v222, 1.0 op_sel:[1,1,0]
	v_pk_fma_f32 v[102:103], v[226:227], v[124:125], v[102:103] op_sel_hi:[1,0,1]
	v_cvt_scalef32_pk_f32_fp4 v[224:225], v223, 1.0
	v_pk_fma_f32 v[96:97], v[228:229], v[124:125], v[96:97] op_sel_hi:[1,0,1]
	v_cvt_scalef32_pk_f32_fp4 v[226:227], v223, 1.0 op_sel:[1,0,0]
	v_pk_fma_f32 v[56:57], v[230:231], v[124:125], v[56:57] op_sel_hi:[1,0,1]
	v_cvt_scalef32_pk_f32_fp4 v[228:229], v223, 1.0 op_sel:[0,1,0]
	v_pk_fma_f32 v[50:51], v[224:225], v[124:125], v[50:51] op_sel_hi:[1,0,1]
	v_cvt_scalef32_pk_f32_fp4 v[230:231], v223, 1.0 op_sel:[1,1,0]
	v_pk_fma_f32 v[114:115], v[226:227], v[124:125], v[114:115] op_sel_hi:[1,0,1]
	v_pk_fma_f32 v[110:111], v[228:229], v[124:125], v[110:111] op_sel_hi:[1,0,1]
	v_pk_fma_f32 v[100:101], v[230:231], v[124:125], v[100:101] op_sel_hi:[1,0,1]
	s_add_u32 s19, s19, 2
	s_cmp_lt_u32 s19, 14
	s_cbranch_scc1 .Lxg_loop_p12
	s_waitcnt lgkmcnt(0)
	v_lshl_add_u32 v250, v240, 9, v241
	v_lshl_add_u32 v251, v242, 9, v241
	v_lshl_add_u32 v252, v246, 9, v241
	v_lshl_add_u32 v253, v248, 9, v241
	global_load_dwordx4 v[192:195], v250, s[98:99]
	global_load_dwordx4 v[196:199], v251, s[98:99]
	global_load_dwordx4 v[200:203], v252, s[98:99]
	global_load_dwordx4 v[204:207], v253, s[98:99]
	global_load_dwordx4 v[208:211], v250, s[100:101]
	global_load_dwordx4 v[212:215], v251, s[100:101]
	global_load_dwordx4 v[216:219], v252, s[100:101]
	global_load_dwordx4 v[220:223], v253, s[100:101]
	s_movk_i32 s20, 0xc0
	v_lshl_add_u32 v130, v137, 2, s20
	ds_bpermute_b32 v156, v130, v147
	ds_bpermute_b32 v157, v130, v149
	s_waitcnt vmcnt(14)
	v_cvt_scalef32_pk_f32_fp4 v[224:225], v160, 1.0
	v_cvt_scalef32_pk_f32_fp4 v[226:227], v164, 1.0
	v_cvt_scalef32_pk_f32_fp4 v[228:229], v160, 1.0 op_sel:[1,0,0]
	v_cvt_scalef32_pk_f32_fp4 v[230:231], v164, 1.0 op_sel:[1,0,0]
	v_pk_fma_f32 v[232:233], v[24:25], v[224:225], 0 op_sel_hi:[1,1,0]
	v_pk_fma_f32 v[234:235], v[24:25], v[226:227], 0 op_sel_hi:[1,1,0]
	v_cvt_scalef32_pk_f32_fp4 v[224:225], v160, 1.0 op_sel:[0,1,0]
	v_cvt_scalef32_pk_f32_fp4 v[226:227], v164, 1.0 op_sel:[0,1,0]
	v_pk_fma_f32 v[232:233], v[26:27], v[228:229], v[232:233]
	v_pk_fma_f32 v[234:235], v[26:27], v[230:231], v[234:235]
	v_cvt_scalef32_pk_f32_fp4 v[228:229], v160, 1.0 op_sel:[1,1,0]
	v_cvt_scalef32_pk_f32_fp4 v[230:231], v164, 1.0 op_sel:[1,1,0]
	v_pk_fma_f32 v[232:233], v[12:13], v[224:225], v[232:233]
	v_pk_fma_f32 v[234:235], v[12:13], v[226:227], v[234:235]
	v_cvt_scalef32_pk_f32_fp4 v[224:225], v161, 1.0
	v_cvt_scalef32_pk_f32_fp4 v[226:227], v165, 1.0
	v_pk_fma_f32 v[232:233], v[14:15], v[228:229], v[232:233]
	v_pk_fma_f32 v[234:235], v[14:15], v[230:231], v[234:235]
	v_cvt_scalef32_pk_f32_fp4 v[228:229], v161, 1.0 op_sel:[1,0,0]
	v_cvt_scalef32_pk_f32_fp4 v[230:231], v165, 1.0 op_sel:[1,0,0]
	v_pk_fma_f32 v[232:233], v[4:5], v[224:225], v[232:233]
	v_pk_fma_f32 v[234:235], v[4:5], v[226:227], v[234:235]
	v_cvt_scalef32_pk_f32_fp4 v[224:225], v161, 1.0 op_sel:[0,1,0]
	v_cvt_scalef32_pk_f32_fp4 v[226:227], v165, 1.0 op_sel:[0,1,0]
	v_pk_fma_f32 v[232:233], v[6:7], v[228:229], v[232:233]
	v_pk_fma_f32 v[234:235], v[6:7], v[230:231], v[234:235]
	v_cvt_scalef32_pk_f32_fp4 v[228:229], v161, 1.0 op_sel:[1,1,0]
	v_cvt_scalef32_pk_f32_fp4 v[230:231], v165, 1.0 op_sel:[1,1,0]
	v_pk_fma_f32 v[232:233], v[0:1], v[224:225], v[232:233]
	v_pk_fma_f32 v[234:235], v[0:1], v[226:227], v[234:235]
	v_cvt_scalef32_pk_f32_fp4 v[224:225], v162, 1.0
	v_cvt_scalef32_pk_f32_fp4 v[226:227], v166, 1.0
	v_pk_fma_f32 v[232:233], v[2:3], v[228:229], v[232:233]
	v_pk_fma_f32 v[234:235], v[2:3], v[230:231], v[234:235]
	v_cvt_scalef32_pk_f32_fp4 v[228:229], v162, 1.0 op_sel:[1,0,0]
	v_cvt_scalef32_pk_f32_fp4 v[230:231], v166, 1.0 op_sel:[1,0,0]
	v_pk_fma_f32 v[232:233], v[28:29], v[224:225], v[232:233]
	v_pk_fma_f32 v[234:235], v[28:29], v[226:227], v[234:235]
	v_cvt_scalef32_pk_f32_fp4 v[224:225], v162, 1.0 op_sel:[0,1,0]
	v_cvt_scalef32_pk_f32_fp4 v[226:227], v166, 1.0 op_sel:[0,1,0]
	v_pk_fma_f32 v[232:233], v[30:31], v[228:229], v[232:233]
	v_pk_fma_f32 v[234:235], v[30:31], v[230:231], v[234:235]
	v_cvt_scalef32_pk_f32_fp4 v[228:229], v162, 1.0 op_sel:[1,1,0]
	v_cvt_scalef32_pk_f32_fp4 v[230:231], v166, 1.0 op_sel:[1,1,0]
	v_pk_fma_f32 v[232:233], v[16:17], v[224:225], v[232:233]
	v_pk_fma_f32 v[234:235], v[16:17], v[226:227], v[234:235]
	v_cvt_scalef32_pk_f32_fp4 v[224:225], v163, 1.0
	v_cvt_scalef32_pk_f32_fp4 v[226:227], v167, 1.0
	v_pk_fma_f32 v[232:233], v[18:19], v[228:229], v[232:233]
	v_pk_fma_f32 v[234:235], v[18:19], v[230:231], v[234:235]
	v_cvt_scalef32_pk_f32_fp4 v[228:229], v163, 1.0 op_sel:[1,0,0]
	v_cvt_scalef32_pk_f32_fp4 v[230:231], v167, 1.0 op_sel:[1,0,0]
	v_pk_fma_f32 v[232:233], v[8:9], v[224:225], v[232:233]
	v_pk_fma_f32 v[234:235], v[8:9], v[226:227], v[234:235]
	v_cvt_scalef32_pk_f32_fp4 v[224:225], v163, 1.0 op_sel:[0,1,0]
	v_cvt_scalef32_pk_f32_fp4 v[226:227], v167, 1.0 op_sel:[0,1,0]
	v_pk_fma_f32 v[232:233], v[10:11], v[228:229], v[232:233]
	v_pk_fma_f32 v[234:235], v[10:11], v[230:231], v[234:235]
	v_cvt_scalef32_pk_f32_fp4 v[228:229], v163, 1.0 op_sel:[1,1,0]
	v_cvt_scalef32_pk_f32_fp4 v[230:231], v167, 1.0 op_sel:[1,1,0]
	v_pk_fma_f32 v[232:233], v[20:21], v[224:225], v[232:233]
	v_pk_fma_f32 v[234:235], v[20:21], v[226:227], v[234:235]
	v_pk_fma_f32 v[232:233], v[22:23], v[228:229], v[232:233]
	v_pk_fma_f32 v[234:235], v[22:23], v[230:231], v[234:235]
	v_add_f32_e32 v32, v232, v233
	v_add_f32_e32 v33, v234, v235
	s_waitcnt vmcnt(12)
	v_cvt_scalef32_pk_f32_fp4 v[224:225], v168, 1.0
	v_cvt_scalef32_pk_f32_fp4 v[226:227], v172, 1.0
	v_cvt_scalef32_pk_f32_fp4 v[228:229], v168, 1.0 op_sel:[1,0,0]
	v_cvt_scalef32_pk_f32_fp4 v[230:231], v172, 1.0 op_sel:[1,0,0]
	v_pk_fma_f32 v[236:237], v[24:25], v[224:225], 0 op_sel_hi:[1,1,0]
	v_pk_fma_f32 v[238:239], v[24:25], v[226:227], 0 op_sel_hi:[1,1,0]
	v_cvt_scalef32_pk_f32_fp4 v[224:225], v168, 1.0 op_sel:[0,1,0]
	v_cvt_scalef32_pk_f32_fp4 v[226:227], v172, 1.0 op_sel:[0,1,0]
	v_pk_fma_f32 v[236:237], v[26:27], v[228:229], v[236:237]
	v_pk_fma_f32 v[238:239], v[26:27], v[230:231], v[238:239]
	v_cvt_scalef32_pk_f32_fp4 v[228:229], v168, 1.0 op_sel:[1,1,0]
	v_cvt_scalef32_pk_f32_fp4 v[230:231], v172, 1.0 op_sel:[1,1,0]
	v_pk_fma_f32 v[236:237], v[12:13], v[224:225], v[236:237]
	v_pk_fma_f32 v[238:239], v[12:13], v[226:227], v[238:239]
	v_cvt_scalef32_pk_f32_fp4 v[224:225], v169, 1.0
	v_cvt_scalef32_pk_f32_fp4 v[226:227], v173, 1.0
	v_pk_fma_f32 v[236:237], v[14:15], v[228:229], v[236:237]
	v_pk_fma_f32 v[238:239], v[14:15], v[230:231], v[238:239]
	v_cvt_scalef32_pk_f32_fp4 v[228:229], v169, 1.0 op_sel:[1,0,0]
	v_cvt_scalef32_pk_f32_fp4 v[230:231], v173, 1.0 op_sel:[1,0,0]
	v_pk_fma_f32 v[236:237], v[4:5], v[224:225], v[236:237]
	v_pk_fma_f32 v[238:239], v[4:5], v[226:227], v[238:239]
	v_cvt_scalef32_pk_f32_fp4 v[224:225], v169, 1.0 op_sel:[0,1,0]
	v_cvt_scalef32_pk_f32_fp4 v[226:227], v173, 1.0 op_sel:[0,1,0]
	v_pk_fma_f32 v[236:237], v[6:7], v[228:229], v[236:237]
	v_pk_fma_f32 v[238:239], v[6:7], v[230:231], v[238:239]
	v_cvt_scalef32_pk_f32_fp4 v[228:229], v169, 1.0 op_sel:[1,1,0]
	v_cvt_scalef32_pk_f32_fp4 v[230:231], v173, 1.0 op_sel:[1,1,0]
	v_pk_fma_f32 v[236:237], v[0:1], v[224:225], v[236:237]
	v_pk_fma_f32 v[238:239], v[0:1], v[226:227], v[238:239]
	v_cvt_scalef32_pk_f32_fp4 v[224:225], v170, 1.0
	v_cvt_scalef32_pk_f32_fp4 v[226:227], v174, 1.0
	v_pk_fma_f32 v[236:237], v[2:3], v[228:229], v[236:237]
	v_pk_fma_f32 v[238:239], v[2:3], v[230:231], v[238:239]
	v_cvt_scalef32_pk_f32_fp4 v[228:229], v170, 1.0 op_sel:[1,0,0]
	v_cvt_scalef32_pk_f32_fp4 v[230:231], v174, 1.0 op_sel:[1,0,0]
	v_pk_fma_f32 v[236:237], v[28:29], v[224:225], v[236:237]
	v_pk_fma_f32 v[238:239], v[28:29], v[226:227], v[238:239]
	v_cvt_scalef32_pk_f32_fp4 v[224:225], v170, 1.0 op_sel:[0,1,0]
	v_cvt_scalef32_pk_f32_fp4 v[226:227], v174, 1.0 op_sel:[0,1,0]
	v_pk_fma_f32 v[236:237], v[30:31], v[228:229], v[236:237]
	v_pk_fma_f32 v[238:239], v[30:31], v[230:231], v[238:239]
	v_cvt_scalef32_pk_f32_fp4 v[228:229], v170, 1.0 op_sel:[1,1,0]
	v_cvt_scalef32_pk_f32_fp4 v[230:231], v174, 1.0 op_sel:[1,1,0]
	v_pk_fma_f32 v[236:237], v[16:17], v[224:225], v[236:237]
	v_pk_fma_f32 v[238:239], v[16:17], v[226:227], v[238:239]
	v_cvt_scalef32_pk_f32_fp4 v[224:225], v171, 1.0
	v_cvt_scalef32_pk_f32_fp4 v[226:227], v175, 1.0
	v_pk_fma_f32 v[236:237], v[18:19], v[228:229], v[236:237]
	v_pk_fma_f32 v[238:239], v[18:19], v[230:231], v[238:239]
	v_cvt_scalef32_pk_f32_fp4 v[228:229], v171, 1.0 op_sel:[1,0,0]
	v_cvt_scalef32_pk_f32_fp4 v[230:231], v175, 1.0 op_sel:[1,0,0]
	v_pk_fma_f32 v[236:237], v[8:9], v[224:225], v[236:237]
	v_pk_fma_f32 v[238:239], v[8:9], v[226:227], v[238:239]
	v_cvt_scalef32_pk_f32_fp4 v[224:225], v171, 1.0 op_sel:[0,1,0]
	v_cvt_scalef32_pk_f32_fp4 v[226:227], v175, 1.0 op_sel:[0,1,0]
	v_pk_fma_f32 v[236:237], v[10:11], v[228:229], v[236:237]
	v_pk_fma_f32 v[238:239], v[10:11], v[230:231], v[238:239]
	v_cvt_scalef32_pk_f32_fp4 v[228:229], v171, 1.0 op_sel:[1,1,0]
	v_cvt_scalef32_pk_f32_fp4 v[230:231], v175, 1.0 op_sel:[1,1,0]
	v_pk_fma_f32 v[236:237], v[20:21], v[224:225], v[236:237]
	v_pk_fma_f32 v[238:239], v[20:21], v[226:227], v[238:239]
	v_pk_fma_f32 v[236:237], v[22:23], v[228:229], v[236:237]
	v_pk_fma_f32 v[238:239], v[22:23], v[230:231], v[238:239]
	v_add_f32_e32 v34, v236, v237
	v_add_f32_e32 v35, v238, v239
	v_cndmask_b32_e32 v36, v34, v32, vcc
	v_cndmask_b32_e32 v37, v32, v34, vcc
	v_cndmask_b32_e32 v38, v35, v33, vcc
	v_cndmask_b32_e32 v39, v33, v35, vcc
	ds_bpermute_b32 v37, v61, v37
	ds_bpermute_b32 v39, v61, v39
	s_waitcnt lgkmcnt(0)
	v_add_f32_e32 v36, v36, v37
	v_add_f32_e32 v38, v38, v39
	v_cndmask_b32_e64 v40, v38, v36, s[0:1]
	v_cndmask_b32_e64 v41, v36, v38, s[0:1]
	s_nop 1
	v_add_f32_dpp v40, v41, v40 row_ror:8 row_mask:0xf bank_mask:0xf
	s_nop 1
	v_add_f32_dpp v40, v40, v40 quad_perm:[1,0,3,2] row_mask:0xf bank_mask:0xf
	s_nop 1
	v_add_f32_dpp v40, v40, v40 quad_perm:[2,3,0,1] row_mask:0xf bank_mask:0xf
	s_nop 1
	v_add_f32_dpp v40, v40, v40 row_half_mirror row_mask:0xf bank_mask:0xf
	v_mul_f32_e32 v42, v40, v156
	v_fma_f32 v43, |v42|, s16, 1.0
	v_rcp_f32_e32 v43, v43
	v_cmp_gt_f32_e64 s[4:5], 0, v42
	v_mul_f32_e32 v45, v42, v42
	v_fmamk_f32 v44, v43, 0x3f07dc22, v142
	v_fmaak_f32 v44, v43, v44, 0x3f35f0e3
	v_fmaak_f32 v44, v43, v44, 0xbe11a98e
	v_fmaak_f32 v44, v43, v44, 0x3e027906
	v_mul_f32_e32 v45, 0xbf38aa3b, v45
	v_exp_f32_e32 v45, v45
	v_mul_f32_e32 v43, v43, v44
	v_mul_f32_e32 v43, v45, v43
	v_mul_f32_e32 v44, v42, v43
	v_fma_f32 v42, -v42, v43, v42
	v_cndmask_b32_e64 v42, v42, v44, s[4:5]
	v_mul_f32_e32 v158, v42, v157
	ds_bpermute_b32 v118, v138, v158
	ds_bpermute_b32 v120, v139, v158
	ds_bpermute_b32 v122, v140, v158
	ds_bpermute_b32 v124, v141, v158
	s_waitcnt vmcnt(11)
	v_cvt_scalef32_pk_f32_fp4 v[224:225], v176, 1.0
	v_cvt_scalef32_pk_f32_fp4 v[226:227], v176, 1.0 op_sel:[1,0,0]
	s_waitcnt lgkmcnt(0)
	v_cvt_scalef32_pk_f32_fp4 v[228:229], v176, 1.0 op_sel:[0,1,0]
	v_pk_fma_f32 v[112:113], v[224:225], v[118:119], v[112:113] op_sel_hi:[1,0,1]
	v_cvt_scalef32_pk_f32_fp4 v[230:231], v176, 1.0 op_sel:[1,1,0]
	v_pk_fma_f32 v[108:109], v[226:227], v[118:119], v[108:109] op_sel_hi:[1,0,1]
	v_cvt_scalef32_pk_f32_fp4 v[224:225], v177, 1.0
	v_pk_fma_f32 v[104:105], v[228:229], v[118:119], v[104:105] op_sel_hi:[1,0,1]
	v_cvt_scalef32_pk_f32_fp4 v[226:227], v177, 1.0 op_sel:[1,0,0]
	v_pk_fma_f32 v[98:99], v[230:231], v[118:119], v[98:99] op_sel_hi:[1,0,1]
	v_cvt_scalef32_pk_f32_fp4 v[228:229], v177, 1.0 op_sel:[0,1,0]
	v_pk_fma_f32 v[54:55], v[224:225], v[118:119], v[54:55] op_sel_hi:[1,0,1]
	v_cvt_scalef32_pk_f32_fp4 v[230:231], v177, 1.0 op_sel:[1,1,0]
	v_pk_fma_f32 v[58:59], v[226:227], v[118:119], v[58:59] op_sel_hi:[1,0,1]
	v_cvt_scalef32_pk_f32_fp4 v[224:225], v178, 1.0
	v_pk_fma_f32 v[52:53], v[228:229], v[118:119], v[52:53] op_sel_hi:[1,0,1]
	v_cvt_scalef32_pk_f32_fp4 v[226:227], v178, 1.0 op_sel:[1,0,0]
	v_pk_fma_f32 v[48:49], v[230:231], v[118:119], v[48:49] op_sel_hi:[1,0,1]
	v_cvt_scalef32_pk_f32_fp4 v[228:229], v178, 1.0 op_sel:[0,1,0]
	v_pk_fma_f32 v[106:107], v[224:225], v[118:119], v[106:107] op_sel_hi:[1,0,1]
	v_cvt_scalef32_pk_f32_fp4 v[230:231], v178, 1.0 op_sel:[1,1,0]
	v_pk_fma_f32 v[102:103], v[226:227], v[118:119], v[102:103] op_sel_hi:[1,0,1]
	v_cvt_scalef32_pk_f32_fp4 v[224:225], v179, 1.0
	v_pk_fma_f32 v[96:97], v[228:229], v[118:119], v[96:97] op_sel_hi:[1,0,1]
	v_cvt_scalef32_pk_f32_fp4 v[226:227], v179, 1.0 op_sel:[1,0,0]
	v_pk_fma_f32 v[56:57], v[230:231], v[118:119], v[56:57] op_sel_hi:[1,0,1]
	v_cvt_scalef32_pk_f32_fp4 v[228:229], v179, 1.0 op_sel:[0,1,0]
	v_pk_fma_f32 v[50:51], v[224:225], v[118:119], v[50:51] op_sel_hi:[1,0,1]
	v_cvt_scalef32_pk_f32_fp4 v[230:231], v179, 1.0 op_sel:[1,1,0]
	v_pk_fma_f32 v[114:115], v[226:227], v[118:119], v[114:115] op_sel_hi:[1,0,1]
	v_pk_fma_f32 v[110:111], v[228:229], v[118:119], v[110:111] op_sel_hi:[1,0,1]
	v_pk_fma_f32 v[100:101], v[230:231], v[118:119], v[100:101] op_sel_hi:[1,0,1]
	s_waitcnt vmcnt(10)
	v_cvt_scalef32_pk_f32_fp4 v[224:225], v180, 1.0
	v_cvt_scalef32_pk_f32_fp4 v[226:227], v180, 1.0 op_sel:[1,0,0]
	v_cvt_scalef32_pk_f32_fp4 v[228:229], v180, 1.0 op_sel:[0,1,0]
	v_pk_fma_f32 v[112:113], v[224:225], v[120:121], v[112:113] op_sel_hi:[1,0,1]
	v_cvt_scalef32_pk_f32_fp4 v[230:231], v180, 1.0 op_sel:[1,1,0]
	v_pk_fma_f32 v[108:109], v[226:227], v[120:121], v[108:109] op_sel_hi:[1,0,1]
	v_cvt_scalef32_pk_f32_fp4 v[224:225], v181, 1.0
	v_pk_fma_f32 v[104:105], v[228:229], v[120:121], v[104:105] op_sel_hi:[1,0,1]
	v_cvt_scalef32_pk_f32_fp4 v[226:227], v181, 1.0 op_sel:[1,0,0]
	v_pk_fma_f32 v[98:99], v[230:231], v[120:121], v[98:99] op_sel_hi:[1,0,1]
	v_cvt_scalef32_pk_f32_fp4 v[228:229], v181, 1.0 op_sel:[0,1,0]
	v_pk_fma_f32 v[54:55], v[224:225], v[120:121], v[54:55] op_sel_hi:[1,0,1]
	v_cvt_scalef32_pk_f32_fp4 v[230:231], v181, 1.0 op_sel:[1,1,0]
	v_pk_fma_f32 v[58:59], v[226:227], v[120:121], v[58:59] op_sel_hi:[1,0,1]
	v_cvt_scalef32_pk_f32_fp4 v[224:225], v182, 1.0
	v_pk_fma_f32 v[52:53], v[228:229], v[120:121], v[52:53] op_sel_hi:[1,0,1]
	v_cvt_scalef32_pk_f32_fp4 v[226:227], v182, 1.0 op_sel:[1,0,0]
	v_pk_fma_f32 v[48:49], v[230:231], v[120:121], v[48:49] op_sel_hi:[1,0,1]
	v_cvt_scalef32_pk_f32_fp4 v[228:229], v182, 1.0 op_sel:[0,1,0]
	v_pk_fma_f32 v[106:107], v[224:225], v[120:121], v[106:107] op_sel_hi:[1,0,1]
	v_cvt_scalef32_pk_f32_fp4 v[230:231], v182, 1.0 op_sel:[1,1,0]
	v_pk_fma_f32 v[102:103], v[226:227], v[120:121], v[102:103] op_sel_hi:[1,0,1]
	v_cvt_scalef32_pk_f32_fp4 v[224:225], v183, 1.0
	v_pk_fma_f32 v[96:97], v[228:229], v[120:121], v[96:97] op_sel_hi:[1,0,1]
	v_cvt_scalef32_pk_f32_fp4 v[226:227], v183, 1.0 op_sel:[1,0,0]
	v_pk_fma_f32 v[56:57], v[230:231], v[120:121], v[56:57] op_sel_hi:[1,0,1]
	v_cvt_scalef32_pk_f32_fp4 v[228:229], v183, 1.0 op_sel:[0,1,0]
	v_pk_fma_f32 v[50:51], v[224:225], v[120:121], v[50:51] op_sel_hi:[1,0,1]
	v_cvt_scalef32_pk_f32_fp4 v[230:231], v183, 1.0 op_sel:[1,1,0]
	v_pk_fma_f32 v[114:115], v[226:227], v[120:121], v[114:115] op_sel_hi:[1,0,1]
	v_pk_fma_f32 v[110:111], v[228:229], v[120:121], v[110:111] op_sel_hi:[1,0,1]
	v_pk_fma_f32 v[100:101], v[230:231], v[120:121], v[100:101] op_sel_hi:[1,0,1]
	s_waitcnt vmcnt(9)
	v_cvt_scalef32_pk_f32_fp4 v[224:225], v184, 1.0
	v_cvt_scalef32_pk_f32_fp4 v[226:227], v184, 1.0 op_sel:[1,0,0]
	v_cvt_scalef32_pk_f32_fp4 v[228:229], v184, 1.0 op_sel:[0,1,0]
	v_pk_fma_f32 v[112:113], v[224:225], v[122:123], v[112:113] op_sel_hi:[1,0,1]
	v_cvt_scalef32_pk_f32_fp4 v[230:231], v184, 1.0 op_sel:[1,1,0]
	v_pk_fma_f32 v[108:109], v[226:227], v[122:123], v[108:109] op_sel_hi:[1,0,1]
	v_cvt_scalef32_pk_f32_fp4 v[224:225], v185, 1.0
	v_pk_fma_f32 v[104:105], v[228:229], v[122:123], v[104:105] op_sel_hi:[1,0,1]
	v_cvt_scalef32_pk_f32_fp4 v[226:227], v185, 1.0 op_sel:[1,0,0]
	v_pk_fma_f32 v[98:99], v[230:231], v[122:123], v[98:99] op_sel_hi:[1,0,1]
	v_cvt_scalef32_pk_f32_fp4 v[228:229], v185, 1.0 op_sel:[0,1,0]
	v_pk_fma_f32 v[54:55], v[224:225], v[122:123], v[54:55] op_sel_hi:[1,0,1]
	v_cvt_scalef32_pk_f32_fp4 v[230:231], v185, 1.0 op_sel:[1,1,0]
	v_pk_fma_f32 v[58:59], v[226:227], v[122:123], v[58:59] op_sel_hi:[1,0,1]
	v_cvt_scalef32_pk_f32_fp4 v[224:225], v186, 1.0
	v_pk_fma_f32 v[52:53], v[228:229], v[122:123], v[52:53] op_sel_hi:[1,0,1]
	v_cvt_scalef32_pk_f32_fp4 v[226:227], v186, 1.0 op_sel:[1,0,0]
	v_pk_fma_f32 v[48:49], v[230:231], v[122:123], v[48:49] op_sel_hi:[1,0,1]
	v_cvt_scalef32_pk_f32_fp4 v[228:229], v186, 1.0 op_sel:[0,1,0]
	v_pk_fma_f32 v[106:107], v[224:225], v[122:123], v[106:107] op_sel_hi:[1,0,1]
	v_cvt_scalef32_pk_f32_fp4 v[230:231], v186, 1.0 op_sel:[1,1,0]
	v_pk_fma_f32 v[102:103], v[226:227], v[122:123], v[102:103] op_sel_hi:[1,0,1]
	v_cvt_scalef32_pk_f32_fp4 v[224:225], v187, 1.0
	v_pk_fma_f32 v[96:97], v[228:229], v[122:123], v[96:97] op_sel_hi:[1,0,1]
	v_cvt_scalef32_pk_f32_fp4 v[226:227], v187, 1.0 op_sel:[1,0,0]
	v_pk_fma_f32 v[56:57], v[230:231], v[122:123], v[56:57] op_sel_hi:[1,0,1]
	v_cvt_scalef32_pk_f32_fp4 v[228:229], v187, 1.0 op_sel:[0,1,0]
	v_pk_fma_f32 v[50:51], v[224:225], v[122:123], v[50:51] op_sel_hi:[1,0,1]
	v_cvt_scalef32_pk_f32_fp4 v[230:231], v187, 1.0 op_sel:[1,1,0]
	v_pk_fma_f32 v[114:115], v[226:227], v[122:123], v[114:115] op_sel_hi:[1,0,1]
	v_pk_fma_f32 v[110:111], v[228:229], v[122:123], v[110:111] op_sel_hi:[1,0,1]
	v_pk_fma_f32 v[100:101], v[230:231], v[122:123], v[100:101] op_sel_hi:[1,0,1]
	s_waitcnt vmcnt(8)
	v_cvt_scalef32_pk_f32_fp4 v[224:225], v188, 1.0
	v_cvt_scalef32_pk_f32_fp4 v[226:227], v188, 1.0 op_sel:[1,0,0]
	v_cvt_scalef32_pk_f32_fp4 v[228:229], v188, 1.0 op_sel:[0,1,0]
	v_pk_fma_f32 v[112:113], v[224:225], v[124:125], v[112:113] op_sel_hi:[1,0,1]
	v_cvt_scalef32_pk_f32_fp4 v[230:231], v188, 1.0 op_sel:[1,1,0]
	v_pk_fma_f32 v[108:109], v[226:227], v[124:125], v[108:109] op_sel_hi:[1,0,1]
	v_cvt_scalef32_pk_f32_fp4 v[224:225], v189, 1.0
	v_pk_fma_f32 v[104:105], v[228:229], v[124:125], v[104:105] op_sel_hi:[1,0,1]
	v_cvt_scalef32_pk_f32_fp4 v[226:227], v189, 1.0 op_sel:[1,0,0]
	v_pk_fma_f32 v[98:99], v[230:231], v[124:125], v[98:99] op_sel_hi:[1,0,1]
	v_cvt_scalef32_pk_f32_fp4 v[228:229], v189, 1.0 op_sel:[0,1,0]
	v_pk_fma_f32 v[54:55], v[224:225], v[124:125], v[54:55] op_sel_hi:[1,0,1]
	v_cvt_scalef32_pk_f32_fp4 v[230:231], v189, 1.0 op_sel:[1,1,0]
	v_pk_fma_f32 v[58:59], v[226:227], v[124:125], v[58:59] op_sel_hi:[1,0,1]
	v_cvt_scalef32_pk_f32_fp4 v[224:225], v190, 1.0
	v_pk_fma_f32 v[52:53], v[228:229], v[124:125], v[52:53] op_sel_hi:[1,0,1]
	v_cvt_scalef32_pk_f32_fp4 v[226:227], v190, 1.0 op_sel:[1,0,0]
	v_pk_fma_f32 v[48:49], v[230:231], v[124:125], v[48:49] op_sel_hi:[1,0,1]
	v_cvt_scalef32_pk_f32_fp4 v[228:229], v190, 1.0 op_sel:[0,1,0]
	v_pk_fma_f32 v[106:107], v[224:225], v[124:125], v[106:107] op_sel_hi:[1,0,1]
	v_cvt_scalef32_pk_f32_fp4 v[230:231], v190, 1.0 op_sel:[1,1,0]
	v_pk_fma_f32 v[102:103], v[226:227], v[124:125], v[102:103] op_sel_hi:[1,0,1]
	v_cvt_scalef32_pk_f32_fp4 v[224:225], v191, 1.0
	v_pk_fma_f32 v[96:97], v[228:229], v[124:125], v[96:97] op_sel_hi:[1,0,1]
	v_cvt_scalef32_pk_f32_fp4 v[226:227], v191, 1.0 op_sel:[1,0,0]
	v_pk_fma_f32 v[56:57], v[230:231], v[124:125], v[56:57] op_sel_hi:[1,0,1]
	v_cvt_scalef32_pk_f32_fp4 v[228:229], v191, 1.0 op_sel:[0,1,0]
	v_pk_fma_f32 v[50:51], v[224:225], v[124:125], v[50:51] op_sel_hi:[1,0,1]
	v_cvt_scalef32_pk_f32_fp4 v[230:231], v191, 1.0 op_sel:[1,1,0]
	v_pk_fma_f32 v[114:115], v[226:227], v[124:125], v[114:115] op_sel_hi:[1,0,1]
	v_pk_fma_f32 v[110:111], v[228:229], v[124:125], v[110:111] op_sel_hi:[1,0,1]
	v_pk_fma_f32 v[100:101], v[230:231], v[124:125], v[100:101] op_sel_hi:[1,0,1]
	s_waitcnt lgkmcnt(0)
	s_movk_i32 s20, 0xe0
	v_lshl_add_u32 v130, v137, 2, s20
	ds_bpermute_b32 v156, v130, v147
	ds_bpermute_b32 v157, v130, v149
	s_waitcnt vmcnt(6)
	v_cvt_scalef32_pk_f32_fp4 v[224:225], v192, 1.0
	v_cvt_scalef32_pk_f32_fp4 v[226:227], v196, 1.0
	v_cvt_scalef32_pk_f32_fp4 v[228:229], v192, 1.0 op_sel:[1,0,0]
	v_cvt_scalef32_pk_f32_fp4 v[230:231], v196, 1.0 op_sel:[1,0,0]
	v_pk_fma_f32 v[232:233], v[24:25], v[224:225], 0 op_sel_hi:[1,1,0]
	v_pk_fma_f32 v[234:235], v[24:25], v[226:227], 0 op_sel_hi:[1,1,0]
	v_cvt_scalef32_pk_f32_fp4 v[224:225], v192, 1.0 op_sel:[0,1,0]
	v_cvt_scalef32_pk_f32_fp4 v[226:227], v196, 1.0 op_sel:[0,1,0]
	v_pk_fma_f32 v[232:233], v[26:27], v[228:229], v[232:233]
	v_pk_fma_f32 v[234:235], v[26:27], v[230:231], v[234:235]
	v_cvt_scalef32_pk_f32_fp4 v[228:229], v192, 1.0 op_sel:[1,1,0]
	v_cvt_scalef32_pk_f32_fp4 v[230:231], v196, 1.0 op_sel:[1,1,0]
	v_pk_fma_f32 v[232:233], v[12:13], v[224:225], v[232:233]
	v_pk_fma_f32 v[234:235], v[12:13], v[226:227], v[234:235]
	v_cvt_scalef32_pk_f32_fp4 v[224:225], v193, 1.0
	v_cvt_scalef32_pk_f32_fp4 v[226:227], v197, 1.0
	v_pk_fma_f32 v[232:233], v[14:15], v[228:229], v[232:233]
	v_pk_fma_f32 v[234:235], v[14:15], v[230:231], v[234:235]
	v_cvt_scalef32_pk_f32_fp4 v[228:229], v193, 1.0 op_sel:[1,0,0]
	v_cvt_scalef32_pk_f32_fp4 v[230:231], v197, 1.0 op_sel:[1,0,0]
	v_pk_fma_f32 v[232:233], v[4:5], v[224:225], v[232:233]
	v_pk_fma_f32 v[234:235], v[4:5], v[226:227], v[234:235]
	v_cvt_scalef32_pk_f32_fp4 v[224:225], v193, 1.0 op_sel:[0,1,0]
	v_cvt_scalef32_pk_f32_fp4 v[226:227], v197, 1.0 op_sel:[0,1,0]
	v_pk_fma_f32 v[232:233], v[6:7], v[228:229], v[232:233]
	v_pk_fma_f32 v[234:235], v[6:7], v[230:231], v[234:235]
	v_cvt_scalef32_pk_f32_fp4 v[228:229], v193, 1.0 op_sel:[1,1,0]
	v_cvt_scalef32_pk_f32_fp4 v[230:231], v197, 1.0 op_sel:[1,1,0]
	v_pk_fma_f32 v[232:233], v[0:1], v[224:225], v[232:233]
	v_pk_fma_f32 v[234:235], v[0:1], v[226:227], v[234:235]
	v_cvt_scalef32_pk_f32_fp4 v[224:225], v194, 1.0
	v_cvt_scalef32_pk_f32_fp4 v[226:227], v198, 1.0
	v_pk_fma_f32 v[232:233], v[2:3], v[228:229], v[232:233]
	v_pk_fma_f32 v[234:235], v[2:3], v[230:231], v[234:235]
	v_cvt_scalef32_pk_f32_fp4 v[228:229], v194, 1.0 op_sel:[1,0,0]
	v_cvt_scalef32_pk_f32_fp4 v[230:231], v198, 1.0 op_sel:[1,0,0]
	v_pk_fma_f32 v[232:233], v[28:29], v[224:225], v[232:233]
	v_pk_fma_f32 v[234:235], v[28:29], v[226:227], v[234:235]
	v_cvt_scalef32_pk_f32_fp4 v[224:225], v194, 1.0 op_sel:[0,1,0]
	v_cvt_scalef32_pk_f32_fp4 v[226:227], v198, 1.0 op_sel:[0,1,0]
	v_pk_fma_f32 v[232:233], v[30:31], v[228:229], v[232:233]
	v_pk_fma_f32 v[234:235], v[30:31], v[230:231], v[234:235]
	v_cvt_scalef32_pk_f32_fp4 v[228:229], v194, 1.0 op_sel:[1,1,0]
	v_cvt_scalef32_pk_f32_fp4 v[230:231], v198, 1.0 op_sel:[1,1,0]
	v_pk_fma_f32 v[232:233], v[16:17], v[224:225], v[232:233]
	v_pk_fma_f32 v[234:235], v[16:17], v[226:227], v[234:235]
	v_cvt_scalef32_pk_f32_fp4 v[224:225], v195, 1.0
	v_cvt_scalef32_pk_f32_fp4 v[226:227], v199, 1.0
	v_pk_fma_f32 v[232:233], v[18:19], v[228:229], v[232:233]
	v_pk_fma_f32 v[234:235], v[18:19], v[230:231], v[234:235]
	v_cvt_scalef32_pk_f32_fp4 v[228:229], v195, 1.0 op_sel:[1,0,0]
	v_cvt_scalef32_pk_f32_fp4 v[230:231], v199, 1.0 op_sel:[1,0,0]
	v_pk_fma_f32 v[232:233], v[8:9], v[224:225], v[232:233]
	v_pk_fma_f32 v[234:235], v[8:9], v[226:227], v[234:235]
	v_cvt_scalef32_pk_f32_fp4 v[224:225], v195, 1.0 op_sel:[0,1,0]
	v_cvt_scalef32_pk_f32_fp4 v[226:227], v199, 1.0 op_sel:[0,1,0]
	v_pk_fma_f32 v[232:233], v[10:11], v[228:229], v[232:233]
	v_pk_fma_f32 v[234:235], v[10:11], v[230:231], v[234:235]
	v_cvt_scalef32_pk_f32_fp4 v[228:229], v195, 1.0 op_sel:[1,1,0]
	v_cvt_scalef32_pk_f32_fp4 v[230:231], v199, 1.0 op_sel:[1,1,0]
	v_pk_fma_f32 v[232:233], v[20:21], v[224:225], v[232:233]
	v_pk_fma_f32 v[234:235], v[20:21], v[226:227], v[234:235]
	v_pk_fma_f32 v[232:233], v[22:23], v[228:229], v[232:233]
	v_pk_fma_f32 v[234:235], v[22:23], v[230:231], v[234:235]
	v_add_f32_e32 v32, v232, v233
	v_add_f32_e32 v33, v234, v235
	s_waitcnt vmcnt(4)
	v_cvt_scalef32_pk_f32_fp4 v[224:225], v200, 1.0
	v_cvt_scalef32_pk_f32_fp4 v[226:227], v204, 1.0
	v_cvt_scalef32_pk_f32_fp4 v[228:229], v200, 1.0 op_sel:[1,0,0]
	v_cvt_scalef32_pk_f32_fp4 v[230:231], v204, 1.0 op_sel:[1,0,0]
	v_pk_fma_f32 v[236:237], v[24:25], v[224:225], 0 op_sel_hi:[1,1,0]
	v_pk_fma_f32 v[238:239], v[24:25], v[226:227], 0 op_sel_hi:[1,1,0]
	v_cvt_scalef32_pk_f32_fp4 v[224:225], v200, 1.0 op_sel:[0,1,0]
	v_cvt_scalef32_pk_f32_fp4 v[226:227], v204, 1.0 op_sel:[0,1,0]
	v_pk_fma_f32 v[236:237], v[26:27], v[228:229], v[236:237]
	v_pk_fma_f32 v[238:239], v[26:27], v[230:231], v[238:239]
	v_cvt_scalef32_pk_f32_fp4 v[228:229], v200, 1.0 op_sel:[1,1,0]
	v_cvt_scalef32_pk_f32_fp4 v[230:231], v204, 1.0 op_sel:[1,1,0]
	v_pk_fma_f32 v[236:237], v[12:13], v[224:225], v[236:237]
	v_pk_fma_f32 v[238:239], v[12:13], v[226:227], v[238:239]
	v_cvt_scalef32_pk_f32_fp4 v[224:225], v201, 1.0
	v_cvt_scalef32_pk_f32_fp4 v[226:227], v205, 1.0
	v_pk_fma_f32 v[236:237], v[14:15], v[228:229], v[236:237]
	v_pk_fma_f32 v[238:239], v[14:15], v[230:231], v[238:239]
	v_cvt_scalef32_pk_f32_fp4 v[228:229], v201, 1.0 op_sel:[1,0,0]
	v_cvt_scalef32_pk_f32_fp4 v[230:231], v205, 1.0 op_sel:[1,0,0]
	v_pk_fma_f32 v[236:237], v[4:5], v[224:225], v[236:237]
	v_pk_fma_f32 v[238:239], v[4:5], v[226:227], v[238:239]
	v_cvt_scalef32_pk_f32_fp4 v[224:225], v201, 1.0 op_sel:[0,1,0]
	v_cvt_scalef32_pk_f32_fp4 v[226:227], v205, 1.0 op_sel:[0,1,0]
	v_pk_fma_f32 v[236:237], v[6:7], v[228:229], v[236:237]
	v_pk_fma_f32 v[238:239], v[6:7], v[230:231], v[238:239]
	v_cvt_scalef32_pk_f32_fp4 v[228:229], v201, 1.0 op_sel:[1,1,0]
	v_cvt_scalef32_pk_f32_fp4 v[230:231], v205, 1.0 op_sel:[1,1,0]
	v_pk_fma_f32 v[236:237], v[0:1], v[224:225], v[236:237]
	v_pk_fma_f32 v[238:239], v[0:1], v[226:227], v[238:239]
	v_cvt_scalef32_pk_f32_fp4 v[224:225], v202, 1.0
	v_cvt_scalef32_pk_f32_fp4 v[226:227], v206, 1.0
	v_pk_fma_f32 v[236:237], v[2:3], v[228:229], v[236:237]
	v_pk_fma_f32 v[238:239], v[2:3], v[230:231], v[238:239]
	v_cvt_scalef32_pk_f32_fp4 v[228:229], v202, 1.0 op_sel:[1,0,0]
	v_cvt_scalef32_pk_f32_fp4 v[230:231], v206, 1.0 op_sel:[1,0,0]
	v_pk_fma_f32 v[236:237], v[28:29], v[224:225], v[236:237]
	v_pk_fma_f32 v[238:239], v[28:29], v[226:227], v[238:239]
	v_cvt_scalef32_pk_f32_fp4 v[224:225], v202, 1.0 op_sel:[0,1,0]
	v_cvt_scalef32_pk_f32_fp4 v[226:227], v206, 1.0 op_sel:[0,1,0]
	v_pk_fma_f32 v[236:237], v[30:31], v[228:229], v[236:237]
	v_pk_fma_f32 v[238:239], v[30:31], v[230:231], v[238:239]
	v_cvt_scalef32_pk_f32_fp4 v[228:229], v202, 1.0 op_sel:[1,1,0]
	v_cvt_scalef32_pk_f32_fp4 v[230:231], v206, 1.0 op_sel:[1,1,0]
	v_pk_fma_f32 v[236:237], v[16:17], v[224:225], v[236:237]
	v_pk_fma_f32 v[238:239], v[16:17], v[226:227], v[238:239]
	v_cvt_scalef32_pk_f32_fp4 v[224:225], v203, 1.0
	v_cvt_scalef32_pk_f32_fp4 v[226:227], v207, 1.0
	v_pk_fma_f32 v[236:237], v[18:19], v[228:229], v[236:237]
	v_pk_fma_f32 v[238:239], v[18:19], v[230:231], v[238:239]
	v_cvt_scalef32_pk_f32_fp4 v[228:229], v203, 1.0 op_sel:[1,0,0]
	v_cvt_scalef32_pk_f32_fp4 v[230:231], v207, 1.0 op_sel:[1,0,0]
	v_pk_fma_f32 v[236:237], v[8:9], v[224:225], v[236:237]
	v_pk_fma_f32 v[238:239], v[8:9], v[226:227], v[238:239]
	v_cvt_scalef32_pk_f32_fp4 v[224:225], v203, 1.0 op_sel:[0,1,0]
	v_cvt_scalef32_pk_f32_fp4 v[226:227], v207, 1.0 op_sel:[0,1,0]
	v_pk_fma_f32 v[236:237], v[10:11], v[228:229], v[236:237]
	v_pk_fma_f32 v[238:239], v[10:11], v[230:231], v[238:239]
	v_cvt_scalef32_pk_f32_fp4 v[228:229], v203, 1.0 op_sel:[1,1,0]
	v_cvt_scalef32_pk_f32_fp4 v[230:231], v207, 1.0 op_sel:[1,1,0]
	v_pk_fma_f32 v[236:237], v[20:21], v[224:225], v[236:237]
	v_pk_fma_f32 v[238:239], v[20:21], v[226:227], v[238:239]
	v_pk_fma_f32 v[236:237], v[22:23], v[228:229], v[236:237]
	v_pk_fma_f32 v[238:239], v[22:23], v[230:231], v[238:239]
	v_add_f32_e32 v34, v236, v237
	v_add_f32_e32 v35, v238, v239
	v_cndmask_b32_e32 v36, v34, v32, vcc
	v_cndmask_b32_e32 v37, v32, v34, vcc
	v_cndmask_b32_e32 v38, v35, v33, vcc
	v_cndmask_b32_e32 v39, v33, v35, vcc
	ds_bpermute_b32 v37, v61, v37
	ds_bpermute_b32 v39, v61, v39
	s_waitcnt lgkmcnt(0)
	v_add_f32_e32 v36, v36, v37
	v_add_f32_e32 v38, v38, v39
	v_cndmask_b32_e64 v40, v38, v36, s[0:1]
	v_cndmask_b32_e64 v41, v36, v38, s[0:1]
	s_nop 1
	v_add_f32_dpp v40, v41, v40 row_ror:8 row_mask:0xf bank_mask:0xf
	s_nop 1
	v_add_f32_dpp v40, v40, v40 quad_perm:[1,0,3,2] row_mask:0xf bank_mask:0xf
	s_nop 1
	v_add_f32_dpp v40, v40, v40 quad_perm:[2,3,0,1] row_mask:0xf bank_mask:0xf
	s_nop 1
	v_add_f32_dpp v40, v40, v40 row_half_mirror row_mask:0xf bank_mask:0xf
	v_mul_f32_e32 v42, v40, v156
	v_fma_f32 v43, |v42|, s16, 1.0
	v_rcp_f32_e32 v43, v43
	v_cmp_gt_f32_e64 s[4:5], 0, v42
	v_mul_f32_e32 v45, v42, v42
	v_fmamk_f32 v44, v43, 0x3f07dc22, v142
	v_fmaak_f32 v44, v43, v44, 0x3f35f0e3
	v_fmaak_f32 v44, v43, v44, 0xbe11a98e
	v_fmaak_f32 v44, v43, v44, 0x3e027906
	v_mul_f32_e32 v45, 0xbf38aa3b, v45
	v_exp_f32_e32 v45, v45
	v_mul_f32_e32 v43, v43, v44
	v_mul_f32_e32 v43, v45, v43
	v_mul_f32_e32 v44, v42, v43
	v_fma_f32 v42, -v42, v43, v42
	v_cndmask_b32_e64 v42, v42, v44, s[4:5]
	v_mul_f32_e32 v158, v42, v157
	ds_bpermute_b32 v118, v138, v158
	ds_bpermute_b32 v120, v139, v158
	ds_bpermute_b32 v122, v140, v158
	ds_bpermute_b32 v124, v141, v158
	s_waitcnt vmcnt(3)
	v_cvt_scalef32_pk_f32_fp4 v[224:225], v208, 1.0
	v_cvt_scalef32_pk_f32_fp4 v[226:227], v208, 1.0 op_sel:[1,0,0]
	s_waitcnt lgkmcnt(0)
	v_cvt_scalef32_pk_f32_fp4 v[228:229], v208, 1.0 op_sel:[0,1,0]
	v_pk_fma_f32 v[112:113], v[224:225], v[118:119], v[112:113] op_sel_hi:[1,0,1]
	v_cvt_scalef32_pk_f32_fp4 v[230:231], v208, 1.0 op_sel:[1,1,0]
	v_pk_fma_f32 v[108:109], v[226:227], v[118:119], v[108:109] op_sel_hi:[1,0,1]
	v_cvt_scalef32_pk_f32_fp4 v[224:225], v209, 1.0
	v_pk_fma_f32 v[104:105], v[228:229], v[118:119], v[104:105] op_sel_hi:[1,0,1]
	v_cvt_scalef32_pk_f32_fp4 v[226:227], v209, 1.0 op_sel:[1,0,0]
	v_pk_fma_f32 v[98:99], v[230:231], v[118:119], v[98:99] op_sel_hi:[1,0,1]
	v_cvt_scalef32_pk_f32_fp4 v[228:229], v209, 1.0 op_sel:[0,1,0]
	v_pk_fma_f32 v[54:55], v[224:225], v[118:119], v[54:55] op_sel_hi:[1,0,1]
	v_cvt_scalef32_pk_f32_fp4 v[230:231], v209, 1.0 op_sel:[1,1,0]
	v_pk_fma_f32 v[58:59], v[226:227], v[118:119], v[58:59] op_sel_hi:[1,0,1]
	v_cvt_scalef32_pk_f32_fp4 v[224:225], v210, 1.0
	v_pk_fma_f32 v[52:53], v[228:229], v[118:119], v[52:53] op_sel_hi:[1,0,1]
	v_cvt_scalef32_pk_f32_fp4 v[226:227], v210, 1.0 op_sel:[1,0,0]
	v_pk_fma_f32 v[48:49], v[230:231], v[118:119], v[48:49] op_sel_hi:[1,0,1]
	v_cvt_scalef32_pk_f32_fp4 v[228:229], v210, 1.0 op_sel:[0,1,0]
	v_pk_fma_f32 v[106:107], v[224:225], v[118:119], v[106:107] op_sel_hi:[1,0,1]
	v_cvt_scalef32_pk_f32_fp4 v[230:231], v210, 1.0 op_sel:[1,1,0]
	v_pk_fma_f32 v[102:103], v[226:227], v[118:119], v[102:103] op_sel_hi:[1,0,1]
	v_cvt_scalef32_pk_f32_fp4 v[224:225], v211, 1.0
	v_pk_fma_f32 v[96:97], v[228:229], v[118:119], v[96:97] op_sel_hi:[1,0,1]
	v_cvt_scalef32_pk_f32_fp4 v[226:227], v211, 1.0 op_sel:[1,0,0]
	v_pk_fma_f32 v[56:57], v[230:231], v[118:119], v[56:57] op_sel_hi:[1,0,1]
	v_cvt_scalef32_pk_f32_fp4 v[228:229], v211, 1.0 op_sel:[0,1,0]
	v_pk_fma_f32 v[50:51], v[224:225], v[118:119], v[50:51] op_sel_hi:[1,0,1]
	v_cvt_scalef32_pk_f32_fp4 v[230:231], v211, 1.0 op_sel:[1,1,0]
	v_pk_fma_f32 v[114:115], v[226:227], v[118:119], v[114:115] op_sel_hi:[1,0,1]
	v_pk_fma_f32 v[110:111], v[228:229], v[118:119], v[110:111] op_sel_hi:[1,0,1]
	v_pk_fma_f32 v[100:101], v[230:231], v[118:119], v[100:101] op_sel_hi:[1,0,1]
	s_waitcnt vmcnt(2)
	v_cvt_scalef32_pk_f32_fp4 v[224:225], v212, 1.0
	v_cvt_scalef32_pk_f32_fp4 v[226:227], v212, 1.0 op_sel:[1,0,0]
	v_cvt_scalef32_pk_f32_fp4 v[228:229], v212, 1.0 op_sel:[0,1,0]
	v_pk_fma_f32 v[112:113], v[224:225], v[120:121], v[112:113] op_sel_hi:[1,0,1]
	v_cvt_scalef32_pk_f32_fp4 v[230:231], v212, 1.0 op_sel:[1,1,0]
	v_pk_fma_f32 v[108:109], v[226:227], v[120:121], v[108:109] op_sel_hi:[1,0,1]
	v_cvt_scalef32_pk_f32_fp4 v[224:225], v213, 1.0
	v_pk_fma_f32 v[104:105], v[228:229], v[120:121], v[104:105] op_sel_hi:[1,0,1]
	v_cvt_scalef32_pk_f32_fp4 v[226:227], v213, 1.0 op_sel:[1,0,0]
	v_pk_fma_f32 v[98:99], v[230:231], v[120:121], v[98:99] op_sel_hi:[1,0,1]
	v_cvt_scalef32_pk_f32_fp4 v[228:229], v213, 1.0 op_sel:[0,1,0]
	v_pk_fma_f32 v[54:55], v[224:225], v[120:121], v[54:55] op_sel_hi:[1,0,1]
	v_cvt_scalef32_pk_f32_fp4 v[230:231], v213, 1.0 op_sel:[1,1,0]
	v_pk_fma_f32 v[58:59], v[226:227], v[120:121], v[58:59] op_sel_hi:[1,0,1]
	v_cvt_scalef32_pk_f32_fp4 v[224:225], v214, 1.0
	v_pk_fma_f32 v[52:53], v[228:229], v[120:121], v[52:53] op_sel_hi:[1,0,1]
	v_cvt_scalef32_pk_f32_fp4 v[226:227], v214, 1.0 op_sel:[1,0,0]
	v_pk_fma_f32 v[48:49], v[230:231], v[120:121], v[48:49] op_sel_hi:[1,0,1]
	v_cvt_scalef32_pk_f32_fp4 v[228:229], v214, 1.0 op_sel:[0,1,0]
	v_pk_fma_f32 v[106:107], v[224:225], v[120:121], v[106:107] op_sel_hi:[1,0,1]
	v_cvt_scalef32_pk_f32_fp4 v[230:231], v214, 1.0 op_sel:[1,1,0]
	v_pk_fma_f32 v[102:103], v[226:227], v[120:121], v[102:103] op_sel_hi:[1,0,1]
	v_cvt_scalef32_pk_f32_fp4 v[224:225], v215, 1.0
	v_pk_fma_f32 v[96:97], v[228:229], v[120:121], v[96:97] op_sel_hi:[1,0,1]
	v_cvt_scalef32_pk_f32_fp4 v[226:227], v215, 1.0 op_sel:[1,0,0]
	v_pk_fma_f32 v[56:57], v[230:231], v[120:121], v[56:57] op_sel_hi:[1,0,1]
	v_cvt_scalef32_pk_f32_fp4 v[228:229], v215, 1.0 op_sel:[0,1,0]
	v_pk_fma_f32 v[50:51], v[224:225], v[120:121], v[50:51] op_sel_hi:[1,0,1]
	v_cvt_scalef32_pk_f32_fp4 v[230:231], v215, 1.0 op_sel:[1,1,0]
	v_pk_fma_f32 v[114:115], v[226:227], v[120:121], v[114:115] op_sel_hi:[1,0,1]
	v_pk_fma_f32 v[110:111], v[228:229], v[120:121], v[110:111] op_sel_hi:[1,0,1]
	v_pk_fma_f32 v[100:101], v[230:231], v[120:121], v[100:101] op_sel_hi:[1,0,1]
	s_waitcnt vmcnt(1)
	v_cvt_scalef32_pk_f32_fp4 v[224:225], v216, 1.0
	v_cvt_scalef32_pk_f32_fp4 v[226:227], v216, 1.0 op_sel:[1,0,0]
	v_cvt_scalef32_pk_f32_fp4 v[228:229], v216, 1.0 op_sel:[0,1,0]
	v_pk_fma_f32 v[112:113], v[224:225], v[122:123], v[112:113] op_sel_hi:[1,0,1]
	v_cvt_scalef32_pk_f32_fp4 v[230:231], v216, 1.0 op_sel:[1,1,0]
	v_pk_fma_f32 v[108:109], v[226:227], v[122:123], v[108:109] op_sel_hi:[1,0,1]
	v_cvt_scalef32_pk_f32_fp4 v[224:225], v217, 1.0
	v_pk_fma_f32 v[104:105], v[228:229], v[122:123], v[104:105] op_sel_hi:[1,0,1]
	v_cvt_scalef32_pk_f32_fp4 v[226:227], v217, 1.0 op_sel:[1,0,0]
	v_pk_fma_f32 v[98:99], v[230:231], v[122:123], v[98:99] op_sel_hi:[1,0,1]
	v_cvt_scalef32_pk_f32_fp4 v[228:229], v217, 1.0 op_sel:[0,1,0]
	v_pk_fma_f32 v[54:55], v[224:225], v[122:123], v[54:55] op_sel_hi:[1,0,1]
	v_cvt_scalef32_pk_f32_fp4 v[230:231], v217, 1.0 op_sel:[1,1,0]
	v_pk_fma_f32 v[58:59], v[226:227], v[122:123], v[58:59] op_sel_hi:[1,0,1]
	v_cvt_scalef32_pk_f32_fp4 v[224:225], v218, 1.0
	v_pk_fma_f32 v[52:53], v[228:229], v[122:123], v[52:53] op_sel_hi:[1,0,1]
	v_cvt_scalef32_pk_f32_fp4 v[226:227], v218, 1.0 op_sel:[1,0,0]
	v_pk_fma_f32 v[48:49], v[230:231], v[122:123], v[48:49] op_sel_hi:[1,0,1]
	v_cvt_scalef32_pk_f32_fp4 v[228:229], v218, 1.0 op_sel:[0,1,0]
	v_pk_fma_f32 v[106:107], v[224:225], v[122:123], v[106:107] op_sel_hi:[1,0,1]
	v_cvt_scalef32_pk_f32_fp4 v[230:231], v218, 1.0 op_sel:[1,1,0]
	v_pk_fma_f32 v[102:103], v[226:227], v[122:123], v[102:103] op_sel_hi:[1,0,1]
	v_cvt_scalef32_pk_f32_fp4 v[224:225], v219, 1.0
	v_pk_fma_f32 v[96:97], v[228:229], v[122:123], v[96:97] op_sel_hi:[1,0,1]
	v_cvt_scalef32_pk_f32_fp4 v[226:227], v219, 1.0 op_sel:[1,0,0]
	v_pk_fma_f32 v[56:57], v[230:231], v[122:123], v[56:57] op_sel_hi:[1,0,1]
	v_cvt_scalef32_pk_f32_fp4 v[228:229], v219, 1.0 op_sel:[0,1,0]
	v_pk_fma_f32 v[50:51], v[224:225], v[122:123], v[50:51] op_sel_hi:[1,0,1]
	v_cvt_scalef32_pk_f32_fp4 v[230:231], v219, 1.0 op_sel:[1,1,0]
	v_pk_fma_f32 v[114:115], v[226:227], v[122:123], v[114:115] op_sel_hi:[1,0,1]
	v_pk_fma_f32 v[110:111], v[228:229], v[122:123], v[110:111] op_sel_hi:[1,0,1]
	v_pk_fma_f32 v[100:101], v[230:231], v[122:123], v[100:101] op_sel_hi:[1,0,1]
	s_waitcnt vmcnt(0)
	v_cvt_scalef32_pk_f32_fp4 v[224:225], v220, 1.0
	v_cvt_scalef32_pk_f32_fp4 v[226:227], v220, 1.0 op_sel:[1,0,0]
	v_cvt_scalef32_pk_f32_fp4 v[228:229], v220, 1.0 op_sel:[0,1,0]
	v_pk_fma_f32 v[112:113], v[224:225], v[124:125], v[112:113] op_sel_hi:[1,0,1]
	v_cvt_scalef32_pk_f32_fp4 v[230:231], v220, 1.0 op_sel:[1,1,0]
	v_pk_fma_f32 v[108:109], v[226:227], v[124:125], v[108:109] op_sel_hi:[1,0,1]
	v_cvt_scalef32_pk_f32_fp4 v[224:225], v221, 1.0
	v_pk_fma_f32 v[104:105], v[228:229], v[124:125], v[104:105] op_sel_hi:[1,0,1]
	v_cvt_scalef32_pk_f32_fp4 v[226:227], v221, 1.0 op_sel:[1,0,0]
	v_pk_fma_f32 v[98:99], v[230:231], v[124:125], v[98:99] op_sel_hi:[1,0,1]
	v_cvt_scalef32_pk_f32_fp4 v[228:229], v221, 1.0 op_sel:[0,1,0]
	v_pk_fma_f32 v[54:55], v[224:225], v[124:125], v[54:55] op_sel_hi:[1,0,1]
	v_cvt_scalef32_pk_f32_fp4 v[230:231], v221, 1.0 op_sel:[1,1,0]
	v_pk_fma_f32 v[58:59], v[226:227], v[124:125], v[58:59] op_sel_hi:[1,0,1]
	v_cvt_scalef32_pk_f32_fp4 v[224:225], v222, 1.0
	v_pk_fma_f32 v[52:53], v[228:229], v[124:125], v[52:53] op_sel_hi:[1,0,1]
	v_cvt_scalef32_pk_f32_fp4 v[226:227], v222, 1.0 op_sel:[1,0,0]
	v_pk_fma_f32 v[48:49], v[230:231], v[124:125], v[48:49] op_sel_hi:[1,0,1]
	v_cvt_scalef32_pk_f32_fp4 v[228:229], v222, 1.0 op_sel:[0,1,0]
	v_pk_fma_f32 v[106:107], v[224:225], v[124:125], v[106:107] op_sel_hi:[1,0,1]
	v_cvt_scalef32_pk_f32_fp4 v[230:231], v222, 1.0 op_sel:[1,1,0]
	v_pk_fma_f32 v[102:103], v[226:227], v[124:125], v[102:103] op_sel_hi:[1,0,1]
	v_cvt_scalef32_pk_f32_fp4 v[224:225], v223, 1.0
	v_pk_fma_f32 v[96:97], v[228:229], v[124:125], v[96:97] op_sel_hi:[1,0,1]
	v_cvt_scalef32_pk_f32_fp4 v[226:227], v223, 1.0 op_sel:[1,0,0]
	v_pk_fma_f32 v[56:57], v[230:231], v[124:125], v[56:57] op_sel_hi:[1,0,1]
	v_cvt_scalef32_pk_f32_fp4 v[228:229], v223, 1.0 op_sel:[0,1,0]
	v_pk_fma_f32 v[50:51], v[224:225], v[124:125], v[50:51] op_sel_hi:[1,0,1]
	v_cvt_scalef32_pk_f32_fp4 v[230:231], v223, 1.0 op_sel:[1,1,0]
	v_pk_fma_f32 v[114:115], v[226:227], v[124:125], v[114:115] op_sel_hi:[1,0,1]
	v_pk_fma_f32 v[110:111], v[228:229], v[124:125], v[110:111] op_sel_hi:[1,0,1]
	v_pk_fma_f32 v[100:101], v[230:231], v[124:125], v[100:101] op_sel_hi:[1,0,1]
	ds_bpermute_b32 v32, v135, v112
	ds_bpermute_b32 v33, v135, v113
	ds_bpermute_b32 v126, v135, v110
	ds_bpermute_b32 v127, v135, v111
	ds_bpermute_b32 v116, v135, v106
	ds_bpermute_b32 v117, v135, v107
	ds_bpermute_b32 v34, v135, v108
	ds_bpermute_b32 v35, v135, v109
	ds_bpermute_b32 v118, v135, v102
	ds_bpermute_b32 v119, v135, v103
	s_waitcnt lgkmcnt(8)
	v_pk_add_f32 v[32:33], v[112:113], v[32:33]
	s_waitcnt lgkmcnt(6)
	v_pk_add_f32 v[110:111], v[110:111], v[126:127]
	v_pk_fma_f32 v[24:25], v[24:25], s[12:13], v[32:33] op_sel_hi:[1,0,1]
	v_pk_fma_f32 v[20:21], v[20:21], s[12:13], v[110:111] op_sel_hi:[1,0,1]
	ds_bpermute_b32 v110, v135, v100
	ds_bpermute_b32 v111, v135, v101
	v_add_f32_e32 v32, 0, v24
	ds_bpermute_b32 v36, v135, v104
	ds_bpermute_b32 v37, v135, v105
	v_add_f32_e32 v64, v32, v25
	s_waitcnt lgkmcnt(8)
	v_pk_add_f32 v[32:33], v[106:107], v[116:117]
	ds_bpermute_b32 v120, v135, v96
	ds_bpermute_b32 v121, v135, v97
	v_pk_fma_f32 v[28:29], v[28:29], s[12:13], v[32:33] op_sel_hi:[1,0,1]
	s_waitcnt lgkmcnt(8)
	v_pk_add_f32 v[32:33], v[108:109], v[34:35]
	ds_bpermute_b32 v38, v135, v98
	v_pk_fma_f32 v[26:27], v[26:27], s[12:13], v[32:33] op_sel_hi:[1,0,1]
	s_waitcnt lgkmcnt(7)
	v_pk_add_f32 v[32:33], v[102:103], v[118:119]
	ds_bpermute_b32 v39, v135, v99
	v_pk_fma_f32 v[30:31], v[30:31], s[12:13], v[32:33] op_sel_hi:[1,0,1]
	v_add_f32_e32 v32, v64, v26
	ds_bpermute_b32 v122, v135, v56
	ds_bpermute_b32 v123, v135, v57
	v_add_f32_e32 v34, v32, v27
	s_waitcnt lgkmcnt(8)
	v_pk_add_f32 v[32:33], v[100:101], v[110:111]
	ds_bpermute_b32 v40, v135, v54
	v_pk_fma_f32 v[22:23], v[22:23], s[12:13], v[32:33] op_sel_hi:[1,0,1]
	s_waitcnt lgkmcnt(7)
	v_pk_add_f32 v[32:33], v[104:105], v[36:37]
	ds_bpermute_b32 v41, v135, v55
	v_pk_fma_f32 v[12:13], v[12:13], s[12:13], v[32:33] op_sel_hi:[1,0,1]
	s_waitcnt lgkmcnt(6)
	v_pk_add_f32 v[32:33], v[96:97], v[120:121]
	ds_bpermute_b32 v128, v135, v50
	ds_bpermute_b32 v129, v135, v51
	v_pk_fma_f32 v[16:17], v[16:17], s[12:13], v[32:33] op_sel_hi:[1,0,1]
	v_add_f32_e32 v32, v34, v12
	v_add_f32_e32 v34, v32, v13
	s_waitcnt lgkmcnt(6)
	v_pk_add_f32 v[32:33], v[98:99], v[38:39]
	ds_bpermute_b32 v42, v135, v58
	ds_bpermute_b32 v43, v135, v59
	v_pk_fma_f32 v[14:15], v[14:15], s[12:13], v[32:33] op_sel_hi:[1,0,1]
	s_waitcnt lgkmcnt(6)
	v_pk_add_f32 v[32:33], v[56:57], v[122:123]
	ds_bpermute_b32 v44, v135, v52
	v_pk_fma_f32 v[18:19], v[18:19], s[12:13], v[32:33] op_sel_hi:[1,0,1]
	v_add_f32_e32 v32, v34, v14
	v_add_f32_e32 v34, v32, v15
	s_waitcnt lgkmcnt(5)
	v_pk_add_f32 v[32:33], v[54:55], v[40:41]
	ds_bpermute_b32 v45, v135, v53
	v_pk_fma_f32 v[32:33], v[4:5], s[12:13], v[32:33] op_sel_hi:[1,0,1]
	s_waitcnt lgkmcnt(4)
	v_pk_add_f32 v[4:5], v[50:51], v[128:129]
	ds_bpermute_b32 v46, v135, v48
	v_pk_fma_f32 v[8:9], v[8:9], s[12:13], v[4:5] op_sel_hi:[1,0,1]
	v_add_f32_e32 v4, v34, v32
	v_add_f32_e32 v36, v4, v33
	s_waitcnt lgkmcnt(3)
	v_pk_add_f32 v[4:5], v[58:59], v[42:43]
	ds_bpermute_b32 v47, v135, v49
	v_pk_fma_f32 v[34:35], v[6:7], s[12:13], v[4:5] op_sel_hi:[1,0,1]
	ds_bpermute_b32 v124, v135, v114
	v_add_f32_e32 v4, v36, v34
	v_add_f32_e32 v6, v4, v35
	s_waitcnt lgkmcnt(3)
	v_pk_add_f32 v[4:5], v[52:53], v[44:45]
	ds_bpermute_b32 v125, v135, v115
	v_pk_fma_f32 v[36:37], v[0:1], s[12:13], v[4:5] op_sel_hi:[1,0,1]
	v_mov_b32_e32 v92, v144
	v_add_f32_e32 v0, v6, v36
	v_add_f32_e32 v4, v0, v37
	s_waitcnt lgkmcnt(2)
	v_pk_add_f32 v[0:1], v[48:49], v[46:47]
	s_waitcnt lgkmcnt(0)
	v_pk_add_f32 v[114:115], v[114:115], v[124:125]
	v_pk_fma_f32 v[38:39], v[2:3], s[12:13], v[0:1] op_sel_hi:[1,0,1]
	v_pk_fma_f32 v[10:11], v[10:11], s[12:13], v[114:115] op_sel_hi:[1,0,1]
	v_add_f32_e32 v0, v4, v38
	v_add_f32_e32 v0, v0, v39
	v_add_f32_e32 v0, v0, v28
	v_add_f32_e32 v0, v0, v29
	v_add_f32_e32 v0, v0, v30
	v_add_f32_e32 v0, v0, v31
	v_add_f32_e32 v0, v0, v16
	v_add_f32_e32 v0, v0, v17
	v_add_f32_e32 v0, v0, v18
	v_add_f32_e32 v0, v0, v19
	v_add_f32_e32 v0, v0, v8
	v_add_f32_e32 v0, v0, v9
	v_add_f32_e32 v0, v0, v10
	v_add_f32_e32 v0, v0, v11
	v_add_f32_e32 v0, v0, v20
	v_add_f32_e32 v0, v0, v21
	v_add_f32_e32 v0, v0, v22
	v_add_f32_e32 v0, v0, v23
	ds_bpermute_b32 v1, v61, v0
	v_mov_b32_e32 v94, v145
	s_waitcnt lgkmcnt(0)
	v_add_f32_e32 v0, v0, v1
	ds_bpermute_b32 v1, v63, v0
	s_waitcnt lgkmcnt(0)
	v_add_f32_e32 v0, v0, v1
	ds_bpermute_b32 v1, v132, v0
	s_waitcnt lgkmcnt(0)
	v_add_f32_e32 v0, v0, v1
	ds_bpermute_b32 v1, v133, v0
	s_waitcnt lgkmcnt(0)
	v_add_f32_e32 v40, v0, v1
	ds_bpermute_b32 v41, v134, v40
	global_load_dwordx4 v[0:3], v[70:71], off
	global_load_dwordx4 v[4:7], v[72:73], off
	s_waitcnt lgkmcnt(0)
	v_add_f32_e32 v40, v40, v41
	v_mul_f32_e32 v40, 0x3a800000, v40
	v_pk_add_f32 v[24:25], v[24:25], v[40:41] op_sel_hi:[1,0] neg_lo:[0,1] neg_hi:[0,1]
	v_pk_add_f32 v[26:27], v[26:27], v[40:41] op_sel_hi:[1,0] neg_lo:[0,1] neg_hi:[0,1]
	v_pk_mul_f32 v[42:43], v[24:25], v[24:25]
	v_pk_mul_f32 v[44:45], v[26:27], v[26:27]
	v_add_f32_e32 v42, v42, v43
	v_pk_add_f32 v[12:13], v[12:13], v[40:41] op_sel_hi:[1,0] neg_lo:[0,1] neg_hi:[0,1]
	v_add_f32_e32 v42, v44, v42
	v_pk_mul_f32 v[46:47], v[12:13], v[12:13]
	v_add_f32_e32 v42, v45, v42
	v_pk_add_f32 v[14:15], v[14:15], v[40:41] op_sel_hi:[1,0] neg_lo:[0,1] neg_hi:[0,1]
	v_add_f32_e32 v42, v46, v42
	v_pk_mul_f32 v[48:49], v[14:15], v[14:15]
	v_add_f32_e32 v42, v47, v42
	v_pk_add_f32 v[32:33], v[32:33], v[40:41] op_sel_hi:[1,0] neg_lo:[0,1] neg_hi:[0,1]
	v_add_f32_e32 v42, v48, v42
	v_pk_mul_f32 v[50:51], v[32:33], v[32:33]
	v_add_f32_e32 v42, v49, v42
	v_pk_add_f32 v[34:35], v[34:35], v[40:41] op_sel_hi:[1,0] neg_lo:[0,1] neg_hi:[0,1]
	v_add_f32_e32 v42, v50, v42
	v_pk_mul_f32 v[52:53], v[34:35], v[34:35]
	v_add_f32_e32 v42, v51, v42
	v_pk_add_f32 v[36:37], v[36:37], v[40:41] op_sel_hi:[1,0] neg_lo:[0,1] neg_hi:[0,1]
	v_add_f32_e32 v42, v52, v42
	v_pk_mul_f32 v[54:55], v[36:37], v[36:37]
	v_add_f32_e32 v42, v53, v42
	v_pk_add_f32 v[38:39], v[38:39], v[40:41] op_sel_hi:[1,0] neg_lo:[0,1] neg_hi:[0,1]
	v_add_f32_e32 v42, v54, v42
	v_pk_mul_f32 v[56:57], v[38:39], v[38:39]
	v_add_f32_e32 v42, v55, v42
	v_pk_add_f32 v[28:29], v[28:29], v[40:41] op_sel_hi:[1,0] neg_lo:[0,1] neg_hi:[0,1]
	v_add_f32_e32 v42, v56, v42
	v_pk_mul_f32 v[58:59], v[28:29], v[28:29]
	v_add_f32_e32 v42, v57, v42
	v_pk_add_f32 v[30:31], v[30:31], v[40:41] op_sel_hi:[1,0] neg_lo:[0,1] neg_hi:[0,1]
	v_add_f32_e32 v42, v58, v42
	v_pk_mul_f32 v[96:97], v[30:31], v[30:31]
	v_add_f32_e32 v42, v59, v42
	v_pk_add_f32 v[16:17], v[16:17], v[40:41] op_sel_hi:[1,0] neg_lo:[0,1] neg_hi:[0,1]
	v_add_f32_e32 v42, v96, v42
	v_pk_mul_f32 v[98:99], v[16:17], v[16:17]
	v_add_f32_e32 v42, v97, v42
	v_pk_add_f32 v[18:19], v[18:19], v[40:41] op_sel_hi:[1,0] neg_lo:[0,1] neg_hi:[0,1]
	v_add_f32_e32 v42, v98, v42
	v_pk_mul_f32 v[100:101], v[18:19], v[18:19]
	v_add_f32_e32 v42, v99, v42
	v_pk_add_f32 v[8:9], v[8:9], v[40:41] op_sel_hi:[1,0] neg_lo:[0,1] neg_hi:[0,1]
	v_add_f32_e32 v42, v100, v42
	v_pk_mul_f32 v[102:103], v[8:9], v[8:9]
	v_add_f32_e32 v42, v101, v42
	v_pk_add_f32 v[10:11], v[10:11], v[40:41] op_sel_hi:[1,0] neg_lo:[0,1] neg_hi:[0,1]
	v_add_f32_e32 v42, v102, v42
	v_pk_mul_f32 v[104:105], v[10:11], v[10:11]
	v_add_f32_e32 v42, v103, v42
	v_pk_add_f32 v[20:21], v[20:21], v[40:41] op_sel_hi:[1,0] neg_lo:[0,1] neg_hi:[0,1]
	v_add_f32_e32 v42, v104, v42
	v_pk_mul_f32 v[106:107], v[20:21], v[20:21]
	v_add_f32_e32 v42, v105, v42
	v_pk_add_f32 v[22:23], v[22:23], v[40:41] op_sel_hi:[1,0] neg_lo:[0,1] neg_hi:[0,1]
	v_add_f32_e32 v42, v106, v42
	v_pk_mul_f32 v[40:41], v[22:23], v[22:23]
	v_add_f32_e32 v42, v107, v42
	v_add_f32_e32 v40, v40, v42
	v_add_f32_e32 v40, v41, v40
	ds_bpermute_b32 v41, v61, v40
	v_cndmask_b32_e64 v27, v31, v27, s[2:3]
	v_cndmask_b32_e64 v26, v30, v26, s[2:3]
	v_cndmask_b32_e64 v25, v29, v25, s[2:3]
	v_cndmask_b32_e64 v24, v28, v24, s[2:3]
	s_waitcnt lgkmcnt(0)
	v_add_f32_e32 v40, v40, v41
	ds_bpermute_b32 v41, v63, v40
	v_cndmask_b32_e64 v13, v17, v13, s[2:3]
	v_cndmask_b32_e64 v12, v16, v12, s[2:3]
	v_cndmask_b32_e64 v15, v19, v15, s[2:3]
	v_cndmask_b32_e64 v14, v18, v14, s[2:3]
	s_waitcnt lgkmcnt(0)
	v_add_f32_e32 v40, v40, v41
	ds_bpermute_b32 v41, v132, v40
	v_cndmask_b32_e64 v9, v9, v33, s[2:3]
	v_cndmask_b32_e64 v8, v8, v32, s[2:3]
	v_cndmask_b32_e64 v11, v11, v35, s[2:3]
	v_cndmask_b32_e64 v10, v10, v34, s[2:3]
	s_waitcnt lgkmcnt(0)
	v_add_f32_e32 v40, v40, v41
	ds_bpermute_b32 v41, v133, v40
	v_mov_b32_e32 v32, v95
	s_waitcnt lgkmcnt(0)
	v_add_f32_e32 v40, v40, v41
	ds_bpermute_b32 v41, v134, v40
	s_waitcnt lgkmcnt(0)
	v_add_f32_e32 v40, v40, v41
	v_fmamk_f32 v40, v40, 0x3a800000, v143
	v_mul_f32_e32 v41, 0x4b800000, v40
	v_cmp_gt_f32_e64 s[4:5], s17, v40
	s_nop 1
	v_cndmask_b32_e64 v40, v40, v41, s[4:5]
	v_rsq_f32_e32 v42, v40
	v_lshl_add_u64 v[40:41], v[88:89], 0, v[90:91]
	v_mul_f32_e32 v43, 0x45800000, v42
	v_cndmask_b32_e64 v42, v42, v43, s[4:5]
	v_pk_mul_f32 v[24:25], v[24:25], v[42:43] op_sel_hi:[1,0]
	v_pk_mul_f32 v[26:27], v[26:27], v[42:43] op_sel_hi:[1,0]
	s_waitcnt vmcnt(0)
	v_pk_fma_f32 v[0:1], v[0:1], v[24:25], v[4:5]
	v_pk_fma_f32 v[2:3], v[2:3], v[26:27], v[6:7]
	global_store_dwordx4 v[40:41], v[0:3], off
	global_load_dwordx4 v[0:3], v[74:75], off
	s_nop 0
	global_load_dwordx4 v[4:7], v[76:77], off
	v_pk_mul_f32 v[14:15], v[14:15], v[42:43] op_sel_hi:[1,0]
	v_pk_mul_f32 v[12:13], v[12:13], v[42:43] op_sel_hi:[1,0]
	v_pk_mul_f32 v[10:11], v[10:11], v[42:43] op_sel_hi:[1,0]
	v_pk_mul_f32 v[8:9], v[8:9], v[42:43] op_sel_hi:[1,0]
	s_waitcnt vmcnt(0)
	v_pk_fma_f32 v[0:1], v[0:1], v[12:13], v[4:5]
	v_pk_fma_f32 v[2:3], v[2:3], v[14:15], v[6:7]
	global_store_dwordx4 v[40:41], v[0:3], off offset:16
	global_load_dwordx4 v[0:3], v[78:79], off
	s_nop 0
	global_load_dwordx4 v[4:7], v[80:81], off
	s_waitcnt vmcnt(0)
	v_pk_fma_f32 v[0:1], v[0:1], v[8:9], v[4:5]
	v_pk_fma_f32 v[2:3], v[2:3], v[10:11], v[6:7]
	global_store_dwordx4 v[40:41], v[0:3], off offset:32
	global_load_dwordx4 v[0:3], v[82:83], off
	s_nop 0
	global_load_dwordx4 v[4:7], v[84:85], off
	v_cndmask_b32_e64 v9, v21, v37, s[2:3]
	v_cndmask_b32_e64 v8, v20, v36, s[2:3]
	v_cndmask_b32_e64 v11, v23, v39, s[2:3]
	v_cndmask_b32_e64 v10, v22, v38, s[2:3]
	v_pk_mul_f32 v[10:11], v[10:11], v[42:43] op_sel_hi:[1,0]
	v_pk_mul_f32 v[8:9], v[8:9], v[42:43] op_sel_hi:[1,0]
	s_waitcnt vmcnt(0)
	v_pk_fma_f32 v[2:3], v[2:3], v[10:11], v[6:7]
	v_pk_fma_f32 v[0:1], v[0:1], v[8:9], v[4:5]
	global_store_dwordx4 v[40:41], v[0:3], off offset:48
	s_andn2_b64 exec, exec, s[10:11]
	s_cbranch_execnz .LBB0_698

	.amdhsa_kernel _Z4mega6Paramsii
		.amdhsa_group_segment_fixed_size 65536
		.amdhsa_private_segment_fixed_size 0
		.amdhsa_kernarg_size 536
		.amdhsa_user_sgpr_count 2
		.amdhsa_user_sgpr_dispatch_ptr 0
		.amdhsa_user_sgpr_queue_ptr 0
		.amdhsa_user_sgpr_kernarg_segment_ptr 1
		.amdhsa_user_sgpr_dispatch_id 0
		.amdhsa_user_sgpr_kernarg_preload_length 0
		.amdhsa_user_sgpr_kernarg_preload_offset 0
		.amdhsa_user_sgpr_private_segment_size 0
		.amdhsa_uses_dynamic_stack 0
		.amdhsa_enable_private_segment 0
		.amdhsa_system_sgpr_workgroup_id_x 1
		.amdhsa_system_sgpr_workgroup_id_y 0
		.amdhsa_system_sgpr_workgroup_id_z 0
		.amdhsa_system_sgpr_workgroup_info 0
		.amdhsa_system_vgpr_workitem_id 2
		.amdhsa_next_free_vgpr 256
		.amdhsa_next_free_sgpr 102
		.amdhsa_accum_offset 256
		.amdhsa_reserve_vcc 1
		.amdhsa_float_round_mode_32 0
		.amdhsa_float_round_mode_16_64 0
		.amdhsa_float_denorm_mode_32 3
		.amdhsa_float_denorm_mode_16_64 3
		.amdhsa_dx10_clamp 1
		.amdhsa_ieee_mode 1
		.amdhsa_fp16_overflow 0
		.amdhsa_tg_split 0
		.amdhsa_exception_fp_ieee_invalid_op 0
		.amdhsa_exception_fp_denorm_src 0
		.amdhsa_exception_fp_ieee_div_zero 0
		.amdhsa_exception_fp_ieee_overflow 0
		.amdhsa_exception_fp_ieee_underflow 0
		.amdhsa_exception_fp_ieee_inexact 0
		.amdhsa_exception_int_div_zero 0
	.end_amdhsa_kernel

amdhsa.kernels:
  - .agpr_count:     0
    .args:
      - .offset:         0
        .size:           272
        .value_kind:     by_value
      - .offset:         272
        .size:           4
        .value_kind:     by_value
      - .offset:         276
        .size:           4
        .value_kind:     by_value
      - .offset:         280
        .size:           4
        .value_kind:     hidden_block_count_x
      - .offset:         284
        .size:           4
        .value_kind:     hidden_block_count_y
      - .offset:         288
        .size:           4
        .value_kind:     hidden_block_count_z
      - .offset:         292
        .size:           2
        .value_kind:     hidden_group_size_x
      - .offset:         294
        .size:           2
        .value_kind:     hidden_group_size_y
      - .offset:         296
        .size:           2
        .value_kind:     hidden_group_size_z
      - .offset:         298
        .size:           2
        .value_kind:     hidden_remainder_x
      - .offset:         300
        .size:           2
        .value_kind:     hidden_remainder_y
      - .offset:         302
        .size:           2
        .value_kind:     hidden_remainder_z
      - .offset:         320
        .size:           8
        .value_kind:     hidden_global_offset_x
      - .offset:         328
        .size:           8
        .value_kind:     hidden_global_offset_y
      - .offset:         336
        .size:           8
        .value_kind:     hidden_global_offset_z
      - .offset:         344
        .size:           2
        .value_kind:     hidden_grid_dims
      - .offset:         368
        .size:           8
        .value_kind:     hidden_multigrid_sync_arg
    .group_segment_fixed_size: 65536
    .kernarg_segment_align: 8
    .kernarg_segment_size: 536
    .language:       OpenCL C
    .language_version:
      - 2
      - 0
    .max_flat_workgroup_size: 256
    .name:           _Z4mega6Paramsii
    .private_segment_fixed_size: 0
    .sgpr_count:     108
    .sgpr_spill_count: 92
    .symbol:         _Z4mega6Paramsii.kd
    .uniform_work_group_size: 1
    .uses_dynamic_stack: false
    .vgpr_count:     256
    .vgpr_spill_count: 0
    .wavefront_size: 64
